# hot loop heads (all K loops, MLA, SWA) aligned to 64 B; stacked on pipelined claims + staged rstd tables + zeroing peel + SWA prologue fix
# baseline (speedup 1.0000x reference)
.LBB0_199:
	s_ashr_i32 s31, s30, 31
	s_lshl_b64 s[46:47], s[30:31], 21
	s_add_u32 s46, s48, s46
	s_addc_u32 s47, s49, s47
	s_and_b64 s[50:51], s[4:5], exec
	s_cselect_b32 s2, s47, s61
	s_cselect_b32 s7, s46, s60
	s_ashr_i32 s25, s24, 31
	s_lshl_b64 s[50:51], s[24:25], 21
	s_add_u32 s50, s40, s50
	s_addc_u32 s51, s41, s51
	s_and_b64 s[62:63], s[4:5], exec
	s_cselect_b32 s25, s51, s55
	s_cselect_b32 s31, s50, s54
	s_add_u32 s60, s60, 0x100080
	s_addc_u32 s61, s61, 0
	s_add_u32 s59, s54, 0x100
	s_addc_u32 s69, s55, 0
	s_mov_b32 s70, -2
	ds_read_b128 v[166:169], v156
	ds_read_b128 v[170:173], v156 offset:1024
	ds_read_b128 v[174:177], v156 offset:2048
	ds_read_b128 v[178:181], v156 offset:3072
	ds_read_b128 v[182:185], v157
	ds_read_b128 v[186:189], v157 offset:1024
	ds_read_b128 v[190:193], v157 offset:2048
	ds_read_b128 v[194:197], v157 offset:3072
	s_add_u32 s54, s60, 0xfff00080
	s_addc_u32 s55, s61, -1
	s_cmp_eq_u32 s70, 60
	s_cselect_b32 s63, s2, s55
	s_cselect_b32 s62, s7, s54
	s_cselect_b32 s55, s25, s69
	s_cselect_b32 s54, s31, s59
	v_lshl_add_u64 v[160:161], s[60:61], 0, v[138:139]
	s_add_i32 m0, s26, 0xc000
	ds_read_b128 v[202:205], v158
	ds_read_b128 v[206:209], v158 offset:1024
	ds_read_b128 v[210:213], v158 offset:2048
	ds_read_b128 v[214:217], v158 offset:3072
	ds_read_b128 v[218:221], v158 offset:4096
	ds_read_b128 v[222:225], v158 offset:5120
	ds_read_b128 v[226:229], v158 offset:6144
	ds_read_b128 v[230:233], v158 offset:7168
	global_load_lds_dwordx4 v[160:161], off
	v_lshl_add_u64 v[160:161], s[60:61], 0, v[140:141]
	s_add_i32 m0, s26, 0xe000
	s_nop 0
	global_load_lds_dwordx4 v[160:161], off
	s_waitcnt vmcnt(8)
	s_waitcnt lgkmcnt(0)
	s_barrier
	s_setprio 1
	s_waitcnt lgkmcnt(0)
	v_mfma_f32_16x16x32_bf16 v[126:129], v[166:169], v[202:205], 0
	v_mfma_f32_16x16x32_bf16 v[122:125], v[174:177], v[202:205], 0
	v_mfma_f32_16x16x32_bf16 v[110:113], v[166:169], v[210:213], 0
	v_mfma_f32_16x16x32_bf16 v[106:109], v[174:177], v[210:213], 0
	v_mfma_f32_16x16x32_bf16 v[94:97], v[166:169], v[218:221], 0
	v_mfma_f32_16x16x32_bf16 v[90:93], v[174:177], v[218:221], 0
	v_mfma_f32_16x16x32_bf16 v[78:81], v[166:169], v[226:229], 0
	v_mfma_f32_16x16x32_bf16 v[74:77], v[174:177], v[226:229], 0
	v_mfma_f32_16x16x32_bf16 v[126:129], v[170:173], v[206:209], v[126:129]
	v_mfma_f32_16x16x32_bf16 v[122:125], v[178:181], v[206:209], v[122:125]
	v_mfma_f32_16x16x32_bf16 v[110:113], v[170:173], v[214:217], v[110:113]
	v_mfma_f32_16x16x32_bf16 v[106:109], v[178:181], v[214:217], v[106:109]
	v_mfma_f32_16x16x32_bf16 v[94:97], v[170:173], v[222:225], v[94:97]
	v_mfma_f32_16x16x32_bf16 v[90:93], v[178:181], v[222:225], v[90:93]
	v_mfma_f32_16x16x32_bf16 v[78:81], v[170:173], v[230:233], v[78:81]
	v_mfma_f32_16x16x32_bf16 v[74:77], v[178:181], v[230:233], v[74:77]
	s_setprio 0
	s_setprio 1
	v_mfma_f32_16x16x32_bf16 v[118:121], v[182:185], v[202:205], 0
	v_mfma_f32_16x16x32_bf16 v[114:117], v[190:193], v[202:205], 0
	v_mfma_f32_16x16x32_bf16 v[102:105], v[182:185], v[210:213], 0
	v_mfma_f32_16x16x32_bf16 v[98:101], v[190:193], v[210:213], 0
	v_mfma_f32_16x16x32_bf16 v[86:89], v[182:185], v[218:221], 0
	v_mfma_f32_16x16x32_bf16 v[82:85], v[190:193], v[218:221], 0
	v_mfma_f32_16x16x32_bf16 v[70:73], v[182:185], v[226:229], 0
	v_mfma_f32_16x16x32_bf16 v[66:69], v[190:193], v[226:229], 0
	v_mfma_f32_16x16x32_bf16 v[118:121], v[186:189], v[206:209], v[118:121]
	v_mfma_f32_16x16x32_bf16 v[114:117], v[194:197], v[206:209], v[114:117]
	v_mfma_f32_16x16x32_bf16 v[102:105], v[186:189], v[214:217], v[102:105]
	v_mfma_f32_16x16x32_bf16 v[98:101], v[194:197], v[214:217], v[98:101]
	v_mfma_f32_16x16x32_bf16 v[86:89], v[186:189], v[222:225], v[86:89]
	v_mfma_f32_16x16x32_bf16 v[82:85], v[194:197], v[222:225], v[82:85]
	v_mfma_f32_16x16x32_bf16 v[70:73], v[186:189], v[230:233], v[70:73]
	v_mfma_f32_16x16x32_bf16 v[66:69], v[194:197], v[230:233], v[66:69]
	s_setprio 0
	s_barrier
	s_add_i32 s71, s57, s21
	v_lshl_add_u64 v[160:161], s[54:55], 0, v[134:135]
	s_mov_b32 m0, s71
	ds_read_b128 v[202:205], v158 offset:16384
	ds_read_b128 v[206:209], v158 offset:17408
	ds_read_b128 v[210:213], v158 offset:18432
	ds_read_b128 v[214:217], v158 offset:19456
	ds_read_b128 v[218:221], v158 offset:20480
	ds_read_b128 v[222:225], v158 offset:21504
	ds_read_b128 v[226:229], v158 offset:22528
	ds_read_b128 v[230:233], v158 offset:23552
	global_load_lds_dwordx4 v[160:161], off
	s_add_i32 m0, s71, 0x2000
	s_add_u32 s72, s54, 0x100000
	v_lshl_add_u64 v[198:199], s[54:55], 0, v[136:137]
	s_addc_u32 s73, s55, 0
	s_add_i32 s71, s64, s21
	global_load_lds_dwordx4 v[198:199], off
	v_lshl_add_u64 v[234:235], s[72:73], 0, v[134:135]
	s_mov_b32 m0, s71
	v_lshl_add_u64 v[236:237], s[62:63], 0, v[132:133]
	global_load_lds_dwordx4 v[234:235], off
	v_lshl_add_u64 v[234:235], s[72:73], 0, v[136:137]
	s_add_i32 m0, s71, 0x2000
	s_nop 0
	global_load_lds_dwordx4 v[234:235], off
	v_lshl_add_u64 v[234:235], s[62:63], 0, v[130:131]
	s_mov_b32 m0, s26
	s_nop 0
	global_load_lds_dwordx4 v[234:235], off
	s_mov_b32 m0, s27
	s_nop 0
	global_load_lds_dwordx4 v[236:237], off
	s_waitcnt vmcnt(8)
	s_waitcnt lgkmcnt(0)
	s_barrier
	s_setprio 1
	s_waitcnt lgkmcnt(0)
	v_mfma_f32_16x16x32_bf16 v[62:65], v[166:169], v[202:205], 0
	v_mfma_f32_16x16x32_bf16 v[58:61], v[174:177], v[202:205], 0
	v_mfma_f32_16x16x32_bf16 v[46:49], v[166:169], v[210:213], 0
	v_mfma_f32_16x16x32_bf16 v[42:45], v[174:177], v[210:213], 0
	v_mfma_f32_16x16x32_bf16 v[30:33], v[166:169], v[218:221], 0
	v_mfma_f32_16x16x32_bf16 v[26:29], v[174:177], v[218:221], 0
	v_mfma_f32_16x16x32_bf16 v[14:17], v[166:169], v[226:229], 0
	v_mfma_f32_16x16x32_bf16 v[10:13], v[174:177], v[226:229], 0
	v_mfma_f32_16x16x32_bf16 v[62:65], v[170:173], v[206:209], v[62:65]
	v_mfma_f32_16x16x32_bf16 v[58:61], v[178:181], v[206:209], v[58:61]
	v_mfma_f32_16x16x32_bf16 v[46:49], v[170:173], v[214:217], v[46:49]
	v_mfma_f32_16x16x32_bf16 v[42:45], v[178:181], v[214:217], v[42:45]
	v_mfma_f32_16x16x32_bf16 v[30:33], v[170:173], v[222:225], v[30:33]
	v_mfma_f32_16x16x32_bf16 v[26:29], v[178:181], v[222:225], v[26:29]
	v_mfma_f32_16x16x32_bf16 v[14:17], v[170:173], v[230:233], v[14:17]
	v_mfma_f32_16x16x32_bf16 v[10:13], v[178:181], v[230:233], v[10:13]
	s_setprio 0
	s_setprio 1
	v_mfma_f32_16x16x32_bf16 v[54:57], v[182:185], v[202:205], 0
	v_mfma_f32_16x16x32_bf16 v[50:53], v[190:193], v[202:205], 0
	v_mfma_f32_16x16x32_bf16 v[38:41], v[182:185], v[210:213], 0
	v_mfma_f32_16x16x32_bf16 v[34:37], v[190:193], v[210:213], 0
	v_mfma_f32_16x16x32_bf16 v[22:25], v[182:185], v[218:221], 0
	v_mfma_f32_16x16x32_bf16 v[18:21], v[190:193], v[218:221], 0
	v_mfma_f32_16x16x32_bf16 v[6:9], v[182:185], v[226:229], 0
	v_mfma_f32_16x16x32_bf16 v[2:5], v[190:193], v[226:229], 0
	v_mfma_f32_16x16x32_bf16 v[54:57], v[186:189], v[206:209], v[54:57]
	v_mfma_f32_16x16x32_bf16 v[50:53], v[194:197], v[206:209], v[50:53]
	v_mfma_f32_16x16x32_bf16 v[38:41], v[186:189], v[214:217], v[38:41]
	v_mfma_f32_16x16x32_bf16 v[34:37], v[194:197], v[214:217], v[34:37]
	v_mfma_f32_16x16x32_bf16 v[22:25], v[186:189], v[222:225], v[22:25]
	v_mfma_f32_16x16x32_bf16 v[18:21], v[194:197], v[222:225], v[18:21]
	v_mfma_f32_16x16x32_bf16 v[6:9], v[186:189], v[230:233], v[6:9]
	v_mfma_f32_16x16x32_bf16 v[2:5], v[194:197], v[230:233], v[2:5]
	s_setprio 0
	s_barrier
	s_add_i32 s71, 0, 0x18000
	v_add_u32_e32 v163, s71, v154
	s_add_i32 s72, 0, 0x1c000
	ds_read_b128 v[166:169], v163
	ds_read_b128 v[170:173], v163 offset:1024
	ds_read_b128 v[174:177], v163 offset:2048
	ds_read_b128 v[178:181], v163 offset:3072
	v_add_u32_e32 v163, s72, v154
	ds_read_b128 v[182:185], v163
	ds_read_b128 v[186:189], v163 offset:1024
	ds_read_b128 v[190:193], v163 offset:2048
	ds_read_b128 v[194:197], v163 offset:3072
	s_add_u32 s62, s62, 0x100000
	s_addc_u32 s63, s63, 0
	s_mov_b32 m0, s36
	v_lshl_add_u64 v[238:239], s[62:63], 0, v[130:131]
	ds_read_b128 v[202:205], v158 offset:32768
	ds_read_b128 v[206:209], v158 offset:33792
	ds_read_b128 v[210:213], v158 offset:34816
	ds_read_b128 v[214:217], v158 offset:35840
	ds_read_b128 v[218:221], v158 offset:36864
	ds_read_b128 v[222:225], v158 offset:37888
	ds_read_b128 v[226:229], v158 offset:38912
	ds_read_b128 v[230:233], v158 offset:39936
	global_load_lds_dwordx4 v[238:239], off
	v_lshl_add_u64 v[238:239], s[62:63], 0, v[132:133]
	s_mov_b32 m0, s37
	s_nop 0
	global_load_lds_dwordx4 v[238:239], off
	s_waitcnt vmcnt(8)
	s_waitcnt lgkmcnt(0)
	s_barrier
	s_setprio 1
	s_waitcnt lgkmcnt(0)
	v_mfma_f32_16x16x32_bf16 v[126:129], v[166:169], v[202:205], v[126:129]
	v_mfma_f32_16x16x32_bf16 v[122:125], v[174:177], v[202:205], v[122:125]
	v_mfma_f32_16x16x32_bf16 v[110:113], v[166:169], v[210:213], v[110:113]
	v_mfma_f32_16x16x32_bf16 v[106:109], v[174:177], v[210:213], v[106:109]
	v_mfma_f32_16x16x32_bf16 v[94:97], v[166:169], v[218:221], v[94:97]
	v_mfma_f32_16x16x32_bf16 v[90:93], v[174:177], v[218:221], v[90:93]
	v_mfma_f32_16x16x32_bf16 v[78:81], v[166:169], v[226:229], v[78:81]
	v_mfma_f32_16x16x32_bf16 v[74:77], v[174:177], v[226:229], v[74:77]
	v_mfma_f32_16x16x32_bf16 v[126:129], v[170:173], v[206:209], v[126:129]
	v_mfma_f32_16x16x32_bf16 v[122:125], v[178:181], v[206:209], v[122:125]
	v_mfma_f32_16x16x32_bf16 v[110:113], v[170:173], v[214:217], v[110:113]
	v_mfma_f32_16x16x32_bf16 v[106:109], v[178:181], v[214:217], v[106:109]
	v_mfma_f32_16x16x32_bf16 v[94:97], v[170:173], v[222:225], v[94:97]
	v_mfma_f32_16x16x32_bf16 v[90:93], v[178:181], v[222:225], v[90:93]
	v_mfma_f32_16x16x32_bf16 v[78:81], v[170:173], v[230:233], v[78:81]
	v_mfma_f32_16x16x32_bf16 v[74:77], v[178:181], v[230:233], v[74:77]
	s_setprio 0
	s_setprio 1
	v_mfma_f32_16x16x32_bf16 v[118:121], v[182:185], v[202:205], v[118:121]
	v_mfma_f32_16x16x32_bf16 v[114:117], v[190:193], v[202:205], v[114:117]
	v_mfma_f32_16x16x32_bf16 v[102:105], v[182:185], v[210:213], v[102:105]
	v_mfma_f32_16x16x32_bf16 v[98:101], v[190:193], v[210:213], v[98:101]
	v_mfma_f32_16x16x32_bf16 v[86:89], v[182:185], v[218:221], v[86:89]
	v_mfma_f32_16x16x32_bf16 v[82:85], v[190:193], v[218:221], v[82:85]
	v_mfma_f32_16x16x32_bf16 v[70:73], v[182:185], v[226:229], v[70:73]
	v_mfma_f32_16x16x32_bf16 v[66:69], v[190:193], v[226:229], v[66:69]
	v_mfma_f32_16x16x32_bf16 v[118:121], v[186:189], v[206:209], v[118:121]
	v_mfma_f32_16x16x32_bf16 v[114:117], v[194:197], v[206:209], v[114:117]
	v_mfma_f32_16x16x32_bf16 v[102:105], v[186:189], v[214:217], v[102:105]
	v_mfma_f32_16x16x32_bf16 v[98:101], v[194:197], v[214:217], v[98:101]
	v_mfma_f32_16x16x32_bf16 v[86:89], v[186:189], v[222:225], v[86:89]
	v_mfma_f32_16x16x32_bf16 v[82:85], v[194:197], v[222:225], v[82:85]
	v_mfma_f32_16x16x32_bf16 v[70:73], v[186:189], v[230:233], v[70:73]
	v_mfma_f32_16x16x32_bf16 v[66:69], v[194:197], v[230:233], v[66:69]
	s_setprio 0
	s_barrier
	s_add_i32 s62, s71, s21
	v_lshl_add_u64 v[160:161], v[160:161], 0, s[14:15]
	s_mov_b32 m0, s62
	ds_read_b128 v[202:205], v158 offset:49152
	ds_read_b128 v[206:209], v158 offset:50176
	ds_read_b128 v[210:213], v158 offset:51200
	ds_read_b128 v[214:217], v158 offset:52224
	ds_read_b128 v[218:221], v158 offset:53248
	ds_read_b128 v[222:225], v158 offset:54272
	ds_read_b128 v[226:229], v158 offset:55296
	ds_read_b128 v[230:233], v158 offset:56320
	global_load_lds_dwordx4 v[160:161], off
	s_add_i32 m0, s62, 0x2000
	s_add_u32 s54, s54, 0x100080
	v_lshl_add_u64 v[160:161], v[198:199], 0, s[14:15]
	s_addc_u32 s55, s55, 0
	s_add_i32 s62, s72, s21
	global_load_lds_dwordx4 v[160:161], off
	v_lshl_add_u64 v[160:161], s[54:55], 0, v[134:135]
	s_mov_b32 m0, s62
	s_nop 0
	global_load_lds_dwordx4 v[160:161], off
	v_lshl_add_u64 v[160:161], s[54:55], 0, v[136:137]
	s_add_i32 m0, s62, 0x2000
	s_nop 0
	global_load_lds_dwordx4 v[160:161], off
	v_lshl_add_u64 v[160:161], v[234:235], 0, s[14:15]
	s_mov_b32 m0, s52
	s_nop 0
	global_load_lds_dwordx4 v[160:161], off
	v_lshl_add_u64 v[160:161], v[236:237], 0, s[14:15]
	s_mov_b32 m0, s53
	s_nop 0
	global_load_lds_dwordx4 v[160:161], off
	s_waitcnt vmcnt(8)
	s_waitcnt lgkmcnt(0)
	s_barrier
	s_setprio 1
	s_waitcnt lgkmcnt(0)
	v_mfma_f32_16x16x32_bf16 v[62:65], v[166:169], v[202:205], v[62:65]
	v_mfma_f32_16x16x32_bf16 v[58:61], v[174:177], v[202:205], v[58:61]
	v_mfma_f32_16x16x32_bf16 v[46:49], v[166:169], v[210:213], v[46:49]
	v_mfma_f32_16x16x32_bf16 v[42:45], v[174:177], v[210:213], v[42:45]
	v_mfma_f32_16x16x32_bf16 v[30:33], v[166:169], v[218:221], v[30:33]
	v_mfma_f32_16x16x32_bf16 v[26:29], v[174:177], v[218:221], v[26:29]
	v_mfma_f32_16x16x32_bf16 v[14:17], v[166:169], v[226:229], v[14:17]
	v_mfma_f32_16x16x32_bf16 v[10:13], v[174:177], v[226:229], v[10:13]
	v_mfma_f32_16x16x32_bf16 v[62:65], v[170:173], v[206:209], v[62:65]
	v_mfma_f32_16x16x32_bf16 v[58:61], v[178:181], v[206:209], v[58:61]
	v_mfma_f32_16x16x32_bf16 v[46:49], v[170:173], v[214:217], v[46:49]
	v_mfma_f32_16x16x32_bf16 v[42:45], v[178:181], v[214:217], v[42:45]
	v_mfma_f32_16x16x32_bf16 v[30:33], v[170:173], v[222:225], v[30:33]
	v_mfma_f32_16x16x32_bf16 v[26:29], v[178:181], v[222:225], v[26:29]
	v_mfma_f32_16x16x32_bf16 v[14:17], v[170:173], v[230:233], v[14:17]
	v_mfma_f32_16x16x32_bf16 v[10:13], v[178:181], v[230:233], v[10:13]
	s_setprio 0
	s_setprio 1
	v_mfma_f32_16x16x32_bf16 v[54:57], v[182:185], v[202:205], v[54:57]
	v_mfma_f32_16x16x32_bf16 v[50:53], v[190:193], v[202:205], v[50:53]
	v_mfma_f32_16x16x32_bf16 v[38:41], v[182:185], v[210:213], v[38:41]
	v_mfma_f32_16x16x32_bf16 v[34:37], v[190:193], v[210:213], v[34:37]
	v_mfma_f32_16x16x32_bf16 v[22:25], v[182:185], v[218:221], v[22:25]
	v_mfma_f32_16x16x32_bf16 v[18:21], v[190:193], v[218:221], v[18:21]
	v_mfma_f32_16x16x32_bf16 v[6:9], v[182:185], v[226:229], v[6:9]
	v_mfma_f32_16x16x32_bf16 v[2:5], v[190:193], v[226:229], v[2:5]
	v_mfma_f32_16x16x32_bf16 v[54:57], v[186:189], v[206:209], v[54:57]
	v_mfma_f32_16x16x32_bf16 v[50:53], v[194:197], v[206:209], v[50:53]
	v_mfma_f32_16x16x32_bf16 v[38:41], v[186:189], v[214:217], v[38:41]
	v_mfma_f32_16x16x32_bf16 v[34:37], v[194:197], v[214:217], v[34:37]
	v_mfma_f32_16x16x32_bf16 v[22:25], v[186:189], v[222:225], v[22:25]
	v_mfma_f32_16x16x32_bf16 v[18:21], v[194:197], v[222:225], v[18:21]
	v_mfma_f32_16x16x32_bf16 v[6:9], v[186:189], v[230:233], v[6:9]
	v_mfma_f32_16x16x32_bf16 v[2:5], v[194:197], v[230:233], v[2:5]
	s_setprio 0
	s_barrier
	s_add_i32 s70, s70, 2
	s_add_u32 s60, s60, 0x100
	s_addc_u32 s61, s61, 0
	s_add_u32 s59, s59, 0x100
	s_addc_u32 s69, s69, 0
	.p2align	6

.LBB0_247:
	s_ashr_i32 s47, s46, 31
	s_lshl_b64 s[58:59], s[46:47], 21
	s_add_u32 s58, s20, s58
	s_addc_u32 s59, s21, s59
	s_and_b64 s[62:63], s[60:61], exec
	s_cselect_b32 s15, s59, s65
	s_cselect_b32 s47, s58, s64
	s_ashr_i32 s51, s50, 31
	s_lshl_b64 s[62:63], s[50:51], 21
	v_readlane_b32 s66, v250, 11
	v_readlane_b32 s67, v250, 12
	s_add_u32 s62, s66, s62
	s_addc_u32 s63, s67, s63
	s_and_b64 s[66:67], s[60:61], exec
	s_cselect_b32 s51, s63, s55
	s_cselect_b32 s68, s62, s54
	s_add_u32 s64, s64, 0x100080
	s_addc_u32 s65, s65, 0
	s_add_u32 s69, s54, 0x100
	s_addc_u32 s70, s55, 0
	s_mov_b32 s71, -2
	ds_read_b128 v[144:147], v140
	ds_read_b128 v[148:151], v140 offset:1024
	ds_read_b128 v[152:155], v140 offset:2048
	ds_read_b128 v[156:159], v140 offset:3072
	ds_read_b128 v[166:169], v141
	ds_read_b128 v[170:173], v141 offset:1024
	ds_read_b128 v[174:177], v141 offset:2048
	ds_read_b128 v[178:181], v141 offset:3072
	s_add_u32 s54, s64, 0xfff00080
	s_addc_u32 s55, s65, -1
	s_cmp_eq_u32 s71, 60
	s_cselect_b32 s67, s15, s55
	s_cselect_b32 s66, s47, s54
	s_cselect_b32 s55, s51, s70
	s_cselect_b32 s54, s68, s69
	v_lshl_add_u64 v[160:161], s[64:65], 0, v[134:135]
	s_add_i32 m0, s23, 0xc000
	ds_read_b128 v[182:185], v142
	ds_read_b128 v[186:189], v142 offset:1024
	ds_read_b128 v[190:193], v142 offset:2048
	ds_read_b128 v[194:197], v142 offset:3072
	ds_read_b128 v[202:205], v142 offset:4096
	ds_read_b128 v[206:209], v142 offset:5120
	ds_read_b128 v[210:213], v142 offset:6144
	ds_read_b128 v[214:217], v142 offset:7168
	global_load_lds_dwordx4 v[160:161], off
	v_lshl_add_u64 v[160:161], s[64:65], 0, v[136:137]
	s_add_i32 m0, s23, 0xe000
	s_nop 0
	global_load_lds_dwordx4 v[160:161], off
	s_waitcnt vmcnt(8)
	s_waitcnt lgkmcnt(0)
	s_barrier
	s_setprio 1
	s_waitcnt lgkmcnt(0)
	v_mfma_f32_16x16x32_bf16 v[126:129], v[144:147], v[182:185], 0
	v_mfma_f32_16x16x32_bf16 v[122:125], v[152:155], v[182:185], 0
	v_mfma_f32_16x16x32_bf16 v[118:121], v[144:147], v[190:193], 0
	v_mfma_f32_16x16x32_bf16 v[114:117], v[152:155], v[190:193], 0
	v_mfma_f32_16x16x32_bf16 v[110:113], v[144:147], v[202:205], 0
	v_mfma_f32_16x16x32_bf16 v[102:105], v[152:155], v[202:205], 0
	v_mfma_f32_16x16x32_bf16 v[94:97], v[144:147], v[210:213], 0
	v_mfma_f32_16x16x32_bf16 v[86:89], v[152:155], v[210:213], 0
	v_mfma_f32_16x16x32_bf16 v[126:129], v[148:151], v[186:189], v[126:129]
	v_mfma_f32_16x16x32_bf16 v[122:125], v[156:159], v[186:189], v[122:125]
	v_mfma_f32_16x16x32_bf16 v[118:121], v[148:151], v[194:197], v[118:121]
	v_mfma_f32_16x16x32_bf16 v[114:117], v[156:159], v[194:197], v[114:117]
	v_mfma_f32_16x16x32_bf16 v[110:113], v[148:151], v[206:209], v[110:113]
	v_mfma_f32_16x16x32_bf16 v[102:105], v[156:159], v[206:209], v[102:105]
	v_mfma_f32_16x16x32_bf16 v[94:97], v[148:151], v[214:217], v[94:97]
	v_mfma_f32_16x16x32_bf16 v[86:89], v[156:159], v[214:217], v[86:89]
	s_setprio 0
	s_setprio 1
	v_mfma_f32_16x16x32_bf16 v[106:109], v[166:169], v[182:185], 0
	v_mfma_f32_16x16x32_bf16 v[98:101], v[174:177], v[182:185], 0
	v_mfma_f32_16x16x32_bf16 v[90:93], v[166:169], v[190:193], 0
	v_mfma_f32_16x16x32_bf16 v[82:85], v[174:177], v[190:193], 0
	v_mfma_f32_16x16x32_bf16 v[78:81], v[166:169], v[202:205], 0
	v_mfma_f32_16x16x32_bf16 v[74:77], v[174:177], v[202:205], 0
	v_mfma_f32_16x16x32_bf16 v[70:73], v[166:169], v[210:213], 0
	v_mfma_f32_16x16x32_bf16 v[66:69], v[174:177], v[210:213], 0
	v_mfma_f32_16x16x32_bf16 v[106:109], v[170:173], v[186:189], v[106:109]
	v_mfma_f32_16x16x32_bf16 v[98:101], v[178:181], v[186:189], v[98:101]
	v_mfma_f32_16x16x32_bf16 v[90:93], v[170:173], v[194:197], v[90:93]
	v_mfma_f32_16x16x32_bf16 v[82:85], v[178:181], v[194:197], v[82:85]
	v_mfma_f32_16x16x32_bf16 v[78:81], v[170:173], v[206:209], v[78:81]
	v_mfma_f32_16x16x32_bf16 v[74:77], v[178:181], v[206:209], v[74:77]
	v_mfma_f32_16x16x32_bf16 v[70:73], v[170:173], v[214:217], v[70:73]
	v_mfma_f32_16x16x32_bf16 v[66:69], v[178:181], v[214:217], v[66:69]
	s_setprio 0
	s_barrier
	s_add_i32 s72, s56, s4
	v_lshl_add_u64 v[160:161], s[54:55], 0, v[130:131]
	s_mov_b32 m0, s72
	ds_read_b128 v[182:185], v142 offset:16384
	ds_read_b128 v[186:189], v142 offset:17408
	ds_read_b128 v[190:193], v142 offset:18432
	ds_read_b128 v[194:197], v142 offset:19456
	ds_read_b128 v[202:205], v142 offset:20480
	ds_read_b128 v[206:209], v142 offset:21504
	ds_read_b128 v[210:213], v142 offset:22528
	ds_read_b128 v[214:217], v142 offset:23552
	global_load_lds_dwordx4 v[160:161], off
	s_add_i32 m0, s72, 0x2000
	s_add_u32 s72, s54, 0x100000
	v_lshl_add_u64 v[198:199], s[54:55], 0, v[132:133]
	s_addc_u32 s73, s55, 0
	s_add_i32 s74, s57, s4
	global_load_lds_dwordx4 v[198:199], off
	v_lshl_add_u64 v[218:219], s[72:73], 0, v[130:131]
	s_mov_b32 m0, s74
	v_lshl_add_u64 v[220:221], s[66:67], 0, v[132:133]
	global_load_lds_dwordx4 v[218:219], off
	v_lshl_add_u64 v[218:219], s[72:73], 0, v[132:133]
	s_add_i32 m0, s74, 0x2000
	s_nop 0
	global_load_lds_dwordx4 v[218:219], off
	v_lshl_add_u64 v[218:219], s[66:67], 0, v[130:131]
	s_mov_b32 m0, s23
	s_nop 0
	global_load_lds_dwordx4 v[218:219], off
	s_mov_b32 m0, s27
	s_nop 0
	global_load_lds_dwordx4 v[220:221], off
	s_waitcnt vmcnt(8)
	s_waitcnt lgkmcnt(0)
	s_barrier
	s_setprio 1
	s_waitcnt lgkmcnt(0)
	v_mfma_f32_16x16x32_bf16 v[62:65], v[144:147], v[182:185], 0
	v_mfma_f32_16x16x32_bf16 v[58:61], v[152:155], v[182:185], 0
	v_mfma_f32_16x16x32_bf16 v[54:57], v[144:147], v[190:193], 0
	v_mfma_f32_16x16x32_bf16 v[50:53], v[152:155], v[190:193], 0
	v_mfma_f32_16x16x32_bf16 v[46:49], v[144:147], v[202:205], 0
	v_mfma_f32_16x16x32_bf16 v[38:41], v[152:155], v[202:205], 0
	v_mfma_f32_16x16x32_bf16 v[30:33], v[144:147], v[210:213], 0
	v_mfma_f32_16x16x32_bf16 v[22:25], v[152:155], v[210:213], 0
	v_mfma_f32_16x16x32_bf16 v[62:65], v[148:151], v[186:189], v[62:65]
	v_mfma_f32_16x16x32_bf16 v[58:61], v[156:159], v[186:189], v[58:61]
	v_mfma_f32_16x16x32_bf16 v[54:57], v[148:151], v[194:197], v[54:57]
	v_mfma_f32_16x16x32_bf16 v[50:53], v[156:159], v[194:197], v[50:53]
	v_mfma_f32_16x16x32_bf16 v[46:49], v[148:151], v[206:209], v[46:49]
	v_mfma_f32_16x16x32_bf16 v[38:41], v[156:159], v[206:209], v[38:41]
	v_mfma_f32_16x16x32_bf16 v[30:33], v[148:151], v[214:217], v[30:33]
	v_mfma_f32_16x16x32_bf16 v[22:25], v[156:159], v[214:217], v[22:25]
	s_setprio 0
	s_setprio 1
	v_mfma_f32_16x16x32_bf16 v[42:45], v[166:169], v[182:185], 0
	v_mfma_f32_16x16x32_bf16 v[34:37], v[174:177], v[182:185], 0
	v_mfma_f32_16x16x32_bf16 v[26:29], v[166:169], v[190:193], 0
	v_mfma_f32_16x16x32_bf16 v[18:21], v[174:177], v[190:193], 0
	v_mfma_f32_16x16x32_bf16 v[14:17], v[166:169], v[202:205], 0
	v_mfma_f32_16x16x32_bf16 v[10:13], v[174:177], v[202:205], 0
	v_mfma_f32_16x16x32_bf16 v[6:9], v[166:169], v[210:213], 0
	v_mfma_f32_16x16x32_bf16 v[2:5], v[174:177], v[210:213], 0
	v_mfma_f32_16x16x32_bf16 v[42:45], v[170:173], v[186:189], v[42:45]
	v_mfma_f32_16x16x32_bf16 v[34:37], v[178:181], v[186:189], v[34:37]
	v_mfma_f32_16x16x32_bf16 v[26:29], v[170:173], v[194:197], v[26:29]
	v_mfma_f32_16x16x32_bf16 v[18:21], v[178:181], v[194:197], v[18:21]
	v_mfma_f32_16x16x32_bf16 v[14:17], v[170:173], v[206:209], v[14:17]
	v_mfma_f32_16x16x32_bf16 v[10:13], v[178:181], v[206:209], v[10:13]
	v_mfma_f32_16x16x32_bf16 v[6:9], v[170:173], v[214:217], v[6:9]
	v_mfma_f32_16x16x32_bf16 v[2:5], v[178:181], v[214:217], v[2:5]
	s_setprio 0
	s_barrier
	s_add_i32 s72, 0, 0x18000
	s_add_i32 s73, 0, 0x1c000
	v_add_u32_e32 v156, s72, v138
	v_add_u32_e32 v163, s73, v138
	ds_read_b128 v[144:147], v156
	ds_read_b128 v[148:151], v156 offset:1024
	ds_read_b128 v[152:155], v156 offset:2048
	ds_read_b128 v[156:159], v156 offset:3072
	ds_read_b128 v[166:169], v163
	ds_read_b128 v[170:173], v163 offset:1024
	ds_read_b128 v[174:177], v163 offset:2048
	ds_read_b128 v[178:181], v163 offset:3072
	s_add_u32 s66, s66, 0x100000
	s_addc_u32 s67, s67, 0
	s_mov_b32 m0, s36
	v_lshl_add_u64 v[222:223], s[66:67], 0, v[130:131]
	ds_read_b128 v[182:185], v142 offset:32768
	ds_read_b128 v[186:189], v142 offset:33792
	ds_read_b128 v[190:193], v142 offset:34816
	ds_read_b128 v[194:197], v142 offset:35840
	ds_read_b128 v[202:205], v142 offset:36864
	ds_read_b128 v[206:209], v142 offset:37888
	ds_read_b128 v[210:213], v142 offset:38912
	ds_read_b128 v[214:217], v142 offset:39936
	global_load_lds_dwordx4 v[222:223], off
	v_lshl_add_u64 v[222:223], s[66:67], 0, v[132:133]
	s_mov_b32 m0, s37
	s_nop 0
	global_load_lds_dwordx4 v[222:223], off
	s_waitcnt vmcnt(8)
	s_waitcnt lgkmcnt(0)
	s_barrier
	s_setprio 1
	s_waitcnt lgkmcnt(0)
	v_mfma_f32_16x16x32_bf16 v[126:129], v[144:147], v[182:185], v[126:129]
	v_mfma_f32_16x16x32_bf16 v[122:125], v[152:155], v[182:185], v[122:125]
	v_mfma_f32_16x16x32_bf16 v[118:121], v[144:147], v[190:193], v[118:121]
	v_mfma_f32_16x16x32_bf16 v[114:117], v[152:155], v[190:193], v[114:117]
	v_mfma_f32_16x16x32_bf16 v[110:113], v[144:147], v[202:205], v[110:113]
	v_mfma_f32_16x16x32_bf16 v[102:105], v[152:155], v[202:205], v[102:105]
	v_mfma_f32_16x16x32_bf16 v[94:97], v[144:147], v[210:213], v[94:97]
	v_mfma_f32_16x16x32_bf16 v[86:89], v[152:155], v[210:213], v[86:89]
	v_mfma_f32_16x16x32_bf16 v[126:129], v[148:151], v[186:189], v[126:129]
	v_mfma_f32_16x16x32_bf16 v[122:125], v[156:159], v[186:189], v[122:125]
	v_mfma_f32_16x16x32_bf16 v[118:121], v[148:151], v[194:197], v[118:121]
	v_mfma_f32_16x16x32_bf16 v[114:117], v[156:159], v[194:197], v[114:117]
	v_mfma_f32_16x16x32_bf16 v[110:113], v[148:151], v[206:209], v[110:113]
	v_mfma_f32_16x16x32_bf16 v[102:105], v[156:159], v[206:209], v[102:105]
	v_mfma_f32_16x16x32_bf16 v[94:97], v[148:151], v[214:217], v[94:97]
	v_mfma_f32_16x16x32_bf16 v[86:89], v[156:159], v[214:217], v[86:89]
	s_setprio 0
	s_setprio 1
	v_mfma_f32_16x16x32_bf16 v[106:109], v[166:169], v[182:185], v[106:109]
	v_mfma_f32_16x16x32_bf16 v[98:101], v[174:177], v[182:185], v[98:101]
	v_mfma_f32_16x16x32_bf16 v[90:93], v[166:169], v[190:193], v[90:93]
	v_mfma_f32_16x16x32_bf16 v[82:85], v[174:177], v[190:193], v[82:85]
	v_mfma_f32_16x16x32_bf16 v[78:81], v[166:169], v[202:205], v[78:81]
	v_mfma_f32_16x16x32_bf16 v[74:77], v[174:177], v[202:205], v[74:77]
	v_mfma_f32_16x16x32_bf16 v[70:73], v[166:169], v[210:213], v[70:73]
	v_mfma_f32_16x16x32_bf16 v[66:69], v[174:177], v[210:213], v[66:69]
	v_mfma_f32_16x16x32_bf16 v[106:109], v[170:173], v[186:189], v[106:109]
	v_mfma_f32_16x16x32_bf16 v[98:101], v[178:181], v[186:189], v[98:101]
	v_mfma_f32_16x16x32_bf16 v[90:93], v[170:173], v[194:197], v[90:93]
	v_mfma_f32_16x16x32_bf16 v[82:85], v[178:181], v[194:197], v[82:85]
	v_mfma_f32_16x16x32_bf16 v[78:81], v[170:173], v[206:209], v[78:81]
	v_mfma_f32_16x16x32_bf16 v[74:77], v[178:181], v[206:209], v[74:77]
	v_mfma_f32_16x16x32_bf16 v[70:73], v[170:173], v[214:217], v[70:73]
	v_mfma_f32_16x16x32_bf16 v[66:69], v[178:181], v[214:217], v[66:69]
	s_setprio 0
	s_barrier
	s_add_i32 s66, s72, s4
	v_lshl_add_u64 v[160:161], v[160:161], 0, s[24:25]
	s_mov_b32 m0, s66
	ds_read_b128 v[182:185], v142 offset:49152
	ds_read_b128 v[186:189], v142 offset:50176
	ds_read_b128 v[190:193], v142 offset:51200
	ds_read_b128 v[194:197], v142 offset:52224
	ds_read_b128 v[202:205], v142 offset:53248
	ds_read_b128 v[206:209], v142 offset:54272
	ds_read_b128 v[210:213], v142 offset:55296
	ds_read_b128 v[214:217], v142 offset:56320
	global_load_lds_dwordx4 v[160:161], off
	s_add_i32 m0, s66, 0x2000
	s_add_u32 s54, s54, 0x100080
	v_lshl_add_u64 v[160:161], v[198:199], 0, s[24:25]
	s_addc_u32 s55, s55, 0
	s_add_i32 s66, s73, s4
	global_load_lds_dwordx4 v[160:161], off
	v_lshl_add_u64 v[160:161], s[54:55], 0, v[130:131]
	s_mov_b32 m0, s66
	s_nop 0
	global_load_lds_dwordx4 v[160:161], off
	v_lshl_add_u64 v[160:161], s[54:55], 0, v[132:133]
	s_add_i32 m0, s66, 0x2000
	s_nop 0
	global_load_lds_dwordx4 v[160:161], off
	v_lshl_add_u64 v[160:161], v[218:219], 0, s[24:25]
	s_mov_b32 m0, s39
	s_nop 0
	global_load_lds_dwordx4 v[160:161], off
	v_lshl_add_u64 v[160:161], v[220:221], 0, s[24:25]
	s_mov_b32 m0, s52
	s_nop 0
	global_load_lds_dwordx4 v[160:161], off
	s_waitcnt vmcnt(8)
	s_waitcnt lgkmcnt(0)
	s_barrier
	s_setprio 1
	s_waitcnt lgkmcnt(0)
	v_mfma_f32_16x16x32_bf16 v[62:65], v[144:147], v[182:185], v[62:65]
	v_mfma_f32_16x16x32_bf16 v[58:61], v[152:155], v[182:185], v[58:61]
	v_mfma_f32_16x16x32_bf16 v[54:57], v[144:147], v[190:193], v[54:57]
	v_mfma_f32_16x16x32_bf16 v[50:53], v[152:155], v[190:193], v[50:53]
	v_mfma_f32_16x16x32_bf16 v[46:49], v[144:147], v[202:205], v[46:49]
	v_mfma_f32_16x16x32_bf16 v[38:41], v[152:155], v[202:205], v[38:41]
	v_mfma_f32_16x16x32_bf16 v[30:33], v[144:147], v[210:213], v[30:33]
	v_mfma_f32_16x16x32_bf16 v[22:25], v[152:155], v[210:213], v[22:25]
	v_mfma_f32_16x16x32_bf16 v[62:65], v[148:151], v[186:189], v[62:65]
	v_mfma_f32_16x16x32_bf16 v[58:61], v[156:159], v[186:189], v[58:61]
	v_mfma_f32_16x16x32_bf16 v[54:57], v[148:151], v[194:197], v[54:57]
	v_mfma_f32_16x16x32_bf16 v[50:53], v[156:159], v[194:197], v[50:53]
	v_mfma_f32_16x16x32_bf16 v[46:49], v[148:151], v[206:209], v[46:49]
	v_mfma_f32_16x16x32_bf16 v[38:41], v[156:159], v[206:209], v[38:41]
	v_mfma_f32_16x16x32_bf16 v[30:33], v[148:151], v[214:217], v[30:33]
	v_mfma_f32_16x16x32_bf16 v[22:25], v[156:159], v[214:217], v[22:25]
	s_setprio 0
	s_setprio 1
	v_mfma_f32_16x16x32_bf16 v[42:45], v[166:169], v[182:185], v[42:45]
	v_mfma_f32_16x16x32_bf16 v[34:37], v[174:177], v[182:185], v[34:37]
	v_mfma_f32_16x16x32_bf16 v[26:29], v[166:169], v[190:193], v[26:29]
	v_mfma_f32_16x16x32_bf16 v[18:21], v[174:177], v[190:193], v[18:21]
	v_mfma_f32_16x16x32_bf16 v[14:17], v[166:169], v[202:205], v[14:17]
	v_mfma_f32_16x16x32_bf16 v[10:13], v[174:177], v[202:205], v[10:13]
	v_mfma_f32_16x16x32_bf16 v[6:9], v[166:169], v[210:213], v[6:9]
	v_mfma_f32_16x16x32_bf16 v[2:5], v[174:177], v[210:213], v[2:5]
	v_mfma_f32_16x16x32_bf16 v[42:45], v[170:173], v[186:189], v[42:45]
	v_mfma_f32_16x16x32_bf16 v[34:37], v[178:181], v[186:189], v[34:37]
	v_mfma_f32_16x16x32_bf16 v[26:29], v[170:173], v[194:197], v[26:29]
	v_mfma_f32_16x16x32_bf16 v[18:21], v[178:181], v[194:197], v[18:21]
	v_mfma_f32_16x16x32_bf16 v[14:17], v[170:173], v[206:209], v[14:17]
	v_mfma_f32_16x16x32_bf16 v[10:13], v[178:181], v[206:209], v[10:13]
	v_mfma_f32_16x16x32_bf16 v[6:9], v[170:173], v[214:217], v[6:9]
	v_mfma_f32_16x16x32_bf16 v[2:5], v[178:181], v[214:217], v[2:5]
	s_setprio 0
	s_barrier
	s_add_i32 s71, s71, 2
	s_add_u32 s64, s64, 0x100
	s_addc_u32 s65, s65, 0
	s_add_u32 s69, s69, 0x100
	s_addc_u32 s70, s70, 0
	.p2align	6

.LBB0_376:
	v_mov_b32_e32 v10, 0
	s_waitcnt lgkmcnt(0)
	v_lshl_add_u64 v[2:3], s[72:73], 0, v[168:169]
	v_lshl_add_u64 v[4:5], s[72:73], 0, v[170:171]
	v_lshl_add_u64 v[6:7], s[70:71], 0, v[172:173]
	v_lshl_add_u64 v[8:9], s[70:71], 0, v[174:175]
	s_mov_b32 s54, -2
	s_mov_b64 s[74:75], 0
	v_mov_b32_e32 v11, v10
	v_mov_b32_e32 v12, v10
	v_mov_b32_e32 v13, v10
	v_mov_b32_e32 v14, v10
	v_mov_b32_e32 v15, v10
	v_mov_b32_e32 v16, v10
	v_mov_b32_e32 v17, v10
	v_mov_b32_e32 v26, v10
	v_mov_b32_e32 v27, v10
	v_mov_b32_e32 v28, v10
	v_mov_b32_e32 v29, v10
	v_mov_b32_e32 v30, v10
	v_mov_b32_e32 v31, v10
	v_mov_b32_e32 v32, v10
	v_mov_b32_e32 v33, v10
	v_mov_b32_e32 v42, v10
	v_mov_b32_e32 v43, v10
	v_mov_b32_e32 v44, v10
	v_mov_b32_e32 v45, v10
	v_mov_b32_e32 v46, v10
	v_mov_b32_e32 v47, v10
	v_mov_b32_e32 v48, v10
	v_mov_b32_e32 v49, v10
	v_mov_b32_e32 v58, v10
	v_mov_b32_e32 v59, v10
	v_mov_b32_e32 v60, v10
	v_mov_b32_e32 v61, v10
	v_mov_b32_e32 v62, v10
	v_mov_b32_e32 v63, v10
	v_mov_b32_e32 v64, v10
	v_mov_b32_e32 v65, v10
	s_waitcnt vmcnt(0)
	v_mov_b32_e32 v18, v10
	v_mov_b32_e32 v19, v10
	v_mov_b32_e32 v20, v10
	v_mov_b32_e32 v21, v10
	v_mov_b32_e32 v22, v10
	v_mov_b32_e32 v23, v10
	v_mov_b32_e32 v24, v10
	v_mov_b32_e32 v25, v10
	v_mov_b32_e32 v34, v10
	v_mov_b32_e32 v35, v10
	v_mov_b32_e32 v36, v10
	v_mov_b32_e32 v37, v10
	v_mov_b32_e32 v38, v10
	v_mov_b32_e32 v39, v10
	v_mov_b32_e32 v40, v10
	v_mov_b32_e32 v41, v10
	v_mov_b32_e32 v50, v10
	v_mov_b32_e32 v51, v10
	v_mov_b32_e32 v52, v10
	v_mov_b32_e32 v53, v10
	v_mov_b32_e32 v54, v10
	v_mov_b32_e32 v55, v10
	v_mov_b32_e32 v56, v10
	v_mov_b32_e32 v57, v10
	v_mov_b32_e32 v66, v10
	v_mov_b32_e32 v67, v10
	v_mov_b32_e32 v68, v10
	v_mov_b32_e32 v69, v10
	v_mov_b32_e32 v70, v10
	v_mov_b32_e32 v71, v10
	v_mov_b32_e32 v72, v10
	v_mov_b32_e32 v73, v10
	v_mov_b32_e32 v74, v10
	v_mov_b32_e32 v75, v10
	v_mov_b32_e32 v76, v10
	v_mov_b32_e32 v77, v10
	v_mov_b32_e32 v78, v10
	v_mov_b32_e32 v79, v10
	v_mov_b32_e32 v80, v10
	v_mov_b32_e32 v81, v10
	v_mov_b32_e32 v90, v10
	v_mov_b32_e32 v91, v10
	v_mov_b32_e32 v92, v10
	v_mov_b32_e32 v93, v10
	v_mov_b32_e32 v94, v10
	v_mov_b32_e32 v95, v10
	v_mov_b32_e32 v96, v10
	v_mov_b32_e32 v97, v10
	v_mov_b32_e32 v106, v10
	v_mov_b32_e32 v107, v10
	v_mov_b32_e32 v108, v10
	v_mov_b32_e32 v109, v10
	v_mov_b32_e32 v110, v10
	v_mov_b32_e32 v111, v10
	v_mov_b32_e32 v112, v10
	v_mov_b32_e32 v113, v10
	v_mov_b32_e32 v122, v10
	v_mov_b32_e32 v123, v10
	v_mov_b32_e32 v124, v10
	v_mov_b32_e32 v125, v10
	v_mov_b32_e32 v126, v10
	v_mov_b32_e32 v127, v10
	v_mov_b32_e32 v128, v10
	v_mov_b32_e32 v129, v10
	v_mov_b32_e32 v82, v10
	v_mov_b32_e32 v83, v10
	v_mov_b32_e32 v84, v10
	v_mov_b32_e32 v85, v10
	v_mov_b32_e32 v86, v10
	v_mov_b32_e32 v87, v10
	v_mov_b32_e32 v88, v10
	v_mov_b32_e32 v89, v10
	v_mov_b32_e32 v98, v10
	v_mov_b32_e32 v99, v10
	v_mov_b32_e32 v100, v10
	v_mov_b32_e32 v101, v10
	v_mov_b32_e32 v102, v10
	v_mov_b32_e32 v103, v10
	v_mov_b32_e32 v104, v10
	v_mov_b32_e32 v105, v10
	v_mov_b32_e32 v114, v10
	v_mov_b32_e32 v115, v10
	v_mov_b32_e32 v116, v10
	v_mov_b32_e32 v117, v10
	v_mov_b32_e32 v118, v10
	v_mov_b32_e32 v119, v10
	v_mov_b32_e32 v120, v10
	v_mov_b32_e32 v121, v10
	v_mov_b32_e32 v130, v10
	v_mov_b32_e32 v131, v10
	v_mov_b32_e32 v132, v10
	v_mov_b32_e32 v133, v10
	v_mov_b32_e32 v134, v10
	v_mov_b32_e32 v135, v10
	v_mov_b32_e32 v136, v10
	v_mov_b32_e32 v137, v10
	.p2align	6
.LBB0_377:
	ds_read_b128 v[138:141], v191
	ds_read_b128 v[142:145], v191 offset:1024
	ds_read_b128 v[146:149], v191 offset:2048
	ds_read_b128 v[150:153], v191 offset:3072
	ds_read_b128 v[180:183], v192
	ds_read_b128 v[184:187], v192 offset:1024
	ds_read_b128 v[202:205], v192 offset:2048
	ds_read_b128 v[206:209], v192 offset:3072
	v_lshl_add_u64 v[188:189], v[4:5], 0, s[74:75]
	s_add_i32 s36, s38, 0xc000
	v_lshl_add_u64 v[198:199], v[188:189], 0, s[30:31]
	s_mov_b32 m0, s36
	ds_read_b128 v[210:213], v193
	ds_read_b128 v[214:217], v193 offset:1024
	ds_read_b128 v[218:221], v193 offset:2048
	ds_read_b128 v[222:225], v193 offset:3072
	ds_read_b128 v[226:229], v193 offset:4096
	ds_read_b128 v[230:233], v193 offset:5120
	ds_read_b128 v[234:237], v193 offset:6144
	ds_read_b128 v[238:241], v193 offset:7168
	global_load_lds_dwordx4 v[198:199], off
	v_lshl_add_u64 v[198:199], v[2:3], 0, s[74:75]
	s_add_i32 s37, s38, 0xe000
	v_lshl_add_u64 v[242:243], v[198:199], 0, s[30:31]
	s_mov_b32 m0, s37
	s_nop 0
	global_load_lds_dwordx4 v[242:243], off
	s_waitcnt vmcnt(8)
	s_waitcnt lgkmcnt(0)
	s_barrier
	s_setprio 1
	s_waitcnt lgkmcnt(0)
	v_mfma_f32_16x16x32_bf16 v[134:137], v[138:141], v[210:213], v[134:137]
	v_mfma_f32_16x16x32_bf16 v[130:133], v[146:149], v[210:213], v[130:133]
	v_mfma_f32_16x16x32_bf16 v[118:121], v[138:141], v[218:221], v[118:121]
	v_mfma_f32_16x16x32_bf16 v[114:117], v[146:149], v[218:221], v[114:117]
	v_mfma_f32_16x16x32_bf16 v[102:105], v[138:141], v[226:229], v[102:105]
	v_mfma_f32_16x16x32_bf16 v[98:101], v[146:149], v[226:229], v[98:101]
	v_mfma_f32_16x16x32_bf16 v[86:89], v[138:141], v[234:237], v[86:89]
	v_mfma_f32_16x16x32_bf16 v[82:85], v[146:149], v[234:237], v[82:85]
	v_mfma_f32_16x16x32_bf16 v[134:137], v[142:145], v[214:217], v[134:137]
	v_mfma_f32_16x16x32_bf16 v[130:133], v[150:153], v[214:217], v[130:133]
	v_mfma_f32_16x16x32_bf16 v[118:121], v[142:145], v[222:225], v[118:121]
	v_mfma_f32_16x16x32_bf16 v[114:117], v[150:153], v[222:225], v[114:117]
	v_mfma_f32_16x16x32_bf16 v[102:105], v[142:145], v[230:233], v[102:105]
	v_mfma_f32_16x16x32_bf16 v[98:101], v[150:153], v[230:233], v[98:101]
	v_mfma_f32_16x16x32_bf16 v[86:89], v[142:145], v[238:241], v[86:89]
	v_mfma_f32_16x16x32_bf16 v[82:85], v[150:153], v[238:241], v[82:85]
	s_setprio 0
	s_setprio 1
	v_mfma_f32_16x16x32_bf16 v[126:129], v[180:183], v[210:213], v[126:129]
	v_mfma_f32_16x16x32_bf16 v[122:125], v[202:205], v[210:213], v[122:125]
	v_mfma_f32_16x16x32_bf16 v[110:113], v[180:183], v[218:221], v[110:113]
	v_mfma_f32_16x16x32_bf16 v[106:109], v[202:205], v[218:221], v[106:109]
	v_mfma_f32_16x16x32_bf16 v[94:97], v[180:183], v[226:229], v[94:97]
	v_mfma_f32_16x16x32_bf16 v[90:93], v[202:205], v[226:229], v[90:93]
	v_mfma_f32_16x16x32_bf16 v[78:81], v[180:183], v[234:237], v[78:81]
	v_mfma_f32_16x16x32_bf16 v[74:77], v[202:205], v[234:237], v[74:77]
	v_mfma_f32_16x16x32_bf16 v[126:129], v[184:187], v[214:217], v[126:129]
	v_mfma_f32_16x16x32_bf16 v[122:125], v[206:209], v[214:217], v[122:125]
	v_mfma_f32_16x16x32_bf16 v[110:113], v[184:187], v[222:225], v[110:113]
	v_mfma_f32_16x16x32_bf16 v[106:109], v[206:209], v[222:225], v[106:109]
	v_mfma_f32_16x16x32_bf16 v[94:97], v[184:187], v[230:233], v[94:97]
	v_mfma_f32_16x16x32_bf16 v[90:93], v[206:209], v[230:233], v[90:93]
	v_mfma_f32_16x16x32_bf16 v[78:81], v[184:187], v[238:241], v[78:81]
	v_mfma_f32_16x16x32_bf16 v[74:77], v[206:209], v[238:241], v[74:77]
	s_setprio 0
	s_barrier
	v_lshl_add_u64 v[246:247], v[8:9], 0, s[74:75]
	s_add_i32 s83, s79, s27
	v_lshl_add_u64 v[242:243], v[246:247], 0, s[58:59]
	s_mov_b32 m0, s83
	v_lshl_add_u64 v[248:249], v[6:7], 0, s[74:75]
	s_add_i32 s84, s83, 0x2000
	ds_read_b128 v[210:213], v193 offset:16384
	ds_read_b128 v[214:217], v193 offset:17408
	ds_read_b128 v[218:221], v193 offset:18432
	ds_read_b128 v[222:225], v193 offset:19456
	ds_read_b128 v[226:229], v193 offset:20480
	ds_read_b128 v[230:233], v193 offset:21504
	ds_read_b128 v[234:237], v193 offset:22528
	ds_read_b128 v[238:241], v193 offset:23552
	global_load_lds_dwordx4 v[242:243], off
	v_lshl_add_u64 v[242:243], v[248:249], 0, s[58:59]
	s_mov_b32 m0, s84
	s_add_i32 s85, s80, s27
	global_load_lds_dwordx4 v[242:243], off
	v_lshl_add_u64 v[242:243], v[246:247], 0, s[60:61]
	s_mov_b32 m0, s85
	s_add_i32 s86, s85, 0x2000
	global_load_lds_dwordx4 v[242:243], off
	v_lshl_add_u64 v[242:243], v[248:249], 0, s[60:61]
	s_mov_b32 m0, s86
	s_nop 0
	global_load_lds_dwordx4 v[242:243], off
	v_lshl_add_u64 v[242:243], v[188:189], 0, s[58:59]
	s_mov_b32 m0, s38
	s_nop 0
	global_load_lds_dwordx4 v[242:243], off
	v_lshl_add_u64 v[242:243], v[198:199], 0, s[58:59]
	s_mov_b32 m0, s39
	s_nop 0
	global_load_lds_dwordx4 v[242:243], off
	s_waitcnt vmcnt(8)
	s_waitcnt lgkmcnt(0)
	s_barrier
	s_setprio 1
	s_waitcnt lgkmcnt(0)
	v_mfma_f32_16x16x32_bf16 v[70:73], v[138:141], v[210:213], v[70:73]
	v_mfma_f32_16x16x32_bf16 v[66:69], v[146:149], v[210:213], v[66:69]
	v_mfma_f32_16x16x32_bf16 v[54:57], v[138:141], v[218:221], v[54:57]
	v_mfma_f32_16x16x32_bf16 v[50:53], v[146:149], v[218:221], v[50:53]
	v_mfma_f32_16x16x32_bf16 v[38:41], v[138:141], v[226:229], v[38:41]
	v_mfma_f32_16x16x32_bf16 v[34:37], v[146:149], v[226:229], v[34:37]
	v_mfma_f32_16x16x32_bf16 v[22:25], v[138:141], v[234:237], v[22:25]
	v_mfma_f32_16x16x32_bf16 v[18:21], v[146:149], v[234:237], v[18:21]
	v_mfma_f32_16x16x32_bf16 v[70:73], v[142:145], v[214:217], v[70:73]
	v_mfma_f32_16x16x32_bf16 v[66:69], v[150:153], v[214:217], v[66:69]
	v_mfma_f32_16x16x32_bf16 v[54:57], v[142:145], v[222:225], v[54:57]
	v_mfma_f32_16x16x32_bf16 v[50:53], v[150:153], v[222:225], v[50:53]
	v_mfma_f32_16x16x32_bf16 v[38:41], v[142:145], v[230:233], v[38:41]
	v_mfma_f32_16x16x32_bf16 v[34:37], v[150:153], v[230:233], v[34:37]
	v_mfma_f32_16x16x32_bf16 v[22:25], v[142:145], v[238:241], v[22:25]
	v_mfma_f32_16x16x32_bf16 v[18:21], v[150:153], v[238:241], v[18:21]
	s_setprio 0
	s_setprio 1
	v_mfma_f32_16x16x32_bf16 v[62:65], v[180:183], v[210:213], v[62:65]
	v_mfma_f32_16x16x32_bf16 v[58:61], v[202:205], v[210:213], v[58:61]
	v_mfma_f32_16x16x32_bf16 v[46:49], v[180:183], v[218:221], v[46:49]
	v_mfma_f32_16x16x32_bf16 v[42:45], v[202:205], v[218:221], v[42:45]
	v_mfma_f32_16x16x32_bf16 v[30:33], v[180:183], v[226:229], v[30:33]
	v_mfma_f32_16x16x32_bf16 v[26:29], v[202:205], v[226:229], v[26:29]
	v_mfma_f32_16x16x32_bf16 v[14:17], v[180:183], v[234:237], v[14:17]
	v_mfma_f32_16x16x32_bf16 v[10:13], v[202:205], v[234:237], v[10:13]
	v_mfma_f32_16x16x32_bf16 v[62:65], v[184:187], v[214:217], v[62:65]
	v_mfma_f32_16x16x32_bf16 v[58:61], v[206:209], v[214:217], v[58:61]
	v_mfma_f32_16x16x32_bf16 v[46:49], v[184:187], v[222:225], v[46:49]
	v_mfma_f32_16x16x32_bf16 v[42:45], v[206:209], v[222:225], v[42:45]
	v_mfma_f32_16x16x32_bf16 v[30:33], v[184:187], v[230:233], v[30:33]
	v_mfma_f32_16x16x32_bf16 v[26:29], v[206:209], v[230:233], v[26:29]
	v_mfma_f32_16x16x32_bf16 v[14:17], v[184:187], v[238:241], v[14:17]
	v_mfma_f32_16x16x32_bf16 v[10:13], v[206:209], v[238:241], v[10:13]
	s_setprio 0
	s_barrier
	s_add_i32 s87, 0, 0x18000
	s_add_i32 s89, 0, 0x1c000
	v_add_u32_e32 v146, s87, v190
	v_add_u32_e32 v147, s89, v190
	ds_read_b128 v[138:141], v146
	ds_read_b128 v[142:145], v146 offset:1024
	ds_read_b128 v[148:151], v146 offset:2048
	ds_read_b128 v[180:183], v146 offset:3072
	ds_read_b128 v[184:187], v147
	ds_read_b128 v[202:205], v147 offset:1024
	ds_read_b128 v[206:209], v147 offset:2048
	ds_read_b128 v[210:213], v147 offset:3072
	s_mov_b32 m0, s52
	v_lshl_add_u64 v[152:153], v[188:189], 0, s[60:61]
	ds_read_b128 v[214:217], v193 offset:32768
	ds_read_b128 v[218:221], v193 offset:33792
	ds_read_b128 v[222:225], v193 offset:34816
	ds_read_b128 v[226:229], v193 offset:35840
	ds_read_b128 v[230:233], v193 offset:36864
	ds_read_b128 v[234:237], v193 offset:37888
	ds_read_b128 v[238:241], v193 offset:38912
	ds_read_b128 v[242:245], v193 offset:39936
	global_load_lds_dwordx4 v[152:153], off
	v_lshl_add_u64 v[152:153], v[198:199], 0, s[60:61]
	s_mov_b32 m0, s53
	s_nop 0
	global_load_lds_dwordx4 v[152:153], off
	s_waitcnt vmcnt(8)
	s_waitcnt lgkmcnt(0)
	s_barrier
	s_setprio 1
	s_waitcnt lgkmcnt(0)
	v_mfma_f32_16x16x32_bf16 v[134:137], v[138:141], v[214:217], v[134:137]
	v_mfma_f32_16x16x32_bf16 v[130:133], v[148:151], v[214:217], v[130:133]
	v_mfma_f32_16x16x32_bf16 v[118:121], v[138:141], v[222:225], v[118:121]
	v_mfma_f32_16x16x32_bf16 v[114:117], v[148:151], v[222:225], v[114:117]
	v_mfma_f32_16x16x32_bf16 v[102:105], v[138:141], v[230:233], v[102:105]
	v_mfma_f32_16x16x32_bf16 v[98:101], v[148:151], v[230:233], v[98:101]
	v_mfma_f32_16x16x32_bf16 v[86:89], v[138:141], v[238:241], v[86:89]
	v_mfma_f32_16x16x32_bf16 v[82:85], v[148:151], v[238:241], v[82:85]
	v_mfma_f32_16x16x32_bf16 v[134:137], v[142:145], v[218:221], v[134:137]
	v_mfma_f32_16x16x32_bf16 v[130:133], v[180:183], v[218:221], v[130:133]
	v_mfma_f32_16x16x32_bf16 v[118:121], v[142:145], v[226:229], v[118:121]
	v_mfma_f32_16x16x32_bf16 v[114:117], v[180:183], v[226:229], v[114:117]
	v_mfma_f32_16x16x32_bf16 v[102:105], v[142:145], v[234:237], v[102:105]
	v_mfma_f32_16x16x32_bf16 v[98:101], v[180:183], v[234:237], v[98:101]
	v_mfma_f32_16x16x32_bf16 v[86:89], v[142:145], v[242:245], v[86:89]
	v_mfma_f32_16x16x32_bf16 v[82:85], v[180:183], v[242:245], v[82:85]
	s_setprio 0
	s_setprio 1
	v_mfma_f32_16x16x32_bf16 v[126:129], v[184:187], v[214:217], v[126:129]
	v_mfma_f32_16x16x32_bf16 v[122:125], v[206:209], v[214:217], v[122:125]
	v_mfma_f32_16x16x32_bf16 v[110:113], v[184:187], v[222:225], v[110:113]
	v_mfma_f32_16x16x32_bf16 v[106:109], v[206:209], v[222:225], v[106:109]
	v_mfma_f32_16x16x32_bf16 v[94:97], v[184:187], v[230:233], v[94:97]
	v_mfma_f32_16x16x32_bf16 v[90:93], v[206:209], v[230:233], v[90:93]
	v_mfma_f32_16x16x32_bf16 v[78:81], v[184:187], v[238:241], v[78:81]
	v_mfma_f32_16x16x32_bf16 v[74:77], v[206:209], v[238:241], v[74:77]
	v_mfma_f32_16x16x32_bf16 v[126:129], v[202:205], v[218:221], v[126:129]
	v_mfma_f32_16x16x32_bf16 v[122:125], v[210:213], v[218:221], v[122:125]
	v_mfma_f32_16x16x32_bf16 v[110:113], v[202:205], v[226:229], v[110:113]
	v_mfma_f32_16x16x32_bf16 v[106:109], v[210:213], v[226:229], v[106:109]
	v_mfma_f32_16x16x32_bf16 v[94:97], v[202:205], v[234:237], v[94:97]
	v_mfma_f32_16x16x32_bf16 v[90:93], v[210:213], v[234:237], v[90:93]
	v_mfma_f32_16x16x32_bf16 v[78:81], v[202:205], v[242:245], v[78:81]
	v_mfma_f32_16x16x32_bf16 v[74:77], v[210:213], v[242:245], v[74:77]
	s_setprio 0
	s_barrier
	s_add_i32 s87, s87, s27
	v_lshl_add_u64 v[152:153], v[246:247], 0, s[62:63]
	s_mov_b32 m0, s87
	s_add_i32 s88, s87, 0x2000
	ds_read_b128 v[214:217], v193 offset:49152
	ds_read_b128 v[218:221], v193 offset:50176
	ds_read_b128 v[222:225], v193 offset:51200
	ds_read_b128 v[226:229], v193 offset:52224
	ds_read_b128 v[230:233], v193 offset:53248
	ds_read_b128 v[234:237], v193 offset:54272
	ds_read_b128 v[238:241], v193 offset:55296
	ds_read_b128 v[242:245], v193 offset:56320
	global_load_lds_dwordx4 v[152:153], off
	v_lshl_add_u64 v[152:153], v[248:249], 0, s[62:63]
	s_mov_b32 m0, s88
	s_add_i32 s89, s89, s27
	global_load_lds_dwordx4 v[152:153], off
	v_lshl_add_u64 v[152:153], v[246:247], 0, s[64:65]
	s_mov_b32 m0, s89
	s_add_i32 s90, s89, 0x2000
	global_load_lds_dwordx4 v[152:153], off
	v_lshl_add_u64 v[152:153], v[248:249], 0, s[64:65]
	s_mov_b32 m0, s90
	s_nop 0
	global_load_lds_dwordx4 v[152:153], off
	v_lshl_add_u64 v[152:153], v[188:189], 0, s[62:63]
	s_mov_b32 m0, s57
	s_nop 0
	global_load_lds_dwordx4 v[152:153], off
	v_lshl_add_u64 v[152:153], v[198:199], 0, s[62:63]
	s_mov_b32 m0, s67
	s_nop 0
	global_load_lds_dwordx4 v[152:153], off
	s_waitcnt vmcnt(8)
	s_waitcnt lgkmcnt(0)
	s_barrier
	s_setprio 1
	s_waitcnt lgkmcnt(0)
	v_mfma_f32_16x16x32_bf16 v[70:73], v[138:141], v[214:217], v[70:73]
	v_mfma_f32_16x16x32_bf16 v[66:69], v[148:151], v[214:217], v[66:69]
	v_mfma_f32_16x16x32_bf16 v[54:57], v[138:141], v[222:225], v[54:57]
	v_mfma_f32_16x16x32_bf16 v[50:53], v[148:151], v[222:225], v[50:53]
	v_mfma_f32_16x16x32_bf16 v[38:41], v[138:141], v[230:233], v[38:41]
	v_mfma_f32_16x16x32_bf16 v[34:37], v[148:151], v[230:233], v[34:37]
	v_mfma_f32_16x16x32_bf16 v[22:25], v[138:141], v[238:241], v[22:25]
	v_mfma_f32_16x16x32_bf16 v[18:21], v[148:151], v[238:241], v[18:21]
	v_mfma_f32_16x16x32_bf16 v[70:73], v[142:145], v[218:221], v[70:73]
	v_mfma_f32_16x16x32_bf16 v[66:69], v[180:183], v[218:221], v[66:69]
	v_mfma_f32_16x16x32_bf16 v[54:57], v[142:145], v[226:229], v[54:57]
	v_mfma_f32_16x16x32_bf16 v[50:53], v[180:183], v[226:229], v[50:53]
	v_mfma_f32_16x16x32_bf16 v[38:41], v[142:145], v[234:237], v[38:41]
	v_mfma_f32_16x16x32_bf16 v[34:37], v[180:183], v[234:237], v[34:37]
	v_mfma_f32_16x16x32_bf16 v[22:25], v[142:145], v[242:245], v[22:25]
	v_mfma_f32_16x16x32_bf16 v[18:21], v[180:183], v[242:245], v[18:21]
	s_setprio 0
	s_setprio 1
	v_mfma_f32_16x16x32_bf16 v[62:65], v[184:187], v[214:217], v[62:65]
	v_mfma_f32_16x16x32_bf16 v[58:61], v[206:209], v[214:217], v[58:61]
	v_mfma_f32_16x16x32_bf16 v[46:49], v[184:187], v[222:225], v[46:49]
	v_mfma_f32_16x16x32_bf16 v[42:45], v[206:209], v[222:225], v[42:45]
	v_mfma_f32_16x16x32_bf16 v[30:33], v[184:187], v[230:233], v[30:33]
	v_mfma_f32_16x16x32_bf16 v[26:29], v[206:209], v[230:233], v[26:29]
	v_mfma_f32_16x16x32_bf16 v[14:17], v[184:187], v[238:241], v[14:17]
	v_mfma_f32_16x16x32_bf16 v[10:13], v[206:209], v[238:241], v[10:13]
	v_mfma_f32_16x16x32_bf16 v[62:65], v[202:205], v[218:221], v[62:65]
	v_mfma_f32_16x16x32_bf16 v[58:61], v[210:213], v[218:221], v[58:61]
	v_mfma_f32_16x16x32_bf16 v[46:49], v[202:205], v[226:229], v[46:49]
	v_mfma_f32_16x16x32_bf16 v[42:45], v[210:213], v[226:229], v[42:45]
	v_mfma_f32_16x16x32_bf16 v[30:33], v[202:205], v[234:237], v[30:33]
	v_mfma_f32_16x16x32_bf16 v[26:29], v[210:213], v[234:237], v[26:29]
	v_mfma_f32_16x16x32_bf16 v[14:17], v[202:205], v[242:245], v[14:17]
	v_mfma_f32_16x16x32_bf16 v[10:13], v[210:213], v[242:245], v[10:13]
	s_setprio 0
	s_barrier
	s_add_i32 s54, s54, 2
	s_add_u32 s74, s74, 0x100
	s_addc_u32 s75, s75, 0
	s_cmpk_lt_u32 s54, 0x8a
	s_cbranch_scc1 .LBB0_377
	s_add_u32 s54, s72, 0x2b4680
	s_addc_u32 s55, s73, 0
	s_add_u32 s74, s70, 0x4700
	s_addc_u32 s75, s71, 0
	s_movk_i32 s91, 0x8a
	.p2align	6

.LBB0_483:
	s_ashr_i32 s93, s92, 31
	s_lshl_b64 s[22:23], s[92:93], 21
	s_add_u32 s94, s46, s22
	s_addc_u32 s95, s47, s23
	s_and_b64 s[22:23], s[6:7], exec
	s_cselect_b32 s2, s95, s11
	s_cselect_b32 s9, s94, s10
	s_ashr_i32 s91, s90, 31
	s_lshl_b64 s[22:23], s[90:91], 21
	v_readlane_b32 s24, v250, 19
	s_mov_b32 s12, s96
	v_readlane_b32 s25, v250, 20
	s_add_u32 s96, s24, s22
	s_mov_b32 s13, s97
	s_addc_u32 s97, s25, s23
	s_and_b64 s[22:23], s[6:7], exec
	s_cselect_b32 s24, s97, s15
	s_cselect_b32 s25, s96, s14
	s_add_u32 s10, s10, 0x100080
	s_addc_u32 s11, s11, 0
	s_add_u32 s30, s14, 0x100
	v_mov_b32_e32 v2, 0
	s_addc_u32 s31, s15, 0
	s_mov_b32 s36, -2
	v_mov_b32_e32 v3, v2
	v_mov_b32_e32 v4, v2
	v_mov_b32_e32 v5, v2
	v_mov_b32_e32 v6, v2
	v_mov_b32_e32 v7, v2
	v_mov_b32_e32 v8, v2
	v_mov_b32_e32 v9, v2
	v_mov_b32_e32 v34, v2
	v_mov_b32_e32 v35, v2
	v_mov_b32_e32 v36, v2
	v_mov_b32_e32 v37, v2
	v_mov_b32_e32 v38, v2
	v_mov_b32_e32 v39, v2
	v_mov_b32_e32 v40, v2
	v_mov_b32_e32 v41, v2
	v_mov_b32_e32 v50, v2
	v_mov_b32_e32 v51, v2
	v_mov_b32_e32 v52, v2
	v_mov_b32_e32 v53, v2
	v_mov_b32_e32 v54, v2
	v_mov_b32_e32 v55, v2
	v_mov_b32_e32 v56, v2
	v_mov_b32_e32 v57, v2
	v_mov_b32_e32 v66, v2
	v_mov_b32_e32 v67, v2
	v_mov_b32_e32 v68, v2
	v_mov_b32_e32 v69, v2
	v_mov_b32_e32 v70, v2
	v_mov_b32_e32 v71, v2
	v_mov_b32_e32 v72, v2
	v_mov_b32_e32 v73, v2
	v_mov_b32_e32 v10, v2
	v_mov_b32_e32 v11, v2
	v_mov_b32_e32 v12, v2
	v_mov_b32_e32 v13, v2
	v_mov_b32_e32 v14, v2
	v_mov_b32_e32 v15, v2
	v_mov_b32_e32 v16, v2
	v_mov_b32_e32 v17, v2
	v_mov_b32_e32 v42, v2
	v_mov_b32_e32 v43, v2
	v_mov_b32_e32 v44, v2
	v_mov_b32_e32 v45, v2
	v_mov_b32_e32 v46, v2
	v_mov_b32_e32 v47, v2
	v_mov_b32_e32 v48, v2
	v_mov_b32_e32 v49, v2
	v_mov_b32_e32 v58, v2
	v_mov_b32_e32 v59, v2
	v_mov_b32_e32 v60, v2
	v_mov_b32_e32 v61, v2
	v_mov_b32_e32 v62, v2
	v_mov_b32_e32 v63, v2
	v_mov_b32_e32 v64, v2
	v_mov_b32_e32 v65, v2
	v_mov_b32_e32 v74, v2
	v_mov_b32_e32 v75, v2
	v_mov_b32_e32 v76, v2
	v_mov_b32_e32 v77, v2
	v_mov_b32_e32 v78, v2
	v_mov_b32_e32 v79, v2
	v_mov_b32_e32 v80, v2
	v_mov_b32_e32 v81, v2
	v_mov_b32_e32 v82, v2
	v_mov_b32_e32 v83, v2
	v_mov_b32_e32 v84, v2
	v_mov_b32_e32 v85, v2
	v_mov_b32_e32 v86, v2
	v_mov_b32_e32 v87, v2
	v_mov_b32_e32 v88, v2
	v_mov_b32_e32 v89, v2
	v_mov_b32_e32 v98, v2
	v_mov_b32_e32 v99, v2
	v_mov_b32_e32 v100, v2
	v_mov_b32_e32 v101, v2
	v_mov_b32_e32 v102, v2
	v_mov_b32_e32 v103, v2
	v_mov_b32_e32 v104, v2
	v_mov_b32_e32 v105, v2
	v_mov_b32_e32 v114, v2
	v_mov_b32_e32 v115, v2
	v_mov_b32_e32 v116, v2
	v_mov_b32_e32 v117, v2
	v_mov_b32_e32 v118, v2
	v_mov_b32_e32 v119, v2
	v_mov_b32_e32 v120, v2
	v_mov_b32_e32 v121, v2
	v_mov_b32_e32 v130, v2
	v_mov_b32_e32 v131, v2
	v_mov_b32_e32 v132, v2
	v_mov_b32_e32 v133, v2
	v_mov_b32_e32 v134, v2
	v_mov_b32_e32 v135, v2
	v_mov_b32_e32 v136, v2
	v_mov_b32_e32 v137, v2
	v_mov_b32_e32 v90, v2
	v_mov_b32_e32 v91, v2
	v_mov_b32_e32 v92, v2
	v_mov_b32_e32 v93, v2
	v_mov_b32_e32 v94, v2
	v_mov_b32_e32 v95, v2
	v_mov_b32_e32 v96, v2
	v_mov_b32_e32 v97, v2
	v_mov_b32_e32 v106, v2
	v_mov_b32_e32 v107, v2
	v_mov_b32_e32 v108, v2
	v_mov_b32_e32 v109, v2
	v_mov_b32_e32 v110, v2
	v_mov_b32_e32 v111, v2
	v_mov_b32_e32 v112, v2
	v_mov_b32_e32 v113, v2
	v_mov_b32_e32 v122, v2
	v_mov_b32_e32 v123, v2
	v_mov_b32_e32 v124, v2
	v_mov_b32_e32 v125, v2
	v_mov_b32_e32 v126, v2
	v_mov_b32_e32 v127, v2
	v_mov_b32_e32 v128, v2
	v_mov_b32_e32 v129, v2
	v_mov_b32_e32 v138, v2
	v_mov_b32_e32 v139, v2
	v_mov_b32_e32 v140, v2
	v_mov_b32_e32 v141, v2
	v_mov_b32_e32 v142, v2
	v_mov_b32_e32 v143, v2
	v_mov_b32_e32 v144, v2
	v_mov_b32_e32 v145, v2
	s_waitcnt vmcnt(0)
	.p2align	6

.LBB0_829:
	s_add_u32 s30, s30, 0x38080
	s_addc_u32 s31, s31, 0
	s_add_u32 s73, s54, 0x100
	s_addc_u32 s74, s55, 0
	s_mov_b32 s75, -2
	ds_read_b128 v[170:173], v167
	ds_read_b128 v[174:177], v167 offset:1024
	ds_read_b128 v[178:181], v167 offset:2048
	ds_read_b128 v[182:185], v167 offset:3072
	ds_read_b128 v[186:189], v168
	ds_read_b128 v[190:193], v168 offset:1024
	ds_read_b128 v[194:197], v168 offset:2048
	ds_read_b128 v[202:205], v168 offset:3072
	s_add_u32 s54, s30, 0xfffc8080
	s_addc_u32 s55, s31, -1
	s_cmp_eq_u32 s75, 10
	s_cselect_b32 s67, s7, s55
	s_cselect_b32 s66, s6, s54
	s_cselect_b32 s55, s25, s74
	s_cselect_b32 s54, s24, s73
	v_lshl_add_u64 v[146:147], s[30:31], 0, v[138:139]
	s_add_i32 m0, s26, 0xc000
	ds_read_b128 v[206:209], v169
	ds_read_b128 v[210:213], v169 offset:1024
	ds_read_b128 v[214:217], v169 offset:2048
	ds_read_b128 v[218:221], v169 offset:3072
	ds_read_b128 v[222:225], v169 offset:4096
	ds_read_b128 v[226:229], v169 offset:5120
	ds_read_b128 v[230:233], v169 offset:6144
	ds_read_b128 v[234:237], v169 offset:7168
	global_load_lds_dwordx4 v[146:147], off
	v_lshl_add_u64 v[146:147], s[30:31], 0, v[140:141]
	s_add_i32 m0, s26, 0xe000
	s_nop 0
	global_load_lds_dwordx4 v[146:147], off
	s_waitcnt vmcnt(8)
	s_waitcnt lgkmcnt(0)
	s_barrier
	s_setprio 1
	s_waitcnt lgkmcnt(0)
	v_mfma_f32_16x16x32_bf16 v[126:129], v[170:173], v[206:209], 0
	v_mfma_f32_16x16x32_bf16 v[122:125], v[178:181], v[206:209], 0
	v_mfma_f32_16x16x32_bf16 v[110:113], v[170:173], v[214:217], 0
	v_mfma_f32_16x16x32_bf16 v[106:109], v[178:181], v[214:217], 0
	v_mfma_f32_16x16x32_bf16 v[102:105], v[170:173], v[222:225], 0
	v_mfma_f32_16x16x32_bf16 v[98:101], v[178:181], v[222:225], 0
	v_mfma_f32_16x16x32_bf16 v[86:89], v[170:173], v[230:233], 0
	v_mfma_f32_16x16x32_bf16 v[82:85], v[178:181], v[230:233], 0
	v_mfma_f32_16x16x32_bf16 v[126:129], v[174:177], v[210:213], v[126:129]
	v_mfma_f32_16x16x32_bf16 v[122:125], v[182:185], v[210:213], v[122:125]
	v_mfma_f32_16x16x32_bf16 v[110:113], v[174:177], v[218:221], v[110:113]
	v_mfma_f32_16x16x32_bf16 v[106:109], v[182:185], v[218:221], v[106:109]
	v_mfma_f32_16x16x32_bf16 v[102:105], v[174:177], v[226:229], v[102:105]
	v_mfma_f32_16x16x32_bf16 v[98:101], v[182:185], v[226:229], v[98:101]
	v_mfma_f32_16x16x32_bf16 v[86:89], v[174:177], v[234:237], v[86:89]
	v_mfma_f32_16x16x32_bf16 v[82:85], v[182:185], v[234:237], v[82:85]
	s_setprio 0
	s_setprio 1
	v_mfma_f32_16x16x32_bf16 v[118:121], v[186:189], v[206:209], 0
	v_mfma_f32_16x16x32_bf16 v[114:117], v[194:197], v[206:209], 0
	v_mfma_f32_16x16x32_bf16 v[94:97], v[186:189], v[214:217], 0
	v_mfma_f32_16x16x32_bf16 v[90:93], v[194:197], v[214:217], 0
	v_mfma_f32_16x16x32_bf16 v[78:81], v[186:189], v[222:225], 0
	v_mfma_f32_16x16x32_bf16 v[74:77], v[194:197], v[222:225], 0
	v_mfma_f32_16x16x32_bf16 v[70:73], v[186:189], v[230:233], 0
	v_mfma_f32_16x16x32_bf16 v[66:69], v[194:197], v[230:233], 0
	v_mfma_f32_16x16x32_bf16 v[118:121], v[190:193], v[210:213], v[118:121]
	v_mfma_f32_16x16x32_bf16 v[114:117], v[202:205], v[210:213], v[114:117]
	v_mfma_f32_16x16x32_bf16 v[94:97], v[190:193], v[218:221], v[94:97]
	v_mfma_f32_16x16x32_bf16 v[90:93], v[202:205], v[218:221], v[90:93]
	v_mfma_f32_16x16x32_bf16 v[78:81], v[190:193], v[226:229], v[78:81]
	v_mfma_f32_16x16x32_bf16 v[74:77], v[202:205], v[226:229], v[74:77]
	v_mfma_f32_16x16x32_bf16 v[70:73], v[190:193], v[234:237], v[70:73]
	v_mfma_f32_16x16x32_bf16 v[66:69], v[202:205], v[234:237], v[66:69]
	s_setprio 0
	s_barrier
	s_add_i32 s76, s56, s21
	v_lshl_add_u64 v[146:147], s[54:55], 0, v[134:135]
	s_mov_b32 m0, s76
	ds_read_b128 v[206:209], v169 offset:16384
	ds_read_b128 v[210:213], v169 offset:17408
	ds_read_b128 v[214:217], v169 offset:18432
	ds_read_b128 v[218:221], v169 offset:19456
	ds_read_b128 v[222:225], v169 offset:20480
	ds_read_b128 v[226:229], v169 offset:21504
	ds_read_b128 v[230:233], v169 offset:22528
	ds_read_b128 v[234:237], v169 offset:23552
	global_load_lds_dwordx4 v[146:147], off
	s_add_i32 m0, s76, 0x2000
	s_add_u32 s76, s54, 0x38000
	v_lshl_add_u64 v[198:199], s[54:55], 0, v[130:131]
	s_addc_u32 s77, s55, 0
	s_add_i32 s78, s57, s21
	global_load_lds_dwordx4 v[198:199], off
	v_lshl_add_u64 v[238:239], s[76:77], 0, v[134:135]
	s_mov_b32 m0, s78
	v_lshl_add_u64 v[240:241], s[66:67], 0, v[132:133]
	global_load_lds_dwordx4 v[238:239], off
	v_lshl_add_u64 v[238:239], s[76:77], 0, v[130:131]
	s_add_i32 m0, s78, 0x2000
	s_nop 0
	global_load_lds_dwordx4 v[238:239], off
	v_lshl_add_u64 v[238:239], s[66:67], 0, v[136:137]
	s_mov_b32 m0, s26
	s_nop 0
	global_load_lds_dwordx4 v[238:239], off
	s_mov_b32 m0, s27
	s_nop 0
	global_load_lds_dwordx4 v[240:241], off
	s_waitcnt vmcnt(8)
	s_waitcnt lgkmcnt(0)
	s_barrier
	s_setprio 1
	s_waitcnt lgkmcnt(0)
	v_mfma_f32_16x16x32_bf16 v[62:65], v[170:173], v[206:209], 0
	v_mfma_f32_16x16x32_bf16 v[58:61], v[178:181], v[206:209], 0
	v_mfma_f32_16x16x32_bf16 v[54:57], v[170:173], v[214:217], 0
	v_mfma_f32_16x16x32_bf16 v[50:53], v[178:181], v[214:217], 0
	v_mfma_f32_16x16x32_bf16 v[38:41], v[170:173], v[222:225], 0
	v_mfma_f32_16x16x32_bf16 v[34:37], v[178:181], v[222:225], 0
	v_mfma_f32_16x16x32_bf16 v[22:25], v[170:173], v[230:233], 0
	v_mfma_f32_16x16x32_bf16 v[18:21], v[178:181], v[230:233], 0
	v_mfma_f32_16x16x32_bf16 v[62:65], v[174:177], v[210:213], v[62:65]
	v_mfma_f32_16x16x32_bf16 v[58:61], v[182:185], v[210:213], v[58:61]
	v_mfma_f32_16x16x32_bf16 v[54:57], v[174:177], v[218:221], v[54:57]
	v_mfma_f32_16x16x32_bf16 v[50:53], v[182:185], v[218:221], v[50:53]
	v_mfma_f32_16x16x32_bf16 v[38:41], v[174:177], v[226:229], v[38:41]
	v_mfma_f32_16x16x32_bf16 v[34:37], v[182:185], v[226:229], v[34:37]
	v_mfma_f32_16x16x32_bf16 v[22:25], v[174:177], v[234:237], v[22:25]
	v_mfma_f32_16x16x32_bf16 v[18:21], v[182:185], v[234:237], v[18:21]
	s_setprio 0
	s_setprio 1
	v_mfma_f32_16x16x32_bf16 v[46:49], v[186:189], v[206:209], 0
	v_mfma_f32_16x16x32_bf16 v[42:45], v[194:197], v[206:209], 0
	v_mfma_f32_16x16x32_bf16 v[30:33], v[186:189], v[214:217], 0
	v_mfma_f32_16x16x32_bf16 v[26:29], v[194:197], v[214:217], 0
	v_mfma_f32_16x16x32_bf16 v[14:17], v[186:189], v[222:225], 0
	v_mfma_f32_16x16x32_bf16 v[10:13], v[194:197], v[222:225], 0
	v_mfma_f32_16x16x32_bf16 v[6:9], v[186:189], v[230:233], 0
	v_mfma_f32_16x16x32_bf16 v[2:5], v[194:197], v[230:233], 0
	v_mfma_f32_16x16x32_bf16 v[46:49], v[190:193], v[210:213], v[46:49]
	v_mfma_f32_16x16x32_bf16 v[42:45], v[202:205], v[210:213], v[42:45]
	v_mfma_f32_16x16x32_bf16 v[30:33], v[190:193], v[218:221], v[30:33]
	v_mfma_f32_16x16x32_bf16 v[26:29], v[202:205], v[218:221], v[26:29]
	v_mfma_f32_16x16x32_bf16 v[14:17], v[190:193], v[226:229], v[14:17]
	v_mfma_f32_16x16x32_bf16 v[10:13], v[202:205], v[226:229], v[10:13]
	v_mfma_f32_16x16x32_bf16 v[6:9], v[190:193], v[234:237], v[6:9]
	v_mfma_f32_16x16x32_bf16 v[2:5], v[202:205], v[234:237], v[2:5]
	s_setprio 0
	s_barrier
	s_add_i32 s76, 0, 0x18000
	s_add_i32 s77, 0, 0x1c000
	v_add_u32_e32 v182, s76, v163
	v_add_u32_e32 v201, s77, v163
	ds_read_b128 v[170:173], v182
	ds_read_b128 v[174:177], v182 offset:1024
	ds_read_b128 v[178:181], v182 offset:2048
	ds_read_b128 v[182:185], v182 offset:3072
	ds_read_b128 v[186:189], v201
	ds_read_b128 v[190:193], v201 offset:1024
	ds_read_b128 v[194:197], v201 offset:2048
	ds_read_b128 v[202:205], v201 offset:3072
	s_add_u32 s66, s66, 0x38000
	s_addc_u32 s67, s67, 0
	s_mov_b32 m0, s36
	v_lshl_add_u64 v[242:243], s[66:67], 0, v[136:137]
	ds_read_b128 v[206:209], v169 offset:32768
	ds_read_b128 v[210:213], v169 offset:33792
	ds_read_b128 v[214:217], v169 offset:34816
	ds_read_b128 v[218:221], v169 offset:35840
	ds_read_b128 v[222:225], v169 offset:36864
	ds_read_b128 v[226:229], v169 offset:37888
	ds_read_b128 v[230:233], v169 offset:38912
	ds_read_b128 v[234:237], v169 offset:39936
	global_load_lds_dwordx4 v[242:243], off
	v_lshl_add_u64 v[242:243], s[66:67], 0, v[132:133]
	s_mov_b32 m0, s37
	s_nop 0
	global_load_lds_dwordx4 v[242:243], off
	s_waitcnt vmcnt(8)
	s_waitcnt lgkmcnt(0)
	s_barrier
	s_setprio 1
	s_waitcnt lgkmcnt(0)
	v_mfma_f32_16x16x32_bf16 v[126:129], v[170:173], v[206:209], v[126:129]
	v_mfma_f32_16x16x32_bf16 v[122:125], v[178:181], v[206:209], v[122:125]
	v_mfma_f32_16x16x32_bf16 v[110:113], v[170:173], v[214:217], v[110:113]
	v_mfma_f32_16x16x32_bf16 v[106:109], v[178:181], v[214:217], v[106:109]
	v_mfma_f32_16x16x32_bf16 v[102:105], v[170:173], v[222:225], v[102:105]
	v_mfma_f32_16x16x32_bf16 v[98:101], v[178:181], v[222:225], v[98:101]
	v_mfma_f32_16x16x32_bf16 v[86:89], v[170:173], v[230:233], v[86:89]
	v_mfma_f32_16x16x32_bf16 v[82:85], v[178:181], v[230:233], v[82:85]
	v_mfma_f32_16x16x32_bf16 v[126:129], v[174:177], v[210:213], v[126:129]
	v_mfma_f32_16x16x32_bf16 v[122:125], v[182:185], v[210:213], v[122:125]
	v_mfma_f32_16x16x32_bf16 v[110:113], v[174:177], v[218:221], v[110:113]
	v_mfma_f32_16x16x32_bf16 v[106:109], v[182:185], v[218:221], v[106:109]
	v_mfma_f32_16x16x32_bf16 v[102:105], v[174:177], v[226:229], v[102:105]
	v_mfma_f32_16x16x32_bf16 v[98:101], v[182:185], v[226:229], v[98:101]
	v_mfma_f32_16x16x32_bf16 v[86:89], v[174:177], v[234:237], v[86:89]
	v_mfma_f32_16x16x32_bf16 v[82:85], v[182:185], v[234:237], v[82:85]
	s_setprio 0
	s_setprio 1
	v_mfma_f32_16x16x32_bf16 v[118:121], v[186:189], v[206:209], v[118:121]
	v_mfma_f32_16x16x32_bf16 v[114:117], v[194:197], v[206:209], v[114:117]
	v_mfma_f32_16x16x32_bf16 v[94:97], v[186:189], v[214:217], v[94:97]
	v_mfma_f32_16x16x32_bf16 v[90:93], v[194:197], v[214:217], v[90:93]
	v_mfma_f32_16x16x32_bf16 v[78:81], v[186:189], v[222:225], v[78:81]
	v_mfma_f32_16x16x32_bf16 v[74:77], v[194:197], v[222:225], v[74:77]
	v_mfma_f32_16x16x32_bf16 v[70:73], v[186:189], v[230:233], v[70:73]
	v_mfma_f32_16x16x32_bf16 v[66:69], v[194:197], v[230:233], v[66:69]
	v_mfma_f32_16x16x32_bf16 v[118:121], v[190:193], v[210:213], v[118:121]
	v_mfma_f32_16x16x32_bf16 v[114:117], v[202:205], v[210:213], v[114:117]
	v_mfma_f32_16x16x32_bf16 v[94:97], v[190:193], v[218:221], v[94:97]
	v_mfma_f32_16x16x32_bf16 v[90:93], v[202:205], v[218:221], v[90:93]
	v_mfma_f32_16x16x32_bf16 v[78:81], v[190:193], v[226:229], v[78:81]
	v_mfma_f32_16x16x32_bf16 v[74:77], v[202:205], v[226:229], v[74:77]
	v_mfma_f32_16x16x32_bf16 v[70:73], v[190:193], v[234:237], v[70:73]
	v_mfma_f32_16x16x32_bf16 v[66:69], v[202:205], v[234:237], v[66:69]
	s_setprio 0
	s_barrier
	s_add_i32 s66, s76, s21
	v_lshl_add_u64 v[146:147], v[146:147], 0, s[14:15]
	s_mov_b32 m0, s66
	ds_read_b128 v[206:209], v169 offset:49152
	ds_read_b128 v[210:213], v169 offset:50176
	ds_read_b128 v[214:217], v169 offset:51200
	ds_read_b128 v[218:221], v169 offset:52224
	ds_read_b128 v[222:225], v169 offset:53248
	ds_read_b128 v[226:229], v169 offset:54272
	ds_read_b128 v[230:233], v169 offset:55296
	ds_read_b128 v[234:237], v169 offset:56320
	global_load_lds_dwordx4 v[146:147], off
	s_add_i32 m0, s66, 0x2000
	s_add_u32 s54, s54, 0x38080
	v_lshl_add_u64 v[146:147], v[198:199], 0, s[14:15]
	s_addc_u32 s55, s55, 0
	s_add_i32 s66, s77, s21
	global_load_lds_dwordx4 v[146:147], off
	v_lshl_add_u64 v[146:147], s[54:55], 0, v[134:135]
	s_mov_b32 m0, s66
	s_nop 0
	global_load_lds_dwordx4 v[146:147], off
	v_lshl_add_u64 v[146:147], s[54:55], 0, v[130:131]
	s_add_i32 m0, s66, 0x2000
	s_nop 0
	global_load_lds_dwordx4 v[146:147], off
	v_lshl_add_u64 v[146:147], v[238:239], 0, s[14:15]
	s_mov_b32 m0, s39
	s_nop 0
	global_load_lds_dwordx4 v[146:147], off
	v_lshl_add_u64 v[146:147], v[240:241], 0, s[14:15]
	s_mov_b32 m0, s52
	s_nop 0
	global_load_lds_dwordx4 v[146:147], off
	s_waitcnt vmcnt(8)
	s_waitcnt lgkmcnt(0)
	s_barrier
	s_setprio 1
	s_waitcnt lgkmcnt(0)
	v_mfma_f32_16x16x32_bf16 v[62:65], v[170:173], v[206:209], v[62:65]
	v_mfma_f32_16x16x32_bf16 v[58:61], v[178:181], v[206:209], v[58:61]
	v_mfma_f32_16x16x32_bf16 v[54:57], v[170:173], v[214:217], v[54:57]
	v_mfma_f32_16x16x32_bf16 v[50:53], v[178:181], v[214:217], v[50:53]
	v_mfma_f32_16x16x32_bf16 v[38:41], v[170:173], v[222:225], v[38:41]
	v_mfma_f32_16x16x32_bf16 v[34:37], v[178:181], v[222:225], v[34:37]
	v_mfma_f32_16x16x32_bf16 v[22:25], v[170:173], v[230:233], v[22:25]
	v_mfma_f32_16x16x32_bf16 v[18:21], v[178:181], v[230:233], v[18:21]
	v_mfma_f32_16x16x32_bf16 v[62:65], v[174:177], v[210:213], v[62:65]
	v_mfma_f32_16x16x32_bf16 v[58:61], v[182:185], v[210:213], v[58:61]
	v_mfma_f32_16x16x32_bf16 v[54:57], v[174:177], v[218:221], v[54:57]
	v_mfma_f32_16x16x32_bf16 v[50:53], v[182:185], v[218:221], v[50:53]
	v_mfma_f32_16x16x32_bf16 v[38:41], v[174:177], v[226:229], v[38:41]
	v_mfma_f32_16x16x32_bf16 v[34:37], v[182:185], v[226:229], v[34:37]
	v_mfma_f32_16x16x32_bf16 v[22:25], v[174:177], v[234:237], v[22:25]
	v_mfma_f32_16x16x32_bf16 v[18:21], v[182:185], v[234:237], v[18:21]
	s_setprio 0
	s_setprio 1
	v_mfma_f32_16x16x32_bf16 v[46:49], v[186:189], v[206:209], v[46:49]
	v_mfma_f32_16x16x32_bf16 v[42:45], v[194:197], v[206:209], v[42:45]
	v_mfma_f32_16x16x32_bf16 v[30:33], v[186:189], v[214:217], v[30:33]
	v_mfma_f32_16x16x32_bf16 v[26:29], v[194:197], v[214:217], v[26:29]
	v_mfma_f32_16x16x32_bf16 v[14:17], v[186:189], v[222:225], v[14:17]
	v_mfma_f32_16x16x32_bf16 v[10:13], v[194:197], v[222:225], v[10:13]
	v_mfma_f32_16x16x32_bf16 v[6:9], v[186:189], v[230:233], v[6:9]
	v_mfma_f32_16x16x32_bf16 v[2:5], v[194:197], v[230:233], v[2:5]
	v_mfma_f32_16x16x32_bf16 v[46:49], v[190:193], v[210:213], v[46:49]
	v_mfma_f32_16x16x32_bf16 v[42:45], v[202:205], v[210:213], v[42:45]
	v_mfma_f32_16x16x32_bf16 v[30:33], v[190:193], v[218:221], v[30:33]
	v_mfma_f32_16x16x32_bf16 v[26:29], v[202:205], v[218:221], v[26:29]
	v_mfma_f32_16x16x32_bf16 v[14:17], v[190:193], v[226:229], v[14:17]
	v_mfma_f32_16x16x32_bf16 v[10:13], v[202:205], v[226:229], v[10:13]
	v_mfma_f32_16x16x32_bf16 v[6:9], v[190:193], v[234:237], v[6:9]
	v_mfma_f32_16x16x32_bf16 v[2:5], v[202:205], v[234:237], v[2:5]
	s_setprio 0
	s_barrier
	s_add_i32 s75, s75, 2
	s_add_u32 s30, s30, 0x100
	s_addc_u32 s31, s31, 0
	s_add_u32 s73, s73, 0x100
	s_addc_u32 s74, s74, 0
	.p2align	6

.LBB0_877:
	s_ashr_i32 s25, s24, 31
	s_lshl_b64 s[30:31], s[24:25], 18
	s_add_u32 s30, s50, s30
	s_addc_u32 s31, s51, s31
	s_and_b64 s[64:65], s[4:5], exec
	s_cselect_b32 s25, s31, s69
	s_cselect_b32 s77, s30, s68
	s_ashr_i32 s23, s22, 31
	s_lshl_b64 s[64:65], s[22:23], 18
	s_add_u32 s64, s26, s64
	s_addc_u32 s65, s27, s65
	s_and_b64 s[70:71], s[4:5], exec
	s_cselect_b32 s23, s65, s55
	s_cselect_b32 s78, s64, s54
	s_add_u32 s68, s68, 0x20080
	s_addc_u32 s69, s69, 0
	s_add_u32 s79, s54, 0x100
	s_addc_u32 s80, s55, 0
	s_mov_b32 s81, -2
	ds_read_b128 v[152:155], v148
	ds_read_b128 v[156:159], v148 offset:1024
	ds_read_b128 v[166:169], v148 offset:2048
	ds_read_b128 v[170:173], v148 offset:3072
	ds_read_b128 v[174:177], v149
	ds_read_b128 v[178:181], v149 offset:1024
	ds_read_b128 v[182:185], v149 offset:2048
	ds_read_b128 v[186:189], v149 offset:3072
	s_add_u32 s54, s68, 0xfffe0080
	s_addc_u32 s55, s69, -1
	s_cmp_eq_u32 s81, 4
	s_cselect_b32 s71, s25, s55
	s_cselect_b32 s70, s77, s54
	s_cselect_b32 s55, s23, s80
	s_cselect_b32 s54, s78, s79
	v_lshl_add_u64 v[160:161], s[68:69], 0, v[138:139]
	s_add_i32 m0, s36, 0xc000
	ds_read_b128 v[190:193], v150
	ds_read_b128 v[194:197], v150 offset:1024
	ds_read_b128 v[202:205], v150 offset:2048
	ds_read_b128 v[206:209], v150 offset:3072
	ds_read_b128 v[210:213], v150 offset:4096
	ds_read_b128 v[214:217], v150 offset:5120
	ds_read_b128 v[218:221], v150 offset:6144
	ds_read_b128 v[222:225], v150 offset:7168
	global_load_lds_dwordx4 v[160:161], off
	v_lshl_add_u64 v[160:161], s[68:69], 0, v[140:141]
	s_add_i32 m0, s36, 0xe000
	s_nop 0
	global_load_lds_dwordx4 v[160:161], off
	s_waitcnt vmcnt(8)
	s_waitcnt lgkmcnt(0)
	s_barrier
	s_setprio 1
	s_waitcnt lgkmcnt(0)
	v_mfma_f32_16x16x32_bf16 v[126:129], v[152:155], v[190:193], 0
	v_mfma_f32_16x16x32_bf16 v[122:125], v[166:169], v[190:193], 0
	v_mfma_f32_16x16x32_bf16 v[110:113], v[152:155], v[202:205], 0
	v_mfma_f32_16x16x32_bf16 v[106:109], v[166:169], v[202:205], 0
	v_mfma_f32_16x16x32_bf16 v[94:97], v[152:155], v[210:213], 0
	v_mfma_f32_16x16x32_bf16 v[90:93], v[166:169], v[210:213], 0
	v_mfma_f32_16x16x32_bf16 v[78:81], v[152:155], v[218:221], 0
	v_mfma_f32_16x16x32_bf16 v[74:77], v[166:169], v[218:221], 0
	v_mfma_f32_16x16x32_bf16 v[126:129], v[156:159], v[194:197], v[126:129]
	v_mfma_f32_16x16x32_bf16 v[122:125], v[170:173], v[194:197], v[122:125]
	v_mfma_f32_16x16x32_bf16 v[110:113], v[156:159], v[206:209], v[110:113]
	v_mfma_f32_16x16x32_bf16 v[106:109], v[170:173], v[206:209], v[106:109]
	v_mfma_f32_16x16x32_bf16 v[94:97], v[156:159], v[214:217], v[94:97]
	v_mfma_f32_16x16x32_bf16 v[90:93], v[170:173], v[214:217], v[90:93]
	v_mfma_f32_16x16x32_bf16 v[78:81], v[156:159], v[222:225], v[78:81]
	v_mfma_f32_16x16x32_bf16 v[74:77], v[170:173], v[222:225], v[74:77]
	s_setprio 0
	s_setprio 1
	v_mfma_f32_16x16x32_bf16 v[118:121], v[174:177], v[190:193], 0
	v_mfma_f32_16x16x32_bf16 v[114:117], v[182:185], v[190:193], 0
	v_mfma_f32_16x16x32_bf16 v[102:105], v[174:177], v[202:205], 0
	v_mfma_f32_16x16x32_bf16 v[98:101], v[182:185], v[202:205], 0
	v_mfma_f32_16x16x32_bf16 v[86:89], v[174:177], v[210:213], 0
	v_mfma_f32_16x16x32_bf16 v[82:85], v[182:185], v[210:213], 0
	v_mfma_f32_16x16x32_bf16 v[70:73], v[174:177], v[218:221], 0
	v_mfma_f32_16x16x32_bf16 v[66:69], v[182:185], v[218:221], 0
	v_mfma_f32_16x16x32_bf16 v[118:121], v[178:181], v[194:197], v[118:121]
	v_mfma_f32_16x16x32_bf16 v[114:117], v[186:189], v[194:197], v[114:117]
	v_mfma_f32_16x16x32_bf16 v[102:105], v[178:181], v[206:209], v[102:105]
	v_mfma_f32_16x16x32_bf16 v[98:101], v[186:189], v[206:209], v[98:101]
	v_mfma_f32_16x16x32_bf16 v[86:89], v[178:181], v[214:217], v[86:89]
	v_mfma_f32_16x16x32_bf16 v[82:85], v[186:189], v[214:217], v[82:85]
	v_mfma_f32_16x16x32_bf16 v[70:73], v[178:181], v[222:225], v[70:73]
	v_mfma_f32_16x16x32_bf16 v[66:69], v[186:189], v[222:225], v[66:69]
	s_setprio 0
	s_barrier
	s_add_i32 s82, s73, s2
	v_lshl_add_u64 v[160:161], s[54:55], 0, v[132:133]
	s_mov_b32 m0, s82
	ds_read_b128 v[190:193], v150 offset:16384
	ds_read_b128 v[194:197], v150 offset:17408
	ds_read_b128 v[202:205], v150 offset:18432
	ds_read_b128 v[206:209], v150 offset:19456
	ds_read_b128 v[210:213], v150 offset:20480
	ds_read_b128 v[214:217], v150 offset:21504
	ds_read_b128 v[218:221], v150 offset:22528
	ds_read_b128 v[222:225], v150 offset:23552
	global_load_lds_dwordx4 v[160:161], off
	s_add_i32 m0, s82, 0x2000
	s_add_u32 s82, s54, 0x20000
	v_lshl_add_u64 v[198:199], s[54:55], 0, v[136:137]
	s_addc_u32 s83, s55, 0
	s_add_i32 s84, s74, s2
	global_load_lds_dwordx4 v[198:199], off
	v_lshl_add_u64 v[226:227], s[82:83], 0, v[132:133]
	s_mov_b32 m0, s84
	v_lshl_add_u64 v[228:229], s[70:71], 0, v[134:135]
	global_load_lds_dwordx4 v[226:227], off
	v_lshl_add_u64 v[226:227], s[82:83], 0, v[136:137]
	s_add_i32 m0, s84, 0x2000
	s_nop 0
	global_load_lds_dwordx4 v[226:227], off
	v_lshl_add_u64 v[226:227], s[70:71], 0, v[130:131]
	s_mov_b32 m0, s36
	s_nop 0
	global_load_lds_dwordx4 v[226:227], off
	s_mov_b32 m0, s37
	s_nop 0
	global_load_lds_dwordx4 v[228:229], off
	s_waitcnt vmcnt(8)
	s_waitcnt lgkmcnt(0)
	s_barrier
	s_setprio 1
	s_waitcnt lgkmcnt(0)
	v_mfma_f32_16x16x32_bf16 v[62:65], v[152:155], v[190:193], 0
	v_mfma_f32_16x16x32_bf16 v[58:61], v[166:169], v[190:193], 0
	v_mfma_f32_16x16x32_bf16 v[46:49], v[152:155], v[202:205], 0
	v_mfma_f32_16x16x32_bf16 v[42:45], v[166:169], v[202:205], 0
	v_mfma_f32_16x16x32_bf16 v[30:33], v[152:155], v[210:213], 0
	v_mfma_f32_16x16x32_bf16 v[26:29], v[166:169], v[210:213], 0
	v_mfma_f32_16x16x32_bf16 v[14:17], v[152:155], v[218:221], 0
	v_mfma_f32_16x16x32_bf16 v[10:13], v[166:169], v[218:221], 0
	v_mfma_f32_16x16x32_bf16 v[62:65], v[156:159], v[194:197], v[62:65]
	v_mfma_f32_16x16x32_bf16 v[58:61], v[170:173], v[194:197], v[58:61]
	v_mfma_f32_16x16x32_bf16 v[46:49], v[156:159], v[206:209], v[46:49]
	v_mfma_f32_16x16x32_bf16 v[42:45], v[170:173], v[206:209], v[42:45]
	v_mfma_f32_16x16x32_bf16 v[30:33], v[156:159], v[214:217], v[30:33]
	v_mfma_f32_16x16x32_bf16 v[26:29], v[170:173], v[214:217], v[26:29]
	v_mfma_f32_16x16x32_bf16 v[14:17], v[156:159], v[222:225], v[14:17]
	v_mfma_f32_16x16x32_bf16 v[10:13], v[170:173], v[222:225], v[10:13]
	s_setprio 0
	s_setprio 1
	v_mfma_f32_16x16x32_bf16 v[54:57], v[174:177], v[190:193], 0
	v_mfma_f32_16x16x32_bf16 v[50:53], v[182:185], v[190:193], 0
	v_mfma_f32_16x16x32_bf16 v[38:41], v[174:177], v[202:205], 0
	v_mfma_f32_16x16x32_bf16 v[34:37], v[182:185], v[202:205], 0
	v_mfma_f32_16x16x32_bf16 v[22:25], v[174:177], v[210:213], 0
	v_mfma_f32_16x16x32_bf16 v[18:21], v[182:185], v[210:213], 0
	v_mfma_f32_16x16x32_bf16 v[6:9], v[174:177], v[218:221], 0
	v_mfma_f32_16x16x32_bf16 v[2:5], v[182:185], v[218:221], 0
	v_mfma_f32_16x16x32_bf16 v[54:57], v[178:181], v[194:197], v[54:57]
	v_mfma_f32_16x16x32_bf16 v[50:53], v[186:189], v[194:197], v[50:53]
	v_mfma_f32_16x16x32_bf16 v[38:41], v[178:181], v[206:209], v[38:41]
	v_mfma_f32_16x16x32_bf16 v[34:37], v[186:189], v[206:209], v[34:37]
	v_mfma_f32_16x16x32_bf16 v[22:25], v[178:181], v[214:217], v[22:25]
	v_mfma_f32_16x16x32_bf16 v[18:21], v[186:189], v[214:217], v[18:21]
	v_mfma_f32_16x16x32_bf16 v[6:9], v[178:181], v[222:225], v[6:9]
	v_mfma_f32_16x16x32_bf16 v[2:5], v[186:189], v[222:225], v[2:5]
	s_setprio 0
	s_barrier
	s_add_i32 s82, 0, 0x18000
	v_add_u32_e32 v163, s82, v147
	s_add_i32 s83, 0, 0x1c000
	ds_read_b128 v[152:155], v163
	ds_read_b128 v[156:159], v163 offset:1024
	ds_read_b128 v[166:169], v163 offset:2048
	ds_read_b128 v[170:173], v163 offset:3072
	v_add_u32_e32 v163, s83, v147
	ds_read_b128 v[174:177], v163
	ds_read_b128 v[178:181], v163 offset:1024
	ds_read_b128 v[182:185], v163 offset:2048
	ds_read_b128 v[186:189], v163 offset:3072
	s_add_u32 s70, s70, 0x20000
	s_addc_u32 s71, s71, 0
	s_mov_b32 m0, s38
	v_lshl_add_u64 v[230:231], s[70:71], 0, v[130:131]
	ds_read_b128 v[190:193], v150 offset:32768
	ds_read_b128 v[194:197], v150 offset:33792
	ds_read_b128 v[202:205], v150 offset:34816
	ds_read_b128 v[206:209], v150 offset:35840
	ds_read_b128 v[210:213], v150 offset:36864
	ds_read_b128 v[214:217], v150 offset:37888
	ds_read_b128 v[218:221], v150 offset:38912
	ds_read_b128 v[222:225], v150 offset:39936
	global_load_lds_dwordx4 v[230:231], off
	v_lshl_add_u64 v[230:231], s[70:71], 0, v[134:135]
	s_mov_b32 m0, s39
	s_nop 0
	global_load_lds_dwordx4 v[230:231], off
	s_waitcnt vmcnt(8)
	s_waitcnt lgkmcnt(0)
	s_barrier
	s_setprio 1
	s_waitcnt lgkmcnt(0)
	v_mfma_f32_16x16x32_bf16 v[126:129], v[152:155], v[190:193], v[126:129]
	v_mfma_f32_16x16x32_bf16 v[122:125], v[166:169], v[190:193], v[122:125]
	v_mfma_f32_16x16x32_bf16 v[110:113], v[152:155], v[202:205], v[110:113]
	v_mfma_f32_16x16x32_bf16 v[106:109], v[166:169], v[202:205], v[106:109]
	v_mfma_f32_16x16x32_bf16 v[94:97], v[152:155], v[210:213], v[94:97]
	v_mfma_f32_16x16x32_bf16 v[90:93], v[166:169], v[210:213], v[90:93]
	v_mfma_f32_16x16x32_bf16 v[78:81], v[152:155], v[218:221], v[78:81]
	v_mfma_f32_16x16x32_bf16 v[74:77], v[166:169], v[218:221], v[74:77]
	v_mfma_f32_16x16x32_bf16 v[126:129], v[156:159], v[194:197], v[126:129]
	v_mfma_f32_16x16x32_bf16 v[122:125], v[170:173], v[194:197], v[122:125]
	v_mfma_f32_16x16x32_bf16 v[110:113], v[156:159], v[206:209], v[110:113]
	v_mfma_f32_16x16x32_bf16 v[106:109], v[170:173], v[206:209], v[106:109]
	v_mfma_f32_16x16x32_bf16 v[94:97], v[156:159], v[214:217], v[94:97]
	v_mfma_f32_16x16x32_bf16 v[90:93], v[170:173], v[214:217], v[90:93]
	v_mfma_f32_16x16x32_bf16 v[78:81], v[156:159], v[222:225], v[78:81]
	v_mfma_f32_16x16x32_bf16 v[74:77], v[170:173], v[222:225], v[74:77]
	s_setprio 0
	s_setprio 1
	v_mfma_f32_16x16x32_bf16 v[118:121], v[174:177], v[190:193], v[118:121]
	v_mfma_f32_16x16x32_bf16 v[114:117], v[182:185], v[190:193], v[114:117]
	v_mfma_f32_16x16x32_bf16 v[102:105], v[174:177], v[202:205], v[102:105]
	v_mfma_f32_16x16x32_bf16 v[98:101], v[182:185], v[202:205], v[98:101]
	v_mfma_f32_16x16x32_bf16 v[86:89], v[174:177], v[210:213], v[86:89]
	v_mfma_f32_16x16x32_bf16 v[82:85], v[182:185], v[210:213], v[82:85]
	v_mfma_f32_16x16x32_bf16 v[70:73], v[174:177], v[218:221], v[70:73]
	v_mfma_f32_16x16x32_bf16 v[66:69], v[182:185], v[218:221], v[66:69]
	v_mfma_f32_16x16x32_bf16 v[118:121], v[178:181], v[194:197], v[118:121]
	v_mfma_f32_16x16x32_bf16 v[114:117], v[186:189], v[194:197], v[114:117]
	v_mfma_f32_16x16x32_bf16 v[102:105], v[178:181], v[206:209], v[102:105]
	v_mfma_f32_16x16x32_bf16 v[98:101], v[186:189], v[206:209], v[98:101]
	v_mfma_f32_16x16x32_bf16 v[86:89], v[178:181], v[214:217], v[86:89]
	v_mfma_f32_16x16x32_bf16 v[82:85], v[186:189], v[214:217], v[82:85]
	v_mfma_f32_16x16x32_bf16 v[70:73], v[178:181], v[222:225], v[70:73]
	v_mfma_f32_16x16x32_bf16 v[66:69], v[186:189], v[222:225], v[66:69]
	s_setprio 0
	s_barrier
	s_add_i32 s70, s82, s2
	v_lshl_add_u64 v[160:161], v[160:161], 0, s[10:11]
	s_mov_b32 m0, s70
	ds_read_b128 v[190:193], v150 offset:49152
	ds_read_b128 v[194:197], v150 offset:50176
	ds_read_b128 v[202:205], v150 offset:51200
	ds_read_b128 v[206:209], v150 offset:52224
	ds_read_b128 v[210:213], v150 offset:53248
	ds_read_b128 v[214:217], v150 offset:54272
	ds_read_b128 v[218:221], v150 offset:55296
	ds_read_b128 v[222:225], v150 offset:56320
	global_load_lds_dwordx4 v[160:161], off
	s_add_i32 m0, s70, 0x2000
	s_add_u32 s54, s54, 0x20080
	v_lshl_add_u64 v[160:161], v[198:199], 0, s[10:11]
	s_addc_u32 s55, s55, 0
	s_add_i32 s70, s83, s2
	global_load_lds_dwordx4 v[160:161], off
	v_lshl_add_u64 v[160:161], s[54:55], 0, v[132:133]
	s_mov_b32 m0, s70
	s_nop 0
	global_load_lds_dwordx4 v[160:161], off
	v_lshl_add_u64 v[160:161], s[54:55], 0, v[136:137]
	s_add_i32 m0, s70, 0x2000
	s_nop 0
	global_load_lds_dwordx4 v[160:161], off
	v_lshl_add_u64 v[160:161], v[226:227], 0, s[10:11]
	s_mov_b32 m0, s57
	s_nop 0
	global_load_lds_dwordx4 v[160:161], off
	v_lshl_add_u64 v[160:161], v[228:229], 0, s[10:11]
	s_mov_b32 m0, s67
	s_nop 0
	global_load_lds_dwordx4 v[160:161], off
	s_waitcnt vmcnt(8)
	s_waitcnt lgkmcnt(0)
	s_barrier
	s_setprio 1
	s_waitcnt lgkmcnt(0)
	v_mfma_f32_16x16x32_bf16 v[62:65], v[152:155], v[190:193], v[62:65]
	v_mfma_f32_16x16x32_bf16 v[58:61], v[166:169], v[190:193], v[58:61]
	v_mfma_f32_16x16x32_bf16 v[46:49], v[152:155], v[202:205], v[46:49]
	v_mfma_f32_16x16x32_bf16 v[42:45], v[166:169], v[202:205], v[42:45]
	v_mfma_f32_16x16x32_bf16 v[30:33], v[152:155], v[210:213], v[30:33]
	v_mfma_f32_16x16x32_bf16 v[26:29], v[166:169], v[210:213], v[26:29]
	v_mfma_f32_16x16x32_bf16 v[14:17], v[152:155], v[218:221], v[14:17]
	v_mfma_f32_16x16x32_bf16 v[10:13], v[166:169], v[218:221], v[10:13]
	v_mfma_f32_16x16x32_bf16 v[62:65], v[156:159], v[194:197], v[62:65]
	v_mfma_f32_16x16x32_bf16 v[58:61], v[170:173], v[194:197], v[58:61]
	v_mfma_f32_16x16x32_bf16 v[46:49], v[156:159], v[206:209], v[46:49]
	v_mfma_f32_16x16x32_bf16 v[42:45], v[170:173], v[206:209], v[42:45]
	v_mfma_f32_16x16x32_bf16 v[30:33], v[156:159], v[214:217], v[30:33]
	v_mfma_f32_16x16x32_bf16 v[26:29], v[170:173], v[214:217], v[26:29]
	v_mfma_f32_16x16x32_bf16 v[14:17], v[156:159], v[222:225], v[14:17]
	v_mfma_f32_16x16x32_bf16 v[10:13], v[170:173], v[222:225], v[10:13]
	s_setprio 0
	s_setprio 1
	v_mfma_f32_16x16x32_bf16 v[54:57], v[174:177], v[190:193], v[54:57]
	v_mfma_f32_16x16x32_bf16 v[50:53], v[182:185], v[190:193], v[50:53]
	v_mfma_f32_16x16x32_bf16 v[38:41], v[174:177], v[202:205], v[38:41]
	v_mfma_f32_16x16x32_bf16 v[34:37], v[182:185], v[202:205], v[34:37]
	v_mfma_f32_16x16x32_bf16 v[22:25], v[174:177], v[210:213], v[22:25]
	v_mfma_f32_16x16x32_bf16 v[18:21], v[182:185], v[210:213], v[18:21]
	v_mfma_f32_16x16x32_bf16 v[6:9], v[174:177], v[218:221], v[6:9]
	v_mfma_f32_16x16x32_bf16 v[2:5], v[182:185], v[218:221], v[2:5]
	v_mfma_f32_16x16x32_bf16 v[54:57], v[178:181], v[194:197], v[54:57]
	v_mfma_f32_16x16x32_bf16 v[50:53], v[186:189], v[194:197], v[50:53]
	v_mfma_f32_16x16x32_bf16 v[38:41], v[178:181], v[206:209], v[38:41]
	v_mfma_f32_16x16x32_bf16 v[34:37], v[186:189], v[206:209], v[34:37]
	v_mfma_f32_16x16x32_bf16 v[22:25], v[178:181], v[214:217], v[22:25]
	v_mfma_f32_16x16x32_bf16 v[18:21], v[186:189], v[214:217], v[18:21]
	v_mfma_f32_16x16x32_bf16 v[6:9], v[178:181], v[222:225], v[6:9]
	v_mfma_f32_16x16x32_bf16 v[2:5], v[186:189], v[222:225], v[2:5]
	s_setprio 0
	s_barrier
	s_add_i32 s81, s81, 2
	s_add_u32 s68, s68, 0x100
	s_addc_u32 s69, s69, 0
	s_add_u32 s79, s79, 0x100
	s_addc_u32 s80, s80, 0
	.p2align	6

.LBB0_1217:
	s_xor_b64 s[82:83], s[6:7], -1
	s_and_b64 s[6:7], s[6:7], exec
	s_cselect_b32 s50, s8, s9
	s_lshl_b32 s6, s50, 8
	s_add_i32 s24, s6, s29
	s_load_dwordx2 s[86:87], s[0:1], 0x68
	s_waitcnt lgkmcnt(0)
	s_barrier
	s_mov_b32 s6, m0
	s_mov_b32 m0, s21
	s_nop 0
	global_load_lds_dwordx4 v[176:177], off
	s_mov_b32 m0, s6
	s_add_u32 s84, s78, s24
	s_mov_b32 s6, m0
	s_mov_b32 m0, s27
	s_nop 0
	global_load_lds_dwordx4 v[178:179], off
	s_mov_b32 m0, s6
	s_addc_u32 s85, s79, 0
	s_mov_b32 s6, m0
	s_mov_b32 m0, s37
	s_nop 0
	global_load_lds_dwordx4 v[180:181], off
	s_mov_b32 m0, s6
	s_mul_i32 s51, s85, 0x1800
	s_mov_b32 s6, m0
	s_mov_b32 m0, s39
	s_nop 0
	global_load_lds_dwordx4 v[182:183], off
	s_mov_b32 m0, s6
	s_lshl_b32 s50, s50, 2
	s_mov_b32 s6, m0
	s_mov_b32 m0, s89
	s_nop 0
	global_load_lds_dwordx4 v[184:185], off
	s_mov_b32 m0, s6
	s_mov_b32 s55, 0
	s_mov_b32 s6, m0
	s_mov_b32 m0, s91
	s_nop 0
	global_load_lds_dwordx4 v[186:187], off
	s_mov_b32 m0, s6
	s_or_b32 s56, s50, 3
	s_mov_b32 s6, m0
	s_mov_b32 m0, s96
	s_nop 0
	global_load_lds_dwordx4 v[188:189], off
	s_mov_b32 m0, s6
	s_or_b32 s57, s24, 31
	s_mov_b32 s6, m0
	s_mov_b32 m0, s97
	s_nop 0
	global_load_lds_dwordx4 v[190:191], off
	s_mov_b32 m0, s6
	v_or_b32_e32 v213, s24, v203
	s_mov_b32 s6, m0
	s_mov_b32 m0, s14
	s_nop 0
	global_load_lds_dwordx4 v[192:193], off
	s_mov_b32 m0, s6
	s_mov_b32 s93, 0
	s_mov_b32 s6, m0
	s_mov_b32 m0, s15
	s_nop 0
	global_load_lds_dwordx4 v[194:195], off
	s_mov_b32 m0, s6
	s_nop 0
	s_mov_b32 s6, m0
	s_mov_b32 m0, s64
	s_nop 0
	global_load_lds_dwordx4 v[196:197], off
	s_mov_b32 m0, s6
	s_nop 0
	v_mad_u64_u32 v[4:5], s[6:7], s84, v211, v[170:171]
	s_mov_b32 s6, m0
	s_mov_b32 m0, s65
	s_nop 0
	global_load_lds_dwordx4 v[198:199], off
	s_mov_b32 m0, s6
	v_add_u32_e32 v5, s51, v5
	global_load_dwordx4 v[20:23], v[4:5], off
	global_load_dwordx4 v[24:27], v[4:5], off offset:32
	global_load_dwordx4 v[28:31], v[4:5], off offset:64
	global_load_dwordx4 v[36:39], v[4:5], off offset:96
	global_load_dwordx4 v[46:49], v[4:5], off offset:128
	global_load_dwordx4 v[58:61], v[4:5], off offset:160
	global_load_dwordx4 v[62:65], v[4:5], off offset:192
	global_load_dwordx4 v[74:77], v[4:5], off offset:224
	global_load_dwordx4 v[16:19], v[4:5], off offset:256
	global_load_dwordx4 v[12:15], v[4:5], off offset:288
	global_load_dwordx4 v[8:11], v[4:5], off offset:320
	s_nop 0
	global_load_dwordx4 v[4:7], v[4:5], off offset:352
	s_mov_b32 s6, 0xf800000
	s_waitcnt vmcnt(11)
	v_and_b32_e32 v99, 0xffff0000, v21
	v_and_b32_e32 v98, 0xffff0000, v20
	v_and_b32_e32 v85, 0xffff0000, v23
	v_and_b32_e32 v84, 0xffff0000, v22
	s_waitcnt vmcnt(10)
	v_and_b32_e32 v69, 0xffff0000, v25
	v_and_b32_e32 v68, 0xffff0000, v24
	v_and_b32_e32 v73, 0xffff0000, v27
	v_and_b32_e32 v72, 0xffff0000, v26
	v_lshlrev_b32_e32 v97, 16, v21
	v_lshlrev_b32_e32 v96, 16, v20
	v_lshlrev_b32_e32 v83, 16, v23
	v_lshlrev_b32_e32 v82, 16, v22
	v_lshlrev_b32_e32 v67, 16, v25
	v_lshlrev_b32_e32 v66, 16, v24
	v_lshlrev_b32_e32 v71, 16, v27
	v_lshlrev_b32_e32 v70, 16, v26
	s_waitcnt vmcnt(9)
	v_lshlrev_b32_e32 v34, 16, v28
	v_and_b32_e32 v35, 0xffff0000, v28
	v_lshlrev_b32_e32 v40, 16, v29
	v_and_b32_e32 v41, 0xffff0000, v29
	v_pk_mul_f32 v[20:21], v[98:99], v[98:99]
	v_pk_mul_f32 v[22:23], v[84:85], v[84:85]
	v_pk_mul_f32 v[26:27], v[68:69], v[68:69]
	v_pk_mul_f32 v[28:29], v[72:73], v[72:73]
	s_waitcnt vmcnt(8)
	v_lshlrev_b32_e32 v54, 16, v36
	v_and_b32_e32 v55, 0xffff0000, v36
	v_lshlrev_b32_e32 v56, 16, v37
	v_and_b32_e32 v57, 0xffff0000, v37
	v_pk_fma_f32 v[20:21], v[96:97], v[96:97], v[20:21]
	v_pk_fma_f32 v[22:23], v[82:83], v[82:83], v[22:23]
	v_pk_fma_f32 v[26:27], v[66:67], v[66:67], v[26:27]
	v_pk_fma_f32 v[28:29], v[70:71], v[70:71], v[28:29]
	v_lshlrev_b32_e32 v50, 16, v31
	v_and_b32_e32 v51, 0xffff0000, v31
	v_mul_f32_e32 v3, v54, v54
	v_mul_f32_e32 v31, v55, v55
	v_mul_f32_e32 v32, v56, v56
	v_mul_f32_e32 v33, v57, v57
	v_pk_add_f32 v[20:21], v[20:21], v[20:21] op_sel:[0,1] op_sel_hi:[1,0]
	v_pk_add_f32 v[22:23], v[22:23], v[22:23] op_sel:[0,1] op_sel_hi:[1,0]
	v_pk_add_f32 v[26:27], v[26:27], v[26:27] op_sel:[0,1] op_sel_hi:[1,0]
	v_pk_add_f32 v[28:29], v[28:29], v[28:29] op_sel:[0,1] op_sel_hi:[1,0]
	v_mov_b32_e32 v21, v3
	v_mov_b32_e32 v23, v31
	v_mov_b32_e32 v27, v32
	v_mov_b32_e32 v29, v33
	v_lshlrev_b32_e32 v44, 16, v30
	v_and_b32_e32 v45, 0xffff0000, v30
	v_lshlrev_b32_e32 v52, 16, v38
	v_and_b32_e32 v53, 0xffff0000, v38
	v_mul_f32_e32 v30, v35, v35
	v_pk_add_f32 v[20:21], v[20:21], v[22:23]
	v_pk_add_f32 v[22:23], v[26:27], v[28:29]
	v_mul_f32_e32 v26, v41, v41
	v_mul_f32_e32 v36, v52, v52
	v_mul_f32_e32 v37, v53, v53
	v_pk_add_f32 v[20:21], v[20:21], v[22:23]
	v_pk_fma_f32 v[22:23], v[34:35], v[34:35], v[30:31] op_sel_hi:[1,1,0]
	v_pk_fma_f32 v[26:27], v[40:41], v[40:41], v[26:27] op_sel_hi:[1,1,0]
	v_mov_b32_e32 v23, v36
	v_mov_b32_e32 v27, v37
	v_lshlrev_b32_e32 v24, 16, v39
	v_and_b32_e32 v25, 0xffff0000, v39
	v_pk_add_f32 v[22:23], v[22:23], v[26:27]
	v_mul_f32_e32 v26, v45, v45
	v_mul_f32_e32 v28, v51, v51
	v_mul_f32_e32 v38, v24, v24
	v_mul_f32_e32 v39, v25, v25
	v_pk_fma_f32 v[26:27], v[44:45], v[44:45], v[26:27] op_sel_hi:[1,1,0]
	v_pk_fma_f32 v[28:29], v[50:51], v[50:51], v[28:29] op_sel_hi:[1,1,0]
	v_mov_b32_e32 v27, v38
	v_mov_b32_e32 v29, v39
	v_pk_add_f32 v[26:27], v[26:27], v[28:29]
	s_waitcnt vmcnt(7)
	v_and_b32_e32 v81, 0xffff0000, v48
	v_pk_add_f32 v[22:23], v[22:23], v[26:27]
	v_and_b32_e32 v80, 0xffff0000, v46
	v_and_b32_e32 v91, 0xffff0000, v49
	v_and_b32_e32 v90, 0xffff0000, v47
	v_pk_add_f32 v[36:37], v[20:21], v[22:23]
	v_lshlrev_b32_e32 v79, 16, v48
	v_lshlrev_b32_e32 v78, 16, v46
	v_lshlrev_b32_e32 v89, 16, v49
	v_lshlrev_b32_e32 v88, 16, v47
	v_pk_mul_f32 v[20:21], v[80:81], v[80:81]
	v_pk_mul_f32 v[22:23], v[90:91], v[90:91]
	v_pk_fma_f32 v[20:21], v[78:79], v[78:79], v[20:21]
	v_pk_fma_f32 v[22:23], v[88:89], v[88:89], v[22:23]
	s_waitcnt vmcnt(6)
	v_and_b32_e32 v27, 0xffff0000, v59
	v_pk_add_f32 v[38:39], v[20:21], v[22:23]
	v_and_b32_e32 v26, 0xffff0000, v58
	v_lshlrev_b32_e32 v31, 16, v61
	v_lshlrev_b32_e32 v30, 16, v60
	v_and_b32_e32 v33, 0xffff0000, v61
	v_and_b32_e32 v32, 0xffff0000, v60
	s_waitcnt vmcnt(4)
	v_lshlrev_b32_e32 v60, 16, v74
	v_and_b32_e32 v61, 0xffff0000, v74
	v_lshlrev_b32_e32 v29, 16, v59
	v_lshlrev_b32_e32 v28, 16, v58
	v_pk_mul_f32 v[20:21], v[26:27], v[26:27]
	v_lshlrev_b32_e32 v42, 16, v62
	v_and_b32_e32 v43, 0xffff0000, v62
	v_mul_f32_e32 v3, v60, v60
	v_mul_f32_e32 v62, v61, v61
	v_pk_add_f32 v[36:37], v[36:37], v[36:37] op_sel:[0,1] op_sel_hi:[1,0]
	v_pk_add_f32 v[38:39], v[38:39], v[38:39] op_sel:[0,1] op_sel_hi:[1,0]
	v_pk_fma_f32 v[86:87], v[28:29], v[28:29], v[20:21]
	v_pk_mul_f32 v[20:21], v[32:33], v[32:33]
	v_lshlrev_b32_e32 v46, 16, v64
	v_and_b32_e32 v47, 0xffff0000, v64
	v_lshlrev_b32_e32 v64, 16, v75
	v_mov_b32_e32 v37, v3
	v_mov_b32_e32 v39, v62
	v_pk_fma_f32 v[92:93], v[30:31], v[30:31], v[20:21]
	v_lshlrev_b32_e32 v48, 16, v63
	v_and_b32_e32 v49, 0xffff0000, v63
	v_lshlrev_b32_e32 v58, 16, v65
	v_and_b32_e32 v59, 0xffff0000, v65
	v_and_b32_e32 v65, 0xffff0000, v75
	v_mul_f32_e32 v63, v64, v64
	v_pk_add_f32 v[36:37], v[36:37], v[38:39]
	v_pk_add_f32 v[38:39], v[86:87], v[86:87] op_sel:[0,1] op_sel_hi:[1,0]
	v_mul_f32_e32 v74, v65, v65
	v_mov_b32_e32 v39, v63
	v_pk_add_f32 v[62:63], v[92:93], v[92:93] op_sel:[0,1] op_sel_hi:[1,0]
	v_lshlrev_b32_e32 v20, 16, v76
	v_mov_b32_e32 v63, v74
	v_pk_add_f32 v[38:39], v[38:39], v[62:63]
	v_and_b32_e32 v21, 0xffff0000, v76
	v_pk_add_f32 v[36:37], v[36:37], v[38:39]
	v_mul_f32_e32 v38, v43, v43
	v_mul_f32_e32 v62, v49, v49
	v_mul_f32_e32 v75, v20, v20
	v_mul_f32_e32 v76, v21, v21
	v_pk_fma_f32 v[38:39], v[42:43], v[42:43], v[38:39] op_sel_hi:[1,1,0]
	v_pk_fma_f32 v[62:63], v[48:49], v[48:49], v[62:63] op_sel_hi:[1,1,0]
	v_mov_b32_e32 v39, v75
	v_mov_b32_e32 v63, v76
	v_lshlrev_b32_e32 v22, 16, v77
	v_and_b32_e32 v23, 0xffff0000, v77
	v_pk_add_f32 v[38:39], v[38:39], v[62:63]
	v_mul_f32_e32 v62, v47, v47
	v_mul_f32_e32 v74, v59, v59
	v_mul_f32_e32 v77, v22, v22
	v_mul_f32_e32 v94, v23, v23
	v_pk_fma_f32 v[62:63], v[46:47], v[46:47], v[62:63] op_sel_hi:[1,1,0]
	v_pk_fma_f32 v[74:75], v[58:59], v[58:59], v[74:75] op_sel_hi:[1,1,0]
	v_mov_b32_e32 v63, v77
	v_mov_b32_e32 v75, v94
	v_pk_add_f32 v[62:63], v[62:63], v[74:75]
	s_waitcnt vmcnt(0)
	v_lshlrev_b32_e32 v92, 16, v4
	v_pk_add_f32 v[38:39], v[38:39], v[62:63]
	v_lshlrev_b32_e32 v63, 16, v19
	v_pk_add_f32 v[100:101], v[36:37], v[38:39]
	v_lshlrev_b32_e32 v37, 16, v18
	v_and_b32_e32 v39, 0xffff0000, v18
	v_and_b32_e32 v38, 0xffff0000, v16
	v_and_b32_e32 v19, 0xffff0000, v19
	v_and_b32_e32 v18, 0xffff0000, v17
	v_lshlrev_b32_e32 v36, 16, v16
	v_lshlrev_b32_e32 v62, 16, v17
	v_pk_mul_f32 v[16:17], v[38:39], v[38:39]
	v_pk_mul_f32 v[74:75], v[18:19], v[18:19]
	v_pk_fma_f32 v[16:17], v[36:37], v[36:37], v[16:17]
	v_pk_fma_f32 v[74:75], v[62:63], v[62:63], v[74:75]
	v_and_b32_e32 v93, 0xffff0000, v4
	v_pk_add_f32 v[102:103], v[16:17], v[74:75]
	v_lshlrev_b32_e32 v17, 16, v13
	v_lshlrev_b32_e32 v16, 16, v12
	v_and_b32_e32 v13, 0xffff0000, v13
	v_and_b32_e32 v12, 0xffff0000, v12
	v_pk_mul_f32 v[74:75], v[12:13], v[12:13]
	v_lshlrev_b32_e32 v94, 16, v5
	v_pk_fma_f32 v[110:111], v[16:17], v[16:17], v[74:75]
	v_lshlrev_b32_e32 v75, 16, v15
	v_lshlrev_b32_e32 v74, 16, v14
	v_and_b32_e32 v15, 0xffff0000, v15
	v_and_b32_e32 v14, 0xffff0000, v14
	v_pk_mul_f32 v[76:77], v[14:15], v[14:15]
	v_and_b32_e32 v95, 0xffff0000, v5
	v_pk_fma_f32 v[112:113], v[74:75], v[74:75], v[76:77]
	v_mul_f32_e32 v3, v92, v92
	v_mul_f32_e32 v104, v93, v93
	v_mul_f32_e32 v116, v94, v94
	v_mul_f32_e32 v117, v95, v95
	v_pk_add_f32 v[100:101], v[100:101], v[100:101] op_sel:[0,1] op_sel_hi:[1,0]
	v_pk_add_f32 v[114:115], v[102:103], v[102:103] op_sel:[0,1] op_sel_hi:[1,0]
	v_pk_add_f32 v[110:111], v[110:111], v[110:111] op_sel:[0,1] op_sel_hi:[1,0]
	v_pk_add_f32 v[112:113], v[112:113], v[112:113] op_sel:[0,1] op_sel_hi:[1,0]
	v_mov_b32_e32 v101, v3
	v_mov_b32_e32 v115, v104
	v_mov_b32_e32 v111, v116
	v_mov_b32_e32 v113, v117
	v_lshlrev_b32_e32 v76, 16, v8
	v_and_b32_e32 v77, 0xffff0000, v8
	v_lshlrev_b32_e32 v8, 16, v9
	v_and_b32_e32 v9, 0xffff0000, v9
	v_lshlrev_b32_e32 v3, 2, v209
	v_pk_add_f32 v[100:101], v[100:101], v[114:115]
	v_pk_add_f32 v[110:111], v[110:111], v[112:113]
	v_lshlrev_b32_e32 v4, 16, v6
	v_and_b32_e32 v5, 0xffff0000, v6
	global_load_dwordx4 v[102:105], v3, s[86:87] offset:16
	global_load_dwordx4 v[106:109], v3, s[86:87]
	v_pk_add_f32 v[100:101], v[100:101], v[110:111]
	v_mul_f32_e32 v110, v77, v77
	v_mul_f32_e32 v112, v9, v9
	v_mul_f32_e32 v118, v4, v4
	v_mul_f32_e32 v119, v5, v5
	v_pk_fma_f32 v[110:111], v[76:77], v[76:77], v[110:111] op_sel_hi:[1,1,0]
	v_pk_fma_f32 v[112:113], v[8:9], v[8:9], v[112:113] op_sel_hi:[1,1,0]
	v_and_b32_e32 v87, 0xffff0000, v10
	v_mov_b32_e32 v111, v118
	v_mov_b32_e32 v113, v119
	v_lshlrev_b32_e32 v86, 16, v10
	v_pk_add_f32 v[118:119], v[110:111], v[112:113]
	v_mul_f32_e32 v110, v87, v87
	v_pk_fma_f32 v[120:121], v[86:87], v[86:87], v[110:111] op_sel_hi:[1,1,0]
	global_load_dwordx4 v[110:113], v3, s[86:87] offset:80
	global_load_dwordx4 v[114:117], v3, s[86:87] offset:64
	v_lshlrev_b32_e32 v6, 16, v7
	v_lshlrev_b32_e32 v10, 16, v11
	v_and_b32_e32 v11, 0xffff0000, v11
	v_mul_f32_e32 v122, v6, v6
	v_and_b32_e32 v7, 0xffff0000, v7
	v_mov_b32_e32 v121, v122
	v_mul_f32_e32 v122, v11, v11
	v_mul_f32_e32 v124, v7, v7
	v_pk_fma_f32 v[122:123], v[10:11], v[10:11], v[122:123] op_sel_hi:[1,1,0]
	v_mov_b32_e32 v218, v96
	v_mov_b32_e32 v123, v124
	v_pk_add_f32 v[120:121], v[120:121], v[122:123]
	v_mov_b32_e32 v219, v98
	v_pk_add_f32 v[118:119], v[118:119], v[120:121]
	v_mov_b32_e32 v98, v97
	v_pk_add_f32 v[100:101], v[100:101], v[118:119]
	global_load_dwordx4 v[118:121], v3, s[86:87] offset:144
	global_load_dwordx4 v[122:125], v3, s[86:87] offset:128
	v_pk_add_f32 v[100:101], v[100:101], v[100:101] op_sel:[0,1] op_sel_hi:[1,0]
	global_load_dwordx4 v[126:129], v3, s[86:87] offset:192
	global_load_dwordx4 v[130:133], v3, s[86:87] offset:208
	v_mov_b32_e32 v101, v100
	s_nop 1
	v_permlane32_swap_b32_e32 v100, v101
	v_add_f32_e32 v100, v100, v101
	v_fmamk_f32 v100, v100, 0x3baaaaab, v163
	v_mul_f32_e32 v101, 0x4f800000, v100
	v_cmp_gt_f32_e32 vcc, s6, v100
	s_nop 1
	v_cndmask_b32_e32 v100, v100, v101, vcc
	v_sqrt_f32_e32 v101, v100
	s_nop 0
	v_add_u32_e32 v134, -1, v101
	v_fma_f32 v135, -v134, v101, v100
	v_cmp_ge_f32_e64 s[6:7], 0, v135
	v_add_u32_e32 v135, 1, v101
	s_nop 0
	v_cndmask_b32_e64 v134, v101, v134, s[6:7]
	v_fma_f32 v101, -v135, v101, v100
	v_cmp_lt_f32_e64 s[6:7], 0, v101
	s_nop 1
	v_cndmask_b32_e64 v101, v134, v135, s[6:7]
	v_mul_f32_e32 v134, 0x37800000, v101
	v_cndmask_b32_e32 v101, v101, v134, vcc
	v_cmp_class_f32_e32 vcc, v100, v210
	global_load_dwordx4 v[134:137], v3, s[86:87] offset:272
	global_load_dwordx4 v[138:141], v3, s[86:87] offset:256
	v_cndmask_b32_e32 v100, v101, v100, vcc
	v_div_scale_f32 v101, s[6:7], v100, v100, 1.0
	v_rcp_f32_e32 v142, v101
	s_lshl_b64 s[6:7], s[24:25], 8
	v_lshl_add_u64 v[234:235], v[156:157], 0, s[6:7]
	v_fma_f32 v143, -v101, v142, 1.0
	v_fmac_f32_e32 v142, v143, v142
	v_div_scale_f32 v143, vcc, 1.0, v100, 1.0
	v_mul_f32_e32 v144, v143, v142
	v_fma_f32 v145, -v101, v144, v143
	v_fmac_f32_e32 v144, v145, v142
	v_fma_f32 v101, -v101, v144, v143
	v_div_fmas_f32 v101, v101, v142, v144
	v_div_fixup_f32 v100, v101, v100, 1.0
	global_load_dwordx4 v[142:145], v3, s[86:87] offset:336
	global_load_dwordx4 v[214:217], v3, s[86:87] offset:320
	v_mul_f32_e32 v100, 0x3dd53b94, v100
	v_pk_mul_f32 v[218:219], v[100:101], v[218:219] op_sel_hi:[0,1]
	v_pk_mul_f32 v[96:97], v[100:101], v[98:99] op_sel_hi:[0,1]
	s_waitcnt vmcnt(10)
	v_pk_mul_f32 v[98:99], v[106:107], v[218:219]
	v_mov_b32_e32 v106, v82
	v_mov_b32_e32 v107, v84
	v_pk_mul_f32 v[106:107], v[100:101], v[106:107] op_sel_hi:[0,1]
	global_load_dwordx4 v[218:221], v3, s[86:87] offset:400
	global_load_dwordx4 v[222:225], v3, s[86:87] offset:384
	v_mov_b32_e32 v84, v83
	v_pk_mul_f32 v[82:83], v[100:101], v[84:85] op_sel_hi:[0,1]
	v_pk_mul_f32 v[84:85], v[102:103], v[106:107]
	v_mov_b32_e32 v106, v66
	v_mov_b32_e32 v107, v68
	v_pk_mul_f32 v[82:83], v[104:105], v[82:83]
	global_load_dwordx4 v[102:105], v3, s[86:87] offset:464
	global_load_dwordx4 v[226:229], v3, s[86:87] offset:448
	v_pk_mul_f32 v[106:107], v[100:101], v[106:107] op_sel_hi:[0,1]
	v_mov_b32_e32 v68, v67
	v_pk_mul_f32 v[66:67], v[100:101], v[68:69] op_sel_hi:[0,1]
	s_waitcnt vmcnt(12)
	v_pk_mul_f32 v[68:69], v[114:115], v[106:107]
	v_mov_b32_e32 v106, v70
	v_mov_b32_e32 v107, v72
	v_mov_b32_e32 v72, v71
	v_pk_mul_f32 v[106:107], v[100:101], v[106:107] op_sel_hi:[0,1]
	v_pk_mul_f32 v[70:71], v[100:101], v[72:73] op_sel_hi:[0,1]
	v_pk_mul_f32 v[66:67], v[116:117], v[66:67]
	v_pk_mul_f32 v[70:71], v[112:113], v[70:71]
	v_pk_mul_f32 v[72:73], v[110:111], v[106:107]
	global_load_dwordx4 v[110:113], v3, s[86:87] offset:528
	global_load_dwordx4 v[114:117], v3, s[86:87] offset:512
	v_pk_mul_f32 v[106:107], v[100:101], v[34:35] op_sel_hi:[0,1]
	v_pk_mul_f32 v[34:35], v[100:101], v[40:41] op_sel_hi:[0,1]
	v_pk_mul_f32 v[40:41], v[100:101], v[44:45] op_sel_hi:[0,1]
	v_pk_mul_f32 v[44:45], v[100:101], v[50:51] op_sel_hi:[0,1]
	v_pk_mul_f32 v[50:51], v[100:101], v[54:55] op_sel_hi:[0,1]
	v_mov_b32_e32 v54, v78
	v_mov_b32_e32 v55, v80
	v_pk_mul_f32 v[96:97], v[108:109], v[96:97]
	s_waitcnt vmcnt(13)
	v_pk_mul_f32 v[108:109], v[118:119], v[40:41]
	v_pk_mul_f32 v[40:41], v[100:101], v[56:57] op_sel_hi:[0,1]
	v_pk_mul_f32 v[56:57], v[100:101], v[54:55] op_sel_hi:[0,1]
	v_mov_b32_e32 v80, v79
	v_mov_b32_e32 v54, v88
	v_mov_b32_e32 v55, v90
	s_waitcnt vmcnt(12)
	v_pk_mul_f32 v[34:35], v[124:125], v[34:35]
	v_pk_mul_f32 v[106:107], v[122:123], v[106:107]
	v_pk_mul_f32 v[44:45], v[120:121], v[44:45]
	global_load_dwordx4 v[118:121], v3, s[86:87] offset:592
	global_load_dwordx4 v[122:125], v3, s[86:87] offset:576
	v_pk_mul_f32 v[54:55], v[100:101], v[54:55] op_sel_hi:[0,1]
	v_mov_b32_e32 v90, v89
	v_pk_mul_f32 v[52:53], v[100:101], v[52:53] op_sel_hi:[0,1]
	v_pk_mul_f32 v[24:25], v[100:101], v[24:25] op_sel_hi:[0,1]
	s_waitcnt vmcnt(13)
	v_pk_mul_f32 v[40:41], v[128:129], v[40:41]
	v_pk_mul_f32 v[50:51], v[126:127], v[50:51]
	s_waitcnt vmcnt(12)
	v_pk_mul_f32 v[24:25], v[132:133], v[24:25]
	v_pk_mul_f32 v[52:53], v[130:131], v[52:53]
	global_load_dwordx4 v[126:129], v3, s[86:87] offset:656
	global_load_dwordx4 v[130:133], v3, s[86:87] offset:640
	v_pk_mul_f32 v[48:49], v[100:101], v[48:49] op_sel_hi:[0,1]
	v_pk_mul_f32 v[46:47], v[100:101], v[46:47] op_sel_hi:[0,1]
	v_pk_mul_f32 v[42:43], v[100:101], v[42:43] op_sel_hi:[0,1]
	v_pk_mul_f32 v[4:5], v[100:101], v[4:5] op_sel_hi:[0,1]
	v_pk_mul_f32 v[8:9], v[100:101], v[8:9] op_sel_hi:[0,1]
	v_pk_mul_f32 v[6:7], v[100:101], v[6:7] op_sel_hi:[0,1]
	s_waitcnt vmcnt(12)
	v_pk_mul_f32 v[56:57], v[138:139], v[56:57]
	v_pk_mul_f32 v[138:139], v[100:101], v[80:81] op_sel_hi:[0,1]
	v_pk_mul_f32 v[232:233], v[134:135], v[138:139]
	v_mov_b32_e32 v139, v26
	v_mov_b32_e32 v26, v29
	v_pk_mul_f32 v[54:55], v[140:141], v[54:55]
	v_pk_mul_f32 v[140:141], v[100:101], v[90:91] op_sel_hi:[0,1]
	v_pk_mul_f32 v[26:27], v[100:101], v[26:27] op_sel_hi:[0,1]
	global_load_dwordx4 v[78:81], v3, s[86:87] offset:720
	global_load_dwordx4 v[88:91], v3, s[86:87] offset:704
	v_pk_mul_f32 v[230:231], v[136:137], v[140:141]
	v_mov_b32_e32 v138, v28
	global_load_dwordx4 v[134:137], v[234:235], off
	v_pk_mul_f32 v[236:237], v[100:101], v[138:139] op_sel_hi:[0,1]
	global_load_dwordx4 v[138:141], v[234:235], off offset:16
	v_pk_mul_f32 v[10:11], v[100:101], v[10:11] op_sel_hi:[0,1]
	v_cvt_pk_bf16_f32 v106, v106, v107
	v_cvt_pk_bf16_f32 v107, v34, v35
	v_cvt_pk_bf16_f32 v108, v108, v109
	s_waitcnt vmcnt(14)
	v_pk_mul_f32 v[216:217], v[26:27], v[216:217]
	v_mov_b32_e32 v26, v30
	v_mov_b32_e32 v27, v32
	v_mov_b32_e32 v32, v31
	v_pk_mul_f32 v[26:27], v[100:101], v[26:27] op_sel_hi:[0,1]
	v_pk_mul_f32 v[28:29], v[100:101], v[32:33] op_sel_hi:[0,1]
	v_pk_mul_f32 v[144:145], v[28:29], v[144:145]
	v_pk_mul_f32 v[142:143], v[26:27], v[142:143]
	global_load_dwordx4 v[26:29], v[234:235], off offset:32
	global_load_dwordx4 v[30:33], v[234:235], off offset:48
	s_waitcnt vmcnt(14)
	v_pk_mul_f32 v[224:225], v[48:49], v[224:225]
	v_pk_mul_f32 v[48:49], v[100:101], v[58:59] op_sel_hi:[0,1]
	v_pk_mul_f32 v[220:221], v[48:49], v[220:221]
	v_pk_mul_f32 v[218:219], v[46:47], v[218:219]
	v_pk_mul_f32 v[46:47], v[100:101], v[60:61] op_sel_hi:[0,1]
	v_pk_mul_f32 v[48:49], v[100:101], v[64:65] op_sel_hi:[0,1]
	v_pk_mul_f32 v[42:43], v[42:43], v[222:223]
	s_waitcnt vmcnt(12)
	v_pk_mul_f32 v[222:223], v[48:49], v[228:229]
	v_pk_mul_f32 v[226:227], v[46:47], v[226:227]
	global_load_dwordx4 v[46:49], v[234:235], off offset:128
	v_pk_mul_f32 v[58:59], v[100:101], v[20:21] op_sel_hi:[0,1]
	v_pk_mul_f32 v[60:61], v[100:101], v[22:23] op_sel_hi:[0,1]
	global_load_dwordx4 v[20:23], v[234:235], off offset:144
	v_pk_mul_f32 v[214:215], v[236:237], v[214:215]
	v_pk_mul_f32 v[228:229], v[60:61], v[104:105]
	v_pk_mul_f32 v[236:237], v[58:59], v[102:103]
	v_mov_b32_e32 v58, v62
	v_mov_b32_e32 v59, v18
	v_mov_b32_e32 v60, v36
	v_mov_b32_e32 v61, v38
	v_pk_mul_f32 v[58:59], v[100:101], v[58:59] op_sel_hi:[0,1]
	v_pk_mul_f32 v[60:61], v[100:101], v[60:61] op_sel_hi:[0,1]
	s_waitcnt vmcnt(12)
	v_pk_mul_f32 v[102:103], v[60:61], v[114:115]
	v_pk_mul_f32 v[104:105], v[58:59], v[116:117]
	global_load_dwordx4 v[58:61], v[234:235], off offset:160
	v_mov_b32_e32 v18, v63
	global_load_dwordx4 v[62:65], v[234:235], off offset:176
	v_mov_b32_e32 v38, v37
	v_pk_mul_f32 v[36:37], v[100:101], v[38:39] op_sel_hi:[0,1]
	v_mov_b32_e32 v38, v17
	v_mov_b32_e32 v39, v13
	v_pk_mul_f32 v[38:39], v[100:101], v[38:39] op_sel_hi:[0,1]
	v_mov_b32_e32 v17, v12
	v_pk_mul_f32 v[12:13], v[100:101], v[16:17] op_sel_hi:[0,1]
	v_pk_mul_f32 v[18:19], v[100:101], v[18:19] op_sel_hi:[0,1]
	v_pk_mul_f32 v[36:37], v[36:37], v[110:111]
	s_waitcnt vmcnt(12)
	v_pk_mul_f32 v[16:17], v[38:39], v[124:125]
	v_mov_b32_e32 v38, v75
	v_mov_b32_e32 v75, v14
	v_mov_b32_e32 v39, v15
	v_pk_mul_f32 v[14:15], v[100:101], v[74:75] op_sel_hi:[0,1]
	v_pk_mul_f32 v[74:75], v[100:101], v[76:77] op_sel_hi:[0,1]
	v_pk_mul_f32 v[76:77], v[100:101], v[86:87] op_sel_hi:[0,1]
	v_pk_mul_f32 v[86:87], v[100:101], v[92:93] op_sel_hi:[0,1]
	v_pk_mul_f32 v[92:93], v[100:101], v[94:95] op_sel_hi:[0,1]
	s_waitcnt vmcnt(10)
	v_pk_mul_f32 v[74:75], v[74:75], v[130:131]
	v_pk_mul_f32 v[8:9], v[8:9], v[132:133]
	v_pk_mul_f32 v[76:77], v[76:77], v[126:127]
	v_pk_mul_f32 v[10:11], v[10:11], v[128:129]
	v_pk_mul_f32 v[18:19], v[18:19], v[112:113]
	v_pk_mul_f32 v[38:39], v[100:101], v[38:39] op_sel_hi:[0,1]
	v_pk_mul_f32 v[12:13], v[12:13], v[122:123]
	v_pk_mul_f32 v[14:15], v[14:15], v[118:119]
	v_pk_mul_f32 v[38:39], v[38:39], v[120:121]
	v_cvt_pk_bf16_f32 v120, v142, v143
	v_cvt_pk_bf16_f32 v109, v44, v45
	v_cvt_pk_bf16_f32 v110, v50, v51
	v_cvt_pk_bf16_f32 v111, v40, v41
	v_cvt_pk_bf16_f32 v112, v52, v53
	s_waitcnt vmcnt(9)
	v_pk_mul_f32 v[4:5], v[4:5], v[78:79]
	s_waitcnt vmcnt(8)
	v_pk_mul_f32 v[86:87], v[86:87], v[88:89]
	v_pk_mul_f32 v[6:7], v[6:7], v[80:81]
	v_pk_mul_f32 v[90:91], v[92:93], v[90:91]
	s_waitcnt vmcnt(7)
	v_mov_b32_e32 v78, v135
	v_mov_b32_e32 v79, v137
	v_mov_b32_e32 v135, v136
	v_pk_mul_f32 v[80:81], v[74:75], v[78:79]
	s_waitcnt vmcnt(6)
	v_mov_b32_e32 v88, v139
	v_mov_b32_e32 v89, v141
	v_mov_b32_e32 v139, v140
	v_pk_mul_f32 v[74:75], v[74:75], v[134:135]
	v_pk_mul_f32 v[92:93], v[8:9], v[88:89]
	v_pk_mul_f32 v[8:9], v[8:9], v[138:139]
	v_pk_fma_f32 v[74:75], v[102:103], v[78:79], v[74:75]
	v_pk_fma_f32 v[8:9], v[104:105], v[88:89], v[8:9]
	v_pk_fma_f32 v[80:81], v[102:103], v[134:135], v[80:81] neg_lo:[0,0,1] neg_hi:[0,0,1]
	v_pk_fma_f32 v[92:93], v[104:105], v[138:139], v[92:93] neg_lo:[0,0,1] neg_hi:[0,0,1]
	v_cvt_pk_bf16_f32 v102, v68, v69
	s_waitcnt vmcnt(5)
	v_mov_b32_e32 v78, v27
	v_mov_b32_e32 v79, v29
	v_pk_mul_f32 v[88:89], v[76:77], v[78:79]
	s_waitcnt vmcnt(4)
	v_mov_b32_e32 v94, v31
	v_mov_b32_e32 v95, v33
	v_mov_b32_e32 v31, v32
	v_mov_b32_e32 v27, v28
	v_pk_mul_f32 v[100:101], v[10:11], v[94:95]
	v_pk_fma_f32 v[28:29], v[36:37], v[26:27], v[88:89] neg_lo:[0,0,1] neg_hi:[0,0,1]
	v_pk_mul_f32 v[26:27], v[76:77], v[26:27]
	v_pk_mul_f32 v[10:11], v[10:11], v[30:31]
	v_pk_fma_f32 v[32:33], v[18:19], v[30:31], v[100:101] neg_lo:[0,0,1] neg_hi:[0,0,1]
	v_pk_fma_f32 v[10:11], v[18:19], v[94:95], v[10:11]
	v_pk_fma_f32 v[18:19], v[36:37], v[78:79], v[26:27]
	s_waitcnt vmcnt(2)
	v_mov_b32_e32 v36, v21
	v_mov_b32_e32 v37, v23
	v_mov_b32_e32 v26, v47
	v_mov_b32_e32 v27, v49
	v_pk_mul_f32 v[76:77], v[90:91], v[36:37]
	v_mov_b32_e32 v21, v22
	v_pk_mul_f32 v[30:31], v[86:87], v[26:27]
	v_pk_fma_f32 v[22:23], v[16:17], v[20:21], v[76:77] neg_lo:[0,0,1] neg_hi:[0,0,1]
	v_mov_b32_e32 v47, v48
	v_pk_mul_f32 v[20:21], v[90:91], v[20:21]
	v_pk_fma_f32 v[30:31], v[12:13], v[46:47], v[30:31] neg_lo:[0,0,1] neg_hi:[0,0,1]
	v_pk_mul_f32 v[46:47], v[86:87], v[46:47]
	v_pk_fma_f32 v[16:17], v[16:17], v[36:37], v[20:21]
	s_waitcnt vmcnt(1)
	v_mov_b32_e32 v20, v59
	v_mov_b32_e32 v21, v61
	s_waitcnt vmcnt(0)
	v_mov_b32_e32 v36, v63
	v_mov_b32_e32 v37, v65
	v_mov_b32_e32 v63, v64
	v_mov_b32_e32 v59, v60
	v_pk_fma_f32 v[12:13], v[12:13], v[26:27], v[46:47]
	v_pk_mul_f32 v[26:27], v[4:5], v[20:21]
	v_pk_mul_f32 v[46:47], v[6:7], v[36:37]
	v_pk_mul_f32 v[4:5], v[4:5], v[58:59]
	v_pk_mul_f32 v[6:7], v[6:7], v[62:63]
	v_pk_fma_f32 v[46:47], v[38:39], v[62:63], v[46:47] neg_lo:[0,0,1] neg_hi:[0,0,1]
	v_pk_fma_f32 v[26:27], v[14:15], v[58:59], v[26:27] neg_lo:[0,0,1] neg_hi:[0,0,1]
	v_pk_fma_f32 v[6:7], v[38:39], v[36:37], v[6:7]
	v_pk_fma_f32 v[4:5], v[14:15], v[20:21], v[4:5]
	v_cvt_pk_bf16_f32 v143, v16, v17
	v_mov_b32_e32 v16, v2
	v_mov_b32_e32 v17, v2
	v_cvt_pk_bf16_f32 v103, v66, v67
	v_cvt_pk_bf16_f32 v104, v72, v73
	v_cvt_pk_bf16_f32 v105, v70, v71
	v_cvt_pk_bf16_f32 v113, v24, v25
	v_cvt_pk_bf16_f32 v114, v56, v57
	v_cvt_pk_bf16_f32 v115, v54, v55
	v_cvt_pk_bf16_f32 v121, v144, v145
	v_cvt_pk_bf16_f32 v122, v42, v43
	v_cvt_pk_bf16_f32 v130, v80, v81
	v_cvt_pk_bf16_f32 v132, v28, v29
	v_cvt_pk_bf16_f32 v133, v32, v33
	v_cvt_pk_bf16_f32 v134, v30, v31
	v_cvt_pk_bf16_f32 v135, v22, v23
	v_cvt_pk_bf16_f32 v136, v26, v27
	v_cvt_pk_bf16_f32 v137, v46, v47
	v_cvt_pk_bf16_f32 v138, v74, v75
	v_cvt_pk_bf16_f32 v139, v8, v9
	v_cvt_pk_bf16_f32 v140, v18, v19
	v_cvt_pk_bf16_f32 v141, v10, v11
	v_cvt_pk_bf16_f32 v142, v12, v13
	v_cvt_pk_bf16_f32 v144, v4, v5
	v_cvt_pk_bf16_f32 v145, v6, v7
	v_mov_b32_e32 v3, v2
	v_mov_b32_e32 v4, v2
	v_mov_b32_e32 v5, v2
	v_mov_b32_e32 v6, v2
	v_mov_b32_e32 v7, v2
	v_mov_b32_e32 v8, v2
	v_mov_b32_e32 v9, v2
	v_mov_b32_e32 v10, v2
	v_mov_b32_e32 v11, v2
	v_mov_b32_e32 v12, v2
	v_mov_b32_e32 v13, v2
	v_mov_b32_e32 v14, v2
	v_mov_b32_e32 v15, v2
	v_mov_b64_e32 v[32:33], v[16:17]
	v_mov_b64_e32 v[48:49], v[16:17]
	v_mov_b64_e32 v[64:65], v[16:17]
	v_mov_b64_e32 v[80:81], v[16:17]
	v_cvt_pk_bf16_f32 v98, v98, v99
	v_cvt_pk_bf16_f32 v99, v96, v97
	v_cvt_pk_bf16_f32 v100, v84, v85
	v_cvt_pk_bf16_f32 v101, v82, v83
	v_cvt_pk_bf16_f32 v116, v232, v233
	v_cvt_pk_bf16_f32 v117, v230, v231
	v_cvt_pk_bf16_f32 v118, v214, v215
	v_cvt_pk_bf16_f32 v119, v216, v217
	v_cvt_pk_bf16_f32 v123, v224, v225
	v_cvt_pk_bf16_f32 v124, v218, v219
	v_cvt_pk_bf16_f32 v125, v220, v221
	v_cvt_pk_bf16_f32 v126, v226, v227
	v_cvt_pk_bf16_f32 v127, v222, v223
	v_cvt_pk_bf16_f32 v128, v236, v237
	v_cvt_pk_bf16_f32 v129, v228, v229
	v_cvt_pk_bf16_f32 v131, v92, v93
	v_mov_b32_e32 v214, 0
	v_mov_b32_e32 v215, 0xf149f2ca
	v_mov_b64_e32 v[30:31], v[14:15]
	v_mov_b64_e32 v[28:29], v[12:13]
	v_mov_b64_e32 v[26:27], v[10:11]
	v_mov_b64_e32 v[24:25], v[8:9]
	v_mov_b64_e32 v[22:23], v[6:7]
	v_mov_b64_e32 v[20:21], v[4:5]
	v_mov_b64_e32 v[18:19], v[2:3]
	v_mov_b64_e32 v[46:47], v[14:15]
	v_mov_b64_e32 v[44:45], v[12:13]
	v_mov_b64_e32 v[42:43], v[10:11]
	v_mov_b64_e32 v[40:41], v[8:9]
	v_mov_b64_e32 v[38:39], v[6:7]
	v_mov_b64_e32 v[36:37], v[4:5]
	v_mov_b64_e32 v[34:35], v[2:3]
	v_mov_b64_e32 v[62:63], v[14:15]
	v_mov_b64_e32 v[60:61], v[12:13]
	v_mov_b64_e32 v[58:59], v[10:11]
	v_mov_b64_e32 v[56:57], v[8:9]
	v_mov_b64_e32 v[54:55], v[6:7]
	v_mov_b64_e32 v[52:53], v[4:5]
	v_mov_b64_e32 v[50:51], v[2:3]
	v_mov_b64_e32 v[78:79], v[14:15]
	v_mov_b64_e32 v[76:77], v[12:13]
	v_mov_b64_e32 v[74:75], v[10:11]
	v_mov_b64_e32 v[72:73], v[8:9]
	v_mov_b64_e32 v[70:71], v[6:7]
	v_mov_b64_e32 v[68:69], v[4:5]
	v_mov_b64_e32 v[66:67], v[2:3]
	.p2align	6

.LBB0_1286:
	s_or_b32 s22, s78, s55
	v_mov_b32_e32 v49, 0
	s_andn2_b64 vcc, exec, s[80:81]
	v_mov_b32_e32 v48, 0
	v_mov_b32_e32 v47, 0
	v_mov_b32_e32 v46, 0
	v_mov_b32_e32 v45, 0
	v_mov_b32_e32 v44, 0
	v_mov_b32_e32 v43, 0
	v_mov_b32_e32 v42, 0
	v_mov_b32_e32 v41, 0
	v_mov_b32_e32 v40, 0
	v_mov_b32_e32 v39, 0
	v_mov_b32_e32 v38, 0
	v_mov_b32_e32 v37, 0
	v_mov_b32_e32 v36, 0
	v_mov_b32_e32 v35, 0
	v_mov_b32_e32 v34, 0
	v_mov_b32_e32 v33, 0
	v_mov_b32_e32 v32, 0
	v_mov_b32_e32 v31, 0
	v_mov_b32_e32 v30, 0
	v_mov_b32_e32 v29, 0
	v_mov_b32_e32 v28, 0
	v_mov_b32_e32 v27, 0
	v_mov_b32_e32 v26, 0
	v_mov_b32_e32 v25, 0
	v_mov_b32_e32 v24, 0
	v_mov_b32_e32 v23, 0
	v_mov_b32_e32 v22, 0
	v_mov_b32_e32 v21, 0
	v_mov_b32_e32 v20, 0
	v_mov_b32_e32 v19, 0
	v_mov_b32_e32 v18, 0
	v_mov_b32_e32 v3, v149
	s_cbranch_vccnz .LBB0_1294
	s_lshl_b32 s36, s22, 9
	v_mov_b32_e32 v16, v2
	v_mov_b32_e32 v17, v2
	s_add_i32 s36, s36, 0
	v_mul_f32_e32 v159, 0x3fb8aa3b, v4
	v_mov_b32_e32 v3, v2
	v_mov_b32_e32 v4, v2
	v_mov_b32_e32 v5, v2
	v_mov_b32_e32 v6, v2
	v_mov_b32_e32 v7, v2
	v_mov_b32_e32 v8, v2
	v_mov_b32_e32 v9, v2
	v_mov_b32_e32 v10, v2
	v_mov_b32_e32 v11, v2
	v_mov_b32_e32 v12, v2
	v_mov_b32_e32 v13, v2
	v_mov_b32_e32 v14, v2
	v_mov_b32_e32 v15, v2
	v_mov_b64_e32 v[32:33], v[16:17]
	v_mov_b64_e32 v[48:49], v[16:17]
	s_add_i32 s36, s36, 0x18000
	v_mov_b64_e32 v[30:31], v[14:15]
	v_mov_b64_e32 v[28:29], v[12:13]
	v_mov_b64_e32 v[26:27], v[10:11]
	v_mov_b64_e32 v[24:25], v[8:9]
	v_mov_b64_e32 v[22:23], v[6:7]
	v_mov_b64_e32 v[20:21], v[4:5]
	v_mov_b64_e32 v[18:19], v[2:3]
	v_mov_b64_e32 v[46:47], v[14:15]
	v_mov_b64_e32 v[44:45], v[12:13]
	v_mov_b64_e32 v[42:43], v[10:11]
	v_mov_b64_e32 v[40:41], v[8:9]
	v_mov_b64_e32 v[38:39], v[6:7]
	v_mov_b64_e32 v[36:37], v[4:5]
	v_mov_b64_e32 v[34:35], v[2:3]
	v_mov_b32_e32 v3, v149
	s_mov_b32 s37, s66
	.p2align	6

.LBB0_1382:
	s_ashr_i32 s69, s68, 31
	s_lshl_b64 s[14:15], s[68:69], 21
	s_add_u32 s9, s48, s14
	s_addc_u32 s14, s49, s15
	s_ashr_i32 s63, s62, 31
	s_lshl_b64 s[36:37], s[62:63], 12
	s_add_u32 s70, s9, s36
	s_addc_u32 s71, s14, s37
	s_and_b64 s[14:15], s[6:7], exec
	s_cselect_b32 s9, s71, s77
	s_cselect_b32 s14, s70, s76
	s_ashr_i32 s61, s60, 31
	s_lshl_b64 s[50:51], s[60:61], 21
	v_readlane_b32 s54, v250, 15
	v_readlane_b32 s55, v250, 16
	s_add_u32 s15, s54, s50
	s_addc_u32 s33, s55, s51
	s_add_u32 s72, s15, s36
	s_addc_u32 s73, s33, s37
	s_and_b64 s[36:37], s[6:7], exec
	s_cselect_b32 s15, s73, s79
	s_cselect_b32 s33, s72, s78
	s_add_u32 s76, s76, 0x100080
	s_addc_u32 s77, s77, 0
	s_add_u32 s36, s78, 0x100
	s_addc_u32 s37, s79, 0
	s_mov_b32 s50, -2
	.p2align	6

.LBB0_1630:
	s_ashr_i32 s63, s62, 31
	s_lshl_b64 s[50:51], s[62:63], 21
	s_add_u32 s54, s46, s50
	s_addc_u32 s55, s47, s51
	s_ashr_i32 s59, s58, 31
	s_lshl_b64 s[50:51], s[58:59], 11
	s_add_u32 s70, s54, s50
	s_addc_u32 s71, s55, s51
	s_and_b64 s[54:55], s[68:69], exec
	s_cselect_b32 s54, s71, s81
	s_cselect_b32 s55, s70, s80
	s_ashr_i32 s61, s60, 31
	s_lshl_b64 s[56:57], s[60:61], 21
	v_readlane_b32 s64, v250, 13
	v_readlane_b32 s65, v250, 14
	s_add_u32 s56, s64, s56
	s_addc_u32 s57, s65, s57
	s_add_u32 s72, s56, s50
	s_addc_u32 s73, s57, s51
	s_and_b64 s[50:51], s[68:69], exec
	s_cselect_b32 s59, s73, s83
	s_cselect_b32 s61, s72, s82
	s_add_u32 s80, s80, 0x100080
	s_addc_u32 s81, s81, 0
	s_add_u32 s63, s82, 0x100
	s_addc_u32 s64, s83, 0
	s_mov_b32 s65, -2
	ds_read_b128 v[150:153], v146
	ds_read_b128 v[154:157], v146 offset:1024
	ds_read_b128 v[158:161], v146 offset:2048
	ds_read_b128 v[166:169], v146 offset:3072
	ds_read_b128 v[170:173], v147
	ds_read_b128 v[174:177], v147 offset:1024
	ds_read_b128 v[178:181], v147 offset:2048
	ds_read_b128 v[182:185], v147 offset:3072
	s_add_u32 s50, s80, 0xfff00080
	s_addc_u32 s51, s81, -1
	s_cmp_eq_u32 s65, 12
	s_cselect_b32 s85, s54, s51
	s_cselect_b32 s84, s55, s50
	s_cselect_b32 s83, s59, s64
	s_cselect_b32 s82, s61, s63
	v_lshl_add_u64 v[198:199], s[80:81], 0, v[138:139]
	s_add_i32 m0, s15, 0xc000
	ds_read_b128 v[186:189], v148
	ds_read_b128 v[190:193], v148 offset:1024
	ds_read_b128 v[194:197], v148 offset:2048
	ds_read_b128 v[210:213], v148 offset:3072
	ds_read_b128 v[214:217], v148 offset:4096
	ds_read_b128 v[218:221], v148 offset:5120
	ds_read_b128 v[222:225], v148 offset:6144
	ds_read_b128 v[226:229], v148 offset:7168
	global_load_lds_dwordx4 v[198:199], off
	v_lshl_add_u64 v[198:199], s[80:81], 0, v[140:141]
	s_add_i32 m0, s15, 0xe000
	s_nop 0
	global_load_lds_dwordx4 v[198:199], off
	s_waitcnt vmcnt(8)
	s_waitcnt lgkmcnt(0)
	s_barrier
	s_setprio 1
	s_waitcnt lgkmcnt(0)
	v_mfma_f32_16x16x32_bf16 v[126:129], v[150:153], v[186:189], 0
	v_mfma_f32_16x16x32_bf16 v[122:125], v[158:161], v[186:189], 0
	v_mfma_f32_16x16x32_bf16 v[110:113], v[150:153], v[194:197], 0
	v_mfma_f32_16x16x32_bf16 v[106:109], v[158:161], v[194:197], 0
	v_mfma_f32_16x16x32_bf16 v[94:97], v[150:153], v[214:217], 0
	v_mfma_f32_16x16x32_bf16 v[90:93], v[158:161], v[214:217], 0
	v_mfma_f32_16x16x32_bf16 v[78:81], v[150:153], v[222:225], 0
	v_mfma_f32_16x16x32_bf16 v[74:77], v[158:161], v[222:225], 0
	v_mfma_f32_16x16x32_bf16 v[126:129], v[154:157], v[190:193], v[126:129]
	v_mfma_f32_16x16x32_bf16 v[122:125], v[166:169], v[190:193], v[122:125]
	v_mfma_f32_16x16x32_bf16 v[110:113], v[154:157], v[210:213], v[110:113]
	v_mfma_f32_16x16x32_bf16 v[106:109], v[166:169], v[210:213], v[106:109]
	v_mfma_f32_16x16x32_bf16 v[94:97], v[154:157], v[218:221], v[94:97]
	v_mfma_f32_16x16x32_bf16 v[90:93], v[166:169], v[218:221], v[90:93]
	v_mfma_f32_16x16x32_bf16 v[78:81], v[154:157], v[226:229], v[78:81]
	v_mfma_f32_16x16x32_bf16 v[74:77], v[166:169], v[226:229], v[74:77]
	s_setprio 0
	s_setprio 1
	v_mfma_f32_16x16x32_bf16 v[118:121], v[170:173], v[186:189], 0
	v_mfma_f32_16x16x32_bf16 v[114:117], v[178:181], v[186:189], 0
	v_mfma_f32_16x16x32_bf16 v[102:105], v[170:173], v[194:197], 0
	v_mfma_f32_16x16x32_bf16 v[98:101], v[178:181], v[194:197], 0
	v_mfma_f32_16x16x32_bf16 v[86:89], v[170:173], v[214:217], 0
	v_mfma_f32_16x16x32_bf16 v[82:85], v[178:181], v[214:217], 0
	v_mfma_f32_16x16x32_bf16 v[70:73], v[170:173], v[222:225], 0
	v_mfma_f32_16x16x32_bf16 v[66:69], v[178:181], v[222:225], 0
	v_mfma_f32_16x16x32_bf16 v[118:121], v[174:177], v[190:193], v[118:121]
	v_mfma_f32_16x16x32_bf16 v[114:117], v[182:185], v[190:193], v[114:117]
	v_mfma_f32_16x16x32_bf16 v[102:105], v[174:177], v[210:213], v[102:105]
	v_mfma_f32_16x16x32_bf16 v[98:101], v[182:185], v[210:213], v[98:101]
	v_mfma_f32_16x16x32_bf16 v[86:89], v[174:177], v[218:221], v[86:89]
	v_mfma_f32_16x16x32_bf16 v[82:85], v[182:185], v[218:221], v[82:85]
	v_mfma_f32_16x16x32_bf16 v[70:73], v[174:177], v[226:229], v[70:73]
	v_mfma_f32_16x16x32_bf16 v[66:69], v[182:185], v[226:229], v[66:69]
	s_setprio 0
	s_barrier
	s_add_i32 s50, s9, s14
	v_lshl_add_u64 v[198:199], s[82:83], 0, v[134:135]
	s_mov_b32 m0, s50
	ds_read_b128 v[186:189], v148 offset:16384
	ds_read_b128 v[190:193], v148 offset:17408
	ds_read_b128 v[194:197], v148 offset:18432
	ds_read_b128 v[210:213], v148 offset:19456
	ds_read_b128 v[214:217], v148 offset:20480
	ds_read_b128 v[218:221], v148 offset:21504
	ds_read_b128 v[222:225], v148 offset:22528
	ds_read_b128 v[226:229], v148 offset:23552
	global_load_lds_dwordx4 v[198:199], off
	s_add_i32 m0, s50, 0x2000
	s_add_u32 s50, s82, 0x100000
	v_lshl_add_u64 v[230:231], s[82:83], 0, v[130:131]
	s_addc_u32 s51, s83, 0
	s_add_i32 s56, s33, s14
	global_load_lds_dwordx4 v[230:231], off
	v_lshl_add_u64 v[232:233], s[50:51], 0, v[134:135]
	s_mov_b32 m0, s56
	v_lshl_add_u64 v[234:235], s[84:85], 0, v[132:133]
	global_load_lds_dwordx4 v[232:233], off
	v_lshl_add_u64 v[232:233], s[50:51], 0, v[130:131]
	s_add_i32 m0, s56, 0x2000
	s_nop 0
	global_load_lds_dwordx4 v[232:233], off
	v_lshl_add_u64 v[232:233], s[84:85], 0, v[136:137]
	s_mov_b32 m0, s15
	s_nop 0
	global_load_lds_dwordx4 v[232:233], off
	s_mov_b32 m0, s20
	s_nop 0
	global_load_lds_dwordx4 v[234:235], off
	s_waitcnt vmcnt(8)
	s_waitcnt lgkmcnt(0)
	s_barrier
	s_setprio 1
	s_waitcnt lgkmcnt(0)
	v_mfma_f32_16x16x32_bf16 v[62:65], v[150:153], v[186:189], 0
	v_mfma_f32_16x16x32_bf16 v[58:61], v[158:161], v[186:189], 0
	v_mfma_f32_16x16x32_bf16 v[46:49], v[150:153], v[194:197], 0
	v_mfma_f32_16x16x32_bf16 v[42:45], v[158:161], v[194:197], 0
	v_mfma_f32_16x16x32_bf16 v[30:33], v[150:153], v[214:217], 0
	v_mfma_f32_16x16x32_bf16 v[26:29], v[158:161], v[214:217], 0
	v_mfma_f32_16x16x32_bf16 v[14:17], v[150:153], v[222:225], 0
	v_mfma_f32_16x16x32_bf16 v[10:13], v[158:161], v[222:225], 0
	v_mfma_f32_16x16x32_bf16 v[62:65], v[154:157], v[190:193], v[62:65]
	v_mfma_f32_16x16x32_bf16 v[58:61], v[166:169], v[190:193], v[58:61]
	v_mfma_f32_16x16x32_bf16 v[46:49], v[154:157], v[210:213], v[46:49]
	v_mfma_f32_16x16x32_bf16 v[42:45], v[166:169], v[210:213], v[42:45]
	v_mfma_f32_16x16x32_bf16 v[30:33], v[154:157], v[218:221], v[30:33]
	v_mfma_f32_16x16x32_bf16 v[26:29], v[166:169], v[218:221], v[26:29]
	v_mfma_f32_16x16x32_bf16 v[14:17], v[154:157], v[226:229], v[14:17]
	v_mfma_f32_16x16x32_bf16 v[10:13], v[166:169], v[226:229], v[10:13]
	s_setprio 0
	s_setprio 1
	v_mfma_f32_16x16x32_bf16 v[54:57], v[170:173], v[186:189], 0
	v_mfma_f32_16x16x32_bf16 v[50:53], v[178:181], v[186:189], 0
	v_mfma_f32_16x16x32_bf16 v[38:41], v[170:173], v[194:197], 0
	v_mfma_f32_16x16x32_bf16 v[34:37], v[178:181], v[194:197], 0
	v_mfma_f32_16x16x32_bf16 v[22:25], v[170:173], v[214:217], 0
	v_mfma_f32_16x16x32_bf16 v[18:21], v[178:181], v[214:217], 0
	v_mfma_f32_16x16x32_bf16 v[6:9], v[170:173], v[222:225], 0
	v_mfma_f32_16x16x32_bf16 v[2:5], v[178:181], v[222:225], 0
	v_mfma_f32_16x16x32_bf16 v[54:57], v[174:177], v[190:193], v[54:57]
	v_mfma_f32_16x16x32_bf16 v[50:53], v[182:185], v[190:193], v[50:53]
	v_mfma_f32_16x16x32_bf16 v[38:41], v[174:177], v[210:213], v[38:41]
	v_mfma_f32_16x16x32_bf16 v[34:37], v[182:185], v[210:213], v[34:37]
	v_mfma_f32_16x16x32_bf16 v[22:25], v[174:177], v[218:221], v[22:25]
	v_mfma_f32_16x16x32_bf16 v[18:21], v[182:185], v[218:221], v[18:21]
	v_mfma_f32_16x16x32_bf16 v[6:9], v[174:177], v[226:229], v[6:9]
	v_mfma_f32_16x16x32_bf16 v[2:5], v[182:185], v[226:229], v[2:5]
	s_setprio 0
	s_barrier
	s_add_i32 s56, 0, 0x18000
	s_add_i32 s57, 0, 0x1c000
	v_add_u32_e32 v166, s56, v145
	v_add_u32_e32 v182, s57, v145
	ds_read_b128 v[150:153], v166
	ds_read_b128 v[154:157], v166 offset:1024
	ds_read_b128 v[158:161], v166 offset:2048
	ds_read_b128 v[166:169], v166 offset:3072
	ds_read_b128 v[170:173], v182
	ds_read_b128 v[174:177], v182 offset:1024
	ds_read_b128 v[178:181], v182 offset:2048
	ds_read_b128 v[182:185], v182 offset:3072
	s_add_u32 s50, s84, 0x100000
	s_addc_u32 s51, s85, 0
	s_mov_b32 m0, s21
	v_lshl_add_u64 v[236:237], s[50:51], 0, v[136:137]
	ds_read_b128 v[186:189], v148 offset:32768
	ds_read_b128 v[190:193], v148 offset:33792
	ds_read_b128 v[194:197], v148 offset:34816
	ds_read_b128 v[210:213], v148 offset:35840
	ds_read_b128 v[214:217], v148 offset:36864
	ds_read_b128 v[218:221], v148 offset:37888
	ds_read_b128 v[222:225], v148 offset:38912
	ds_read_b128 v[226:229], v148 offset:39936
	global_load_lds_dwordx4 v[236:237], off
	v_lshl_add_u64 v[236:237], s[50:51], 0, v[132:133]
	s_mov_b32 m0, s26
	s_nop 0
	global_load_lds_dwordx4 v[236:237], off
	s_waitcnt vmcnt(8)
	s_waitcnt lgkmcnt(0)
	s_barrier
	s_setprio 1
	s_waitcnt lgkmcnt(0)
	v_mfma_f32_16x16x32_bf16 v[126:129], v[150:153], v[186:189], v[126:129]
	v_mfma_f32_16x16x32_bf16 v[122:125], v[158:161], v[186:189], v[122:125]
	v_mfma_f32_16x16x32_bf16 v[110:113], v[150:153], v[194:197], v[110:113]
	v_mfma_f32_16x16x32_bf16 v[106:109], v[158:161], v[194:197], v[106:109]
	v_mfma_f32_16x16x32_bf16 v[94:97], v[150:153], v[214:217], v[94:97]
	v_mfma_f32_16x16x32_bf16 v[90:93], v[158:161], v[214:217], v[90:93]
	v_mfma_f32_16x16x32_bf16 v[78:81], v[150:153], v[222:225], v[78:81]
	v_mfma_f32_16x16x32_bf16 v[74:77], v[158:161], v[222:225], v[74:77]
	v_mfma_f32_16x16x32_bf16 v[126:129], v[154:157], v[190:193], v[126:129]
	v_mfma_f32_16x16x32_bf16 v[122:125], v[166:169], v[190:193], v[122:125]
	v_mfma_f32_16x16x32_bf16 v[110:113], v[154:157], v[210:213], v[110:113]
	v_mfma_f32_16x16x32_bf16 v[106:109], v[166:169], v[210:213], v[106:109]
	v_mfma_f32_16x16x32_bf16 v[94:97], v[154:157], v[218:221], v[94:97]
	v_mfma_f32_16x16x32_bf16 v[90:93], v[166:169], v[218:221], v[90:93]
	v_mfma_f32_16x16x32_bf16 v[78:81], v[154:157], v[226:229], v[78:81]
	v_mfma_f32_16x16x32_bf16 v[74:77], v[166:169], v[226:229], v[74:77]
	s_setprio 0
	s_setprio 1
	v_mfma_f32_16x16x32_bf16 v[118:121], v[170:173], v[186:189], v[118:121]
	v_mfma_f32_16x16x32_bf16 v[114:117], v[178:181], v[186:189], v[114:117]
	v_mfma_f32_16x16x32_bf16 v[102:105], v[170:173], v[194:197], v[102:105]
	v_mfma_f32_16x16x32_bf16 v[98:101], v[178:181], v[194:197], v[98:101]
	v_mfma_f32_16x16x32_bf16 v[86:89], v[170:173], v[214:217], v[86:89]
	v_mfma_f32_16x16x32_bf16 v[82:85], v[178:181], v[214:217], v[82:85]
	v_mfma_f32_16x16x32_bf16 v[70:73], v[170:173], v[222:225], v[70:73]
	v_mfma_f32_16x16x32_bf16 v[66:69], v[178:181], v[222:225], v[66:69]
	v_mfma_f32_16x16x32_bf16 v[118:121], v[174:177], v[190:193], v[118:121]
	v_mfma_f32_16x16x32_bf16 v[114:117], v[182:185], v[190:193], v[114:117]
	v_mfma_f32_16x16x32_bf16 v[102:105], v[174:177], v[210:213], v[102:105]
	v_mfma_f32_16x16x32_bf16 v[98:101], v[182:185], v[210:213], v[98:101]
	v_mfma_f32_16x16x32_bf16 v[86:89], v[174:177], v[218:221], v[86:89]
	v_mfma_f32_16x16x32_bf16 v[82:85], v[182:185], v[218:221], v[82:85]
	v_mfma_f32_16x16x32_bf16 v[70:73], v[174:177], v[226:229], v[70:73]
	v_mfma_f32_16x16x32_bf16 v[66:69], v[182:185], v[226:229], v[66:69]
	s_setprio 0
	s_barrier
	s_add_i32 s50, s56, s14
	v_lshl_add_u64 v[198:199], v[198:199], 0, s[6:7]
	s_mov_b32 m0, s50
	ds_read_b128 v[186:189], v148 offset:49152
	ds_read_b128 v[190:193], v148 offset:50176
	ds_read_b128 v[194:197], v148 offset:51200
	ds_read_b128 v[210:213], v148 offset:52224
	ds_read_b128 v[214:217], v148 offset:53248
	ds_read_b128 v[218:221], v148 offset:54272
	ds_read_b128 v[222:225], v148 offset:55296
	ds_read_b128 v[226:229], v148 offset:56320
	global_load_lds_dwordx4 v[198:199], off
	s_add_i32 m0, s50, 0x2000
	s_add_u32 s50, s82, 0x100080
	v_lshl_add_u64 v[198:199], v[230:231], 0, s[6:7]
	s_addc_u32 s51, s83, 0
	s_add_i32 s56, s57, s14
	global_load_lds_dwordx4 v[198:199], off
	v_lshl_add_u64 v[198:199], s[50:51], 0, v[134:135]
	s_mov_b32 m0, s56
	s_nop 0
	global_load_lds_dwordx4 v[198:199], off
	v_lshl_add_u64 v[198:199], s[50:51], 0, v[130:131]
	s_add_i32 m0, s56, 0x2000
	s_nop 0
	global_load_lds_dwordx4 v[198:199], off
	v_lshl_add_u64 v[198:199], v[232:233], 0, s[6:7]
	s_mov_b32 m0, s37
	s_nop 0
	global_load_lds_dwordx4 v[198:199], off
	v_lshl_add_u64 v[198:199], v[234:235], 0, s[6:7]
	s_mov_b32 m0, s38
	s_nop 0
	global_load_lds_dwordx4 v[198:199], off
	s_waitcnt vmcnt(8)
	s_waitcnt lgkmcnt(0)
	s_barrier
	s_setprio 1
	s_waitcnt lgkmcnt(0)
	v_mfma_f32_16x16x32_bf16 v[62:65], v[150:153], v[186:189], v[62:65]
	v_mfma_f32_16x16x32_bf16 v[58:61], v[158:161], v[186:189], v[58:61]
	v_mfma_f32_16x16x32_bf16 v[46:49], v[150:153], v[194:197], v[46:49]
	v_mfma_f32_16x16x32_bf16 v[42:45], v[158:161], v[194:197], v[42:45]
	v_mfma_f32_16x16x32_bf16 v[30:33], v[150:153], v[214:217], v[30:33]
	v_mfma_f32_16x16x32_bf16 v[26:29], v[158:161], v[214:217], v[26:29]
	v_mfma_f32_16x16x32_bf16 v[14:17], v[150:153], v[222:225], v[14:17]
	v_mfma_f32_16x16x32_bf16 v[10:13], v[158:161], v[222:225], v[10:13]
	v_mfma_f32_16x16x32_bf16 v[62:65], v[154:157], v[190:193], v[62:65]
	v_mfma_f32_16x16x32_bf16 v[58:61], v[166:169], v[190:193], v[58:61]
	v_mfma_f32_16x16x32_bf16 v[46:49], v[154:157], v[210:213], v[46:49]
	v_mfma_f32_16x16x32_bf16 v[42:45], v[166:169], v[210:213], v[42:45]
	v_mfma_f32_16x16x32_bf16 v[30:33], v[154:157], v[218:221], v[30:33]
	v_mfma_f32_16x16x32_bf16 v[26:29], v[166:169], v[218:221], v[26:29]
	v_mfma_f32_16x16x32_bf16 v[14:17], v[154:157], v[226:229], v[14:17]
	v_mfma_f32_16x16x32_bf16 v[10:13], v[166:169], v[226:229], v[10:13]
	s_setprio 0
	s_setprio 1
	v_mfma_f32_16x16x32_bf16 v[54:57], v[170:173], v[186:189], v[54:57]
	v_mfma_f32_16x16x32_bf16 v[50:53], v[178:181], v[186:189], v[50:53]
	v_mfma_f32_16x16x32_bf16 v[38:41], v[170:173], v[194:197], v[38:41]
	v_mfma_f32_16x16x32_bf16 v[34:37], v[178:181], v[194:197], v[34:37]
	v_mfma_f32_16x16x32_bf16 v[22:25], v[170:173], v[214:217], v[22:25]
	v_mfma_f32_16x16x32_bf16 v[18:21], v[178:181], v[214:217], v[18:21]
	v_mfma_f32_16x16x32_bf16 v[6:9], v[170:173], v[222:225], v[6:9]
	v_mfma_f32_16x16x32_bf16 v[2:5], v[178:181], v[222:225], v[2:5]
	v_mfma_f32_16x16x32_bf16 v[54:57], v[174:177], v[190:193], v[54:57]
	v_mfma_f32_16x16x32_bf16 v[50:53], v[182:185], v[190:193], v[50:53]
	v_mfma_f32_16x16x32_bf16 v[38:41], v[174:177], v[210:213], v[38:41]
	v_mfma_f32_16x16x32_bf16 v[34:37], v[182:185], v[210:213], v[34:37]
	v_mfma_f32_16x16x32_bf16 v[22:25], v[174:177], v[218:221], v[22:25]
	v_mfma_f32_16x16x32_bf16 v[18:21], v[182:185], v[218:221], v[18:21]
	v_mfma_f32_16x16x32_bf16 v[6:9], v[174:177], v[226:229], v[6:9]
	v_mfma_f32_16x16x32_bf16 v[2:5], v[182:185], v[226:229], v[2:5]
	s_setprio 0
	s_barrier
	s_add_i32 s65, s65, 2
	s_add_u32 s80, s80, 0x100
	s_addc_u32 s81, s81, 0
	s_add_u32 s63, s63, 0x100
	s_addc_u32 s64, s64, 0
	.p2align	6

.LBB0_1933:
	s_ashr_i32 s59, s58, 31
	s_lshl_b64 s[14:15], s[58:59], 18
	s_add_u32 s60, s2, s14
	s_addc_u32 s61, s39, s15
	s_and_b64 s[14:15], s[6:7], exec
	s_cselect_b32 s14, s61, s67
	s_cselect_b32 s15, s60, s66
	s_ashr_i32 s57, s56, 31
	s_lshl_b64 s[36:37], s[56:57], 18
	s_add_u32 s62, s90, s36
	s_addc_u32 s63, s91, s37
	s_and_b64 s[36:37], s[6:7], exec
	s_cselect_b32 s33, s63, s69
	s_cselect_b32 s36, s62, s68
	s_add_u32 s66, s66, 0x20080
	s_addc_u32 s67, s67, 0
	s_add_u32 s37, s68, 0x100
	s_addc_u32 s57, s69, 0
	s_mov_b32 s59, -2
	s_waitcnt lgkmcnt(0)
	ds_read_b128 v[130:133], v183
	ds_read_b128 v[134:137], v183 offset:1024
	ds_read_b128 v[138:141], v183 offset:2048
	ds_read_b128 v[142:145], v183 offset:3072
	ds_read_b128 v[146:149], v184
	ds_read_b128 v[150:153], v184 offset:1024
	ds_read_b128 v[176:179], v184 offset:2048
	ds_read_b128 v[188:191], v184 offset:3072
	s_add_u32 s50, s66, 0xfffe0080
	s_addc_u32 s51, s67, -1
	s_cmp_eq_u32 s59, 4
	s_cselect_b32 s71, s14, s51
	s_cselect_b32 s70, s15, s50
	s_cselect_b32 s69, s33, s57
	s_cselect_b32 s68, s36, s37
	v_lshl_add_u64 v[228:229], s[66:67], 0, v[168:169]
	s_add_i32 m0, s21, 0xc000
	ds_read_b128 v[192:195], v185
	ds_read_b128 v[196:199], v185 offset:1024
	ds_read_b128 v[204:207], v185 offset:2048
	ds_read_b128 v[208:211], v185 offset:3072
	ds_read_b128 v[212:215], v185 offset:4096
	ds_read_b128 v[216:219], v185 offset:5120
	ds_read_b128 v[220:223], v185 offset:6144
	ds_read_b128 v[224:227], v185 offset:7168
	global_load_lds_dwordx4 v[228:229], off
	v_lshl_add_u64 v[228:229], s[66:67], 0, v[170:171]
	s_add_i32 m0, s21, 0xe000
	s_nop 0
	global_load_lds_dwordx4 v[228:229], off
	s_waitcnt vmcnt(8)
	s_waitcnt lgkmcnt(0)
	s_barrier
	s_setprio 1
	s_waitcnt lgkmcnt(0)
	v_mfma_f32_16x16x32_bf16 v[126:129], v[130:133], v[192:195], 0
	v_mfma_f32_16x16x32_bf16 v[122:125], v[138:141], v[192:195], 0
	v_mfma_f32_16x16x32_bf16 v[110:113], v[130:133], v[204:207], 0
	v_mfma_f32_16x16x32_bf16 v[106:109], v[138:141], v[204:207], 0
	v_mfma_f32_16x16x32_bf16 v[94:97], v[130:133], v[212:215], 0
	v_mfma_f32_16x16x32_bf16 v[90:93], v[138:141], v[212:215], 0
	v_mfma_f32_16x16x32_bf16 v[78:81], v[130:133], v[220:223], 0
	v_mfma_f32_16x16x32_bf16 v[74:77], v[138:141], v[220:223], 0
	v_mfma_f32_16x16x32_bf16 v[126:129], v[134:137], v[196:199], v[126:129]
	v_mfma_f32_16x16x32_bf16 v[122:125], v[142:145], v[196:199], v[122:125]
	v_mfma_f32_16x16x32_bf16 v[110:113], v[134:137], v[208:211], v[110:113]
	v_mfma_f32_16x16x32_bf16 v[106:109], v[142:145], v[208:211], v[106:109]
	v_mfma_f32_16x16x32_bf16 v[94:97], v[134:137], v[216:219], v[94:97]
	v_mfma_f32_16x16x32_bf16 v[90:93], v[142:145], v[216:219], v[90:93]
	v_mfma_f32_16x16x32_bf16 v[78:81], v[134:137], v[224:227], v[78:81]
	v_mfma_f32_16x16x32_bf16 v[74:77], v[142:145], v[224:227], v[74:77]
	s_setprio 0
	s_setprio 1
	v_mfma_f32_16x16x32_bf16 v[118:121], v[146:149], v[192:195], 0
	v_mfma_f32_16x16x32_bf16 v[114:117], v[176:179], v[192:195], 0
	v_mfma_f32_16x16x32_bf16 v[102:105], v[146:149], v[204:207], 0
	v_mfma_f32_16x16x32_bf16 v[98:101], v[176:179], v[204:207], 0
	v_mfma_f32_16x16x32_bf16 v[86:89], v[146:149], v[212:215], 0
	v_mfma_f32_16x16x32_bf16 v[82:85], v[176:179], v[212:215], 0
	v_mfma_f32_16x16x32_bf16 v[70:73], v[146:149], v[220:223], 0
	v_mfma_f32_16x16x32_bf16 v[66:69], v[176:179], v[220:223], 0
	v_mfma_f32_16x16x32_bf16 v[118:121], v[150:153], v[196:199], v[118:121]
	v_mfma_f32_16x16x32_bf16 v[114:117], v[188:191], v[196:199], v[114:117]
	v_mfma_f32_16x16x32_bf16 v[102:105], v[150:153], v[208:211], v[102:105]
	v_mfma_f32_16x16x32_bf16 v[98:101], v[188:191], v[208:211], v[98:101]
	v_mfma_f32_16x16x32_bf16 v[86:89], v[150:153], v[216:219], v[86:89]
	v_mfma_f32_16x16x32_bf16 v[82:85], v[188:191], v[216:219], v[82:85]
	v_mfma_f32_16x16x32_bf16 v[70:73], v[150:153], v[224:227], v[70:73]
	v_mfma_f32_16x16x32_bf16 v[66:69], v[188:191], v[224:227], v[66:69]
	s_setprio 0
	s_barrier
	s_add_i32 s50, s76, s20
	v_lshl_add_u64 v[228:229], s[68:69], 0, v[156:157]
	s_mov_b32 m0, s50
	ds_read_b128 v[192:195], v185 offset:16384
	ds_read_b128 v[196:199], v185 offset:17408
	ds_read_b128 v[204:207], v185 offset:18432
	ds_read_b128 v[208:211], v185 offset:19456
	ds_read_b128 v[212:215], v185 offset:20480
	ds_read_b128 v[216:219], v185 offset:21504
	ds_read_b128 v[220:223], v185 offset:22528
	ds_read_b128 v[224:227], v185 offset:23552
	global_load_lds_dwordx4 v[228:229], off
	s_add_i32 m0, s50, 0x2000
	s_add_u32 s50, s68, 0x20000
	v_lshl_add_u64 v[230:231], s[68:69], 0, v[160:161]
	s_addc_u32 s51, s69, 0
	s_add_i32 s79, s77, s20
	global_load_lds_dwordx4 v[230:231], off
	v_lshl_add_u64 v[232:233], s[50:51], 0, v[156:157]
	s_mov_b32 m0, s79
	v_lshl_add_u64 v[234:235], s[70:71], 0, v[158:159]
	global_load_lds_dwordx4 v[232:233], off
	v_lshl_add_u64 v[232:233], s[50:51], 0, v[160:161]
	s_add_i32 m0, s79, 0x2000
	s_nop 0
	global_load_lds_dwordx4 v[232:233], off
	v_lshl_add_u64 v[232:233], s[70:71], 0, v[154:155]
	s_mov_b32 m0, s21
	s_nop 0
	global_load_lds_dwordx4 v[232:233], off
	s_mov_b32 m0, s23
	s_nop 0
	global_load_lds_dwordx4 v[234:235], off
	s_waitcnt vmcnt(8)
	s_waitcnt lgkmcnt(0)
	s_barrier
	s_setprio 1
	s_waitcnt lgkmcnt(0)
	v_mfma_f32_16x16x32_bf16 v[62:65], v[130:133], v[192:195], 0
	v_mfma_f32_16x16x32_bf16 v[58:61], v[138:141], v[192:195], 0
	v_mfma_f32_16x16x32_bf16 v[46:49], v[130:133], v[204:207], 0
	v_mfma_f32_16x16x32_bf16 v[42:45], v[138:141], v[204:207], 0
	v_mfma_f32_16x16x32_bf16 v[30:33], v[130:133], v[212:215], 0
	v_mfma_f32_16x16x32_bf16 v[26:29], v[138:141], v[212:215], 0
	v_mfma_f32_16x16x32_bf16 v[14:17], v[130:133], v[220:223], 0
	v_mfma_f32_16x16x32_bf16 v[10:13], v[138:141], v[220:223], 0
	v_mfma_f32_16x16x32_bf16 v[62:65], v[134:137], v[196:199], v[62:65]
	v_mfma_f32_16x16x32_bf16 v[58:61], v[142:145], v[196:199], v[58:61]
	v_mfma_f32_16x16x32_bf16 v[46:49], v[134:137], v[208:211], v[46:49]
	v_mfma_f32_16x16x32_bf16 v[42:45], v[142:145], v[208:211], v[42:45]
	v_mfma_f32_16x16x32_bf16 v[30:33], v[134:137], v[216:219], v[30:33]
	v_mfma_f32_16x16x32_bf16 v[26:29], v[142:145], v[216:219], v[26:29]
	v_mfma_f32_16x16x32_bf16 v[14:17], v[134:137], v[224:227], v[14:17]
	v_mfma_f32_16x16x32_bf16 v[10:13], v[142:145], v[224:227], v[10:13]
	s_setprio 0
	s_setprio 1
	v_mfma_f32_16x16x32_bf16 v[54:57], v[146:149], v[192:195], 0
	v_mfma_f32_16x16x32_bf16 v[50:53], v[176:179], v[192:195], 0
	v_mfma_f32_16x16x32_bf16 v[38:41], v[146:149], v[204:207], 0
	v_mfma_f32_16x16x32_bf16 v[34:37], v[176:179], v[204:207], 0
	v_mfma_f32_16x16x32_bf16 v[22:25], v[146:149], v[212:215], 0
	v_mfma_f32_16x16x32_bf16 v[18:21], v[176:179], v[212:215], 0
	v_mfma_f32_16x16x32_bf16 v[6:9], v[146:149], v[220:223], 0
	v_mfma_f32_16x16x32_bf16 v[2:5], v[176:179], v[220:223], 0
	v_mfma_f32_16x16x32_bf16 v[54:57], v[150:153], v[196:199], v[54:57]
	v_mfma_f32_16x16x32_bf16 v[50:53], v[188:191], v[196:199], v[50:53]
	v_mfma_f32_16x16x32_bf16 v[38:41], v[150:153], v[208:211], v[38:41]
	v_mfma_f32_16x16x32_bf16 v[34:37], v[188:191], v[208:211], v[34:37]
	v_mfma_f32_16x16x32_bf16 v[22:25], v[150:153], v[216:219], v[22:25]
	v_mfma_f32_16x16x32_bf16 v[18:21], v[188:191], v[216:219], v[18:21]
	v_mfma_f32_16x16x32_bf16 v[6:9], v[150:153], v[224:227], v[6:9]
	v_mfma_f32_16x16x32_bf16 v[2:5], v[188:191], v[224:227], v[2:5]
	s_setprio 0
	s_barrier
	s_add_i32 s79, 0, 0x18000
	s_add_i32 s80, 0, 0x1c000
	v_add_u32_e32 v142, s79, v181
	v_add_u32_e32 v166, s80, v181
	ds_read_b128 v[130:133], v142
	ds_read_b128 v[134:137], v142 offset:1024
	ds_read_b128 v[138:141], v142 offset:2048
	ds_read_b128 v[142:145], v142 offset:3072
	ds_read_b128 v[146:149], v166
	ds_read_b128 v[150:153], v166 offset:1024
	ds_read_b128 v[176:179], v166 offset:2048
	ds_read_b128 v[188:191], v166 offset:3072
	s_add_u32 s50, s70, 0x20000
	s_addc_u32 s51, s71, 0
	s_mov_b32 m0, s26
	v_lshl_add_u64 v[236:237], s[50:51], 0, v[154:155]
	ds_read_b128 v[192:195], v185 offset:32768
	ds_read_b128 v[196:199], v185 offset:33792
	ds_read_b128 v[204:207], v185 offset:34816
	ds_read_b128 v[208:211], v185 offset:35840
	ds_read_b128 v[212:215], v185 offset:36864
	ds_read_b128 v[216:219], v185 offset:37888
	ds_read_b128 v[220:223], v185 offset:38912
	ds_read_b128 v[224:227], v185 offset:39936
	global_load_lds_dwordx4 v[236:237], off
	v_lshl_add_u64 v[236:237], s[50:51], 0, v[158:159]
	s_mov_b32 m0, s27
	s_nop 0
	global_load_lds_dwordx4 v[236:237], off
	s_waitcnt vmcnt(8)
	s_waitcnt lgkmcnt(0)
	s_barrier
	s_setprio 1
	s_waitcnt lgkmcnt(0)
	v_mfma_f32_16x16x32_bf16 v[126:129], v[130:133], v[192:195], v[126:129]
	v_mfma_f32_16x16x32_bf16 v[122:125], v[138:141], v[192:195], v[122:125]
	v_mfma_f32_16x16x32_bf16 v[110:113], v[130:133], v[204:207], v[110:113]
	v_mfma_f32_16x16x32_bf16 v[106:109], v[138:141], v[204:207], v[106:109]
	v_mfma_f32_16x16x32_bf16 v[94:97], v[130:133], v[212:215], v[94:97]
	v_mfma_f32_16x16x32_bf16 v[90:93], v[138:141], v[212:215], v[90:93]
	v_mfma_f32_16x16x32_bf16 v[78:81], v[130:133], v[220:223], v[78:81]
	v_mfma_f32_16x16x32_bf16 v[74:77], v[138:141], v[220:223], v[74:77]
	v_mfma_f32_16x16x32_bf16 v[126:129], v[134:137], v[196:199], v[126:129]
	v_mfma_f32_16x16x32_bf16 v[122:125], v[142:145], v[196:199], v[122:125]
	v_mfma_f32_16x16x32_bf16 v[110:113], v[134:137], v[208:211], v[110:113]
	v_mfma_f32_16x16x32_bf16 v[106:109], v[142:145], v[208:211], v[106:109]
	v_mfma_f32_16x16x32_bf16 v[94:97], v[134:137], v[216:219], v[94:97]
	v_mfma_f32_16x16x32_bf16 v[90:93], v[142:145], v[216:219], v[90:93]
	v_mfma_f32_16x16x32_bf16 v[78:81], v[134:137], v[224:227], v[78:81]
	v_mfma_f32_16x16x32_bf16 v[74:77], v[142:145], v[224:227], v[74:77]
	s_setprio 0
	s_setprio 1
	v_mfma_f32_16x16x32_bf16 v[118:121], v[146:149], v[192:195], v[118:121]
	v_mfma_f32_16x16x32_bf16 v[114:117], v[176:179], v[192:195], v[114:117]
	v_mfma_f32_16x16x32_bf16 v[102:105], v[146:149], v[204:207], v[102:105]
	v_mfma_f32_16x16x32_bf16 v[98:101], v[176:179], v[204:207], v[98:101]
	v_mfma_f32_16x16x32_bf16 v[86:89], v[146:149], v[212:215], v[86:89]
	v_mfma_f32_16x16x32_bf16 v[82:85], v[176:179], v[212:215], v[82:85]
	v_mfma_f32_16x16x32_bf16 v[70:73], v[146:149], v[220:223], v[70:73]
	v_mfma_f32_16x16x32_bf16 v[66:69], v[176:179], v[220:223], v[66:69]
	v_mfma_f32_16x16x32_bf16 v[118:121], v[150:153], v[196:199], v[118:121]
	v_mfma_f32_16x16x32_bf16 v[114:117], v[188:191], v[196:199], v[114:117]
	v_mfma_f32_16x16x32_bf16 v[102:105], v[150:153], v[208:211], v[102:105]
	v_mfma_f32_16x16x32_bf16 v[98:101], v[188:191], v[208:211], v[98:101]
	v_mfma_f32_16x16x32_bf16 v[86:89], v[150:153], v[216:219], v[86:89]
	v_mfma_f32_16x16x32_bf16 v[82:85], v[188:191], v[216:219], v[82:85]
	v_mfma_f32_16x16x32_bf16 v[70:73], v[150:153], v[224:227], v[70:73]
	v_mfma_f32_16x16x32_bf16 v[66:69], v[188:191], v[224:227], v[66:69]
	s_setprio 0
	s_barrier
	s_add_i32 s50, s79, s20
	v_lshl_add_u64 v[228:229], v[228:229], 0, s[52:53]
	s_mov_b32 m0, s50
	ds_read_b128 v[192:195], v185 offset:49152
	ds_read_b128 v[196:199], v185 offset:50176
	ds_read_b128 v[204:207], v185 offset:51200
	ds_read_b128 v[208:211], v185 offset:52224
	ds_read_b128 v[212:215], v185 offset:53248
	ds_read_b128 v[216:219], v185 offset:54272
	ds_read_b128 v[220:223], v185 offset:55296
	ds_read_b128 v[224:227], v185 offset:56320
	global_load_lds_dwordx4 v[228:229], off
	s_add_i32 m0, s50, 0x2000
	s_add_u32 s50, s68, 0x20080
	v_lshl_add_u64 v[228:229], v[230:231], 0, s[52:53]
	s_addc_u32 s51, s69, 0
	s_add_i32 s68, s80, s20
	global_load_lds_dwordx4 v[228:229], off
	v_lshl_add_u64 v[228:229], s[50:51], 0, v[156:157]
	s_mov_b32 m0, s68
	s_nop 0
	global_load_lds_dwordx4 v[228:229], off
	v_lshl_add_u64 v[228:229], s[50:51], 0, v[160:161]
	s_add_i32 m0, s68, 0x2000
	s_nop 0
	global_load_lds_dwordx4 v[228:229], off
	v_lshl_add_u64 v[228:229], v[232:233], 0, s[52:53]
	s_mov_b32 m0, s65
	s_nop 0
	global_load_lds_dwordx4 v[228:229], off
	v_lshl_add_u64 v[228:229], v[234:235], 0, s[52:53]
	s_mov_b32 m0, s72
	s_nop 0
	global_load_lds_dwordx4 v[228:229], off
	s_waitcnt vmcnt(8)
	s_waitcnt lgkmcnt(0)
	s_barrier
	s_setprio 1
	s_waitcnt lgkmcnt(0)
	v_mfma_f32_16x16x32_bf16 v[62:65], v[130:133], v[192:195], v[62:65]
	v_mfma_f32_16x16x32_bf16 v[58:61], v[138:141], v[192:195], v[58:61]
	v_mfma_f32_16x16x32_bf16 v[46:49], v[130:133], v[204:207], v[46:49]
	v_mfma_f32_16x16x32_bf16 v[42:45], v[138:141], v[204:207], v[42:45]
	v_mfma_f32_16x16x32_bf16 v[30:33], v[130:133], v[212:215], v[30:33]
	v_mfma_f32_16x16x32_bf16 v[26:29], v[138:141], v[212:215], v[26:29]
	v_mfma_f32_16x16x32_bf16 v[14:17], v[130:133], v[220:223], v[14:17]
	v_mfma_f32_16x16x32_bf16 v[10:13], v[138:141], v[220:223], v[10:13]
	v_mfma_f32_16x16x32_bf16 v[62:65], v[134:137], v[196:199], v[62:65]
	v_mfma_f32_16x16x32_bf16 v[58:61], v[142:145], v[196:199], v[58:61]
	v_mfma_f32_16x16x32_bf16 v[46:49], v[134:137], v[208:211], v[46:49]
	v_mfma_f32_16x16x32_bf16 v[42:45], v[142:145], v[208:211], v[42:45]
	v_mfma_f32_16x16x32_bf16 v[30:33], v[134:137], v[216:219], v[30:33]
	v_mfma_f32_16x16x32_bf16 v[26:29], v[142:145], v[216:219], v[26:29]
	v_mfma_f32_16x16x32_bf16 v[14:17], v[134:137], v[224:227], v[14:17]
	v_mfma_f32_16x16x32_bf16 v[10:13], v[142:145], v[224:227], v[10:13]
	s_setprio 0
	s_setprio 1
	v_mfma_f32_16x16x32_bf16 v[54:57], v[146:149], v[192:195], v[54:57]
	v_mfma_f32_16x16x32_bf16 v[50:53], v[176:179], v[192:195], v[50:53]
	v_mfma_f32_16x16x32_bf16 v[38:41], v[146:149], v[204:207], v[38:41]
	v_mfma_f32_16x16x32_bf16 v[34:37], v[176:179], v[204:207], v[34:37]
	v_mfma_f32_16x16x32_bf16 v[22:25], v[146:149], v[212:215], v[22:25]
	v_mfma_f32_16x16x32_bf16 v[18:21], v[176:179], v[212:215], v[18:21]
	v_mfma_f32_16x16x32_bf16 v[6:9], v[146:149], v[220:223], v[6:9]
	v_mfma_f32_16x16x32_bf16 v[2:5], v[176:179], v[220:223], v[2:5]
	v_mfma_f32_16x16x32_bf16 v[54:57], v[150:153], v[196:199], v[54:57]
	v_mfma_f32_16x16x32_bf16 v[50:53], v[188:191], v[196:199], v[50:53]
	v_mfma_f32_16x16x32_bf16 v[38:41], v[150:153], v[208:211], v[38:41]
	v_mfma_f32_16x16x32_bf16 v[34:37], v[188:191], v[208:211], v[34:37]
	v_mfma_f32_16x16x32_bf16 v[22:25], v[150:153], v[216:219], v[22:25]
	v_mfma_f32_16x16x32_bf16 v[18:21], v[188:191], v[216:219], v[18:21]
	v_mfma_f32_16x16x32_bf16 v[6:9], v[150:153], v[224:227], v[6:9]
	v_mfma_f32_16x16x32_bf16 v[2:5], v[188:191], v[224:227], v[2:5]
	s_setprio 0
	s_barrier
	s_add_i32 s59, s59, 2
	s_add_u32 s66, s66, 0x100
	s_addc_u32 s67, s67, 0
	s_add_u32 s37, s37, 0x100
	s_addc_u32 s57, s57, 0
	.p2align	6

.LBB0_2170:
	s_ashr_i32 s49, s48, 31
	s_lshl_b64 s[50:51], s[48:49], 20
	s_add_u32 s50, s21, s50
	s_addc_u32 s51, s26, s51
	s_and_b64 s[52:53], s[4:5], exec
	s_cselect_b32 s49, s51, s57
	s_cselect_b32 s68, s50, s56
	s_ashr_i32 s31, s30, 31
	s_lshl_b64 s[52:53], s[30:31], 20
	s_add_u32 s52, s42, s52
	s_addc_u32 s53, s43, s53
	s_and_b64 s[60:61], s[4:5], exec
	s_cselect_b32 s31, s53, s59
	s_cselect_b32 s69, s52, s58
	s_add_u32 s56, s56, 0x80080
	s_addc_u32 s57, s57, 0
	s_add_u32 s70, s58, 0x100
	s_addc_u32 s71, s59, 0
	s_mov_b32 s72, -2
	ds_read_b128 v[18:21], v193
	ds_read_b128 v[22:25], v193 offset:1024
	ds_read_b128 v[26:29], v193 offset:2048
	ds_read_b128 v[30:33], v193 offset:3072
	ds_read_b128 v[2:5], v194
	ds_read_b128 v[6:9], v194 offset:1024
	ds_read_b128 v[10:13], v194 offset:2048
	ds_read_b128 v[14:17], v194 offset:3072
	s_add_u32 s58, s56, 0xfff80080
	s_addc_u32 s59, s57, -1
	s_cmp_eq_u32 s72, 28
	s_cselect_b32 s61, s49, s59
	s_cselect_b32 s60, s68, s58
	s_cselect_b32 s59, s31, s71
	s_cselect_b32 s58, s69, s70
	v_lshl_add_u64 v[198:199], s[56:57], 0, v[174:175]
	s_add_i32 m0, s37, 0xc000
	ds_read_b128 v[182:185], v195
	ds_read_b128 v[186:189], v195 offset:1024
	ds_read_b128 v[204:207], v195 offset:2048
	ds_read_b128 v[208:211], v195 offset:3072
	ds_read_b128 v[212:215], v195 offset:4096
	ds_read_b128 v[216:219], v195 offset:5120
	ds_read_b128 v[220:223], v195 offset:6144
	ds_read_b128 v[224:227], v195 offset:7168
	global_load_lds_dwordx4 v[198:199], off
	v_lshl_add_u64 v[198:199], s[56:57], 0, v[176:177]
	s_add_i32 m0, s37, 0xe000
	s_nop 0
	global_load_lds_dwordx4 v[198:199], off
	s_waitcnt vmcnt(8)
	s_waitcnt lgkmcnt(0)
	s_barrier
	s_setprio 1
	s_waitcnt lgkmcnt(0)
	v_mfma_scale_f32_16x16x128_f8f6f4 v[158:161], v[18:25], v[182:189], 0, v196, v196 op_sel_hi:[0,0,0]
	v_mfma_scale_f32_16x16x128_f8f6f4 v[154:157], v[26:33], v[182:189], 0, v196, v196 op_sel_hi:[0,0,0]
	v_mfma_scale_f32_16x16x128_f8f6f4 v[142:145], v[18:25], v[204:211], 0, v196, v196 op_sel_hi:[0,0,0]
	v_mfma_scale_f32_16x16x128_f8f6f4 v[138:141], v[26:33], v[204:211], 0, v196, v196 op_sel_hi:[0,0,0]
	v_mfma_scale_f32_16x16x128_f8f6f4 v[126:129], v[18:25], v[212:219], 0, v196, v196 op_sel_hi:[0,0,0]
	v_mfma_scale_f32_16x16x128_f8f6f4 v[122:125], v[26:33], v[212:219], 0, v196, v196 op_sel_hi:[0,0,0]
	v_mfma_scale_f32_16x16x128_f8f6f4 v[110:113], v[18:25], v[220:227], 0, v196, v196 op_sel_hi:[0,0,0]
	v_mfma_scale_f32_16x16x128_f8f6f4 v[106:109], v[26:33], v[220:227], 0, v196, v196 op_sel_hi:[0,0,0]
	s_setprio 0
	s_setprio 1
	v_mfma_scale_f32_16x16x128_f8f6f4 v[150:153], v[2:9], v[182:189], 0, v196, v196 op_sel_hi:[0,0,0]
	v_mfma_scale_f32_16x16x128_f8f6f4 v[146:149], v[10:17], v[182:189], 0, v196, v196 op_sel_hi:[0,0,0]
	v_mfma_scale_f32_16x16x128_f8f6f4 v[134:137], v[2:9], v[204:211], 0, v196, v196 op_sel_hi:[0,0,0]
	v_mfma_scale_f32_16x16x128_f8f6f4 v[130:133], v[10:17], v[204:211], 0, v196, v196 op_sel_hi:[0,0,0]
	v_mfma_scale_f32_16x16x128_f8f6f4 v[118:121], v[2:9], v[212:219], 0, v196, v196 op_sel_hi:[0,0,0]
	v_mfma_scale_f32_16x16x128_f8f6f4 v[114:117], v[10:17], v[212:219], 0, v196, v196 op_sel_hi:[0,0,0]
	v_mfma_scale_f32_16x16x128_f8f6f4 v[102:105], v[2:9], v[220:227], 0, v196, v196 op_sel_hi:[0,0,0]
	v_mfma_scale_f32_16x16x128_f8f6f4 v[98:101], v[10:17], v[220:227], 0, v196, v196 op_sel_hi:[0,0,0]
	s_setprio 0
	s_barrier
	s_add_i32 s73, s15, s20
	v_lshl_add_u64 v[182:183], s[58:59], 0, v[170:171]
	s_mov_b32 m0, s73
	ds_read_b128 v[204:207], v195 offset:16384
	ds_read_b128 v[208:211], v195 offset:17408
	ds_read_b128 v[212:215], v195 offset:18432
	ds_read_b128 v[216:219], v195 offset:19456
	ds_read_b128 v[220:223], v195 offset:20480
	ds_read_b128 v[224:227], v195 offset:21504
	ds_read_b128 v[228:231], v195 offset:22528
	ds_read_b128 v[232:235], v195 offset:23552
	global_load_lds_dwordx4 v[182:183], off
	s_add_i32 m0, s73, 0x2000
	s_add_u32 s74, s58, 0x80000
	v_lshl_add_u64 v[184:185], s[58:59], 0, v[166:167]
	s_addc_u32 s75, s59, 0
	s_add_i32 s73, s65, s20
	global_load_lds_dwordx4 v[184:185], off
	v_lshl_add_u64 v[186:187], s[74:75], 0, v[170:171]
	s_mov_b32 m0, s73
	v_lshl_add_u64 v[188:189], s[60:61], 0, v[168:169]
	global_load_lds_dwordx4 v[186:187], off
	v_lshl_add_u64 v[186:187], s[74:75], 0, v[166:167]
	s_add_i32 m0, s73, 0x2000
	s_nop 0
	global_load_lds_dwordx4 v[186:187], off
	v_lshl_add_u64 v[186:187], s[60:61], 0, v[172:173]
	s_mov_b32 m0, s37
	s_nop 0
	global_load_lds_dwordx4 v[186:187], off
	s_mov_b32 m0, s38
	s_nop 0
	global_load_lds_dwordx4 v[188:189], off
	s_waitcnt vmcnt(8)
	s_waitcnt lgkmcnt(0)
	s_barrier
	s_setprio 1
	s_waitcnt lgkmcnt(0)
	v_mfma_scale_f32_16x16x128_f8f6f4 v[94:97], v[18:25], v[204:211], 0, v196, v196 op_sel_hi:[0,0,0]
	v_mfma_scale_f32_16x16x128_f8f6f4 v[90:93], v[26:33], v[204:211], 0, v196, v196 op_sel_hi:[0,0,0]
	v_mfma_scale_f32_16x16x128_f8f6f4 v[78:81], v[18:25], v[212:219], 0, v196, v196 op_sel_hi:[0,0,0]
	v_mfma_scale_f32_16x16x128_f8f6f4 v[74:77], v[26:33], v[212:219], 0, v196, v196 op_sel_hi:[0,0,0]
	v_mfma_scale_f32_16x16x128_f8f6f4 v[62:65], v[18:25], v[220:227], 0, v196, v196 op_sel_hi:[0,0,0]
	v_mfma_scale_f32_16x16x128_f8f6f4 v[58:61], v[26:33], v[220:227], 0, v196, v196 op_sel_hi:[0,0,0]
	v_mfma_scale_f32_16x16x128_f8f6f4 v[46:49], v[18:25], v[228:235], 0, v196, v196 op_sel_hi:[0,0,0]
	v_mfma_scale_f32_16x16x128_f8f6f4 v[42:45], v[26:33], v[228:235], 0, v196, v196 op_sel_hi:[0,0,0]
	s_setprio 0
	s_setprio 1
	v_mfma_scale_f32_16x16x128_f8f6f4 v[86:89], v[2:9], v[204:211], 0, v196, v196 op_sel_hi:[0,0,0]
	v_mfma_scale_f32_16x16x128_f8f6f4 v[82:85], v[10:17], v[204:211], 0, v196, v196 op_sel_hi:[0,0,0]
	v_mfma_scale_f32_16x16x128_f8f6f4 v[70:73], v[2:9], v[212:219], 0, v196, v196 op_sel_hi:[0,0,0]
	v_mfma_scale_f32_16x16x128_f8f6f4 v[66:69], v[10:17], v[212:219], 0, v196, v196 op_sel_hi:[0,0,0]
	v_mfma_scale_f32_16x16x128_f8f6f4 v[54:57], v[2:9], v[220:227], 0, v196, v196 op_sel_hi:[0,0,0]
	v_mfma_scale_f32_16x16x128_f8f6f4 v[50:53], v[10:17], v[220:227], 0, v196, v196 op_sel_hi:[0,0,0]
	v_mfma_scale_f32_16x16x128_f8f6f4 v[38:41], v[2:9], v[228:235], 0, v196, v196 op_sel_hi:[0,0,0]
	v_mfma_scale_f32_16x16x128_f8f6f4 v[34:37], v[10:17], v[228:235], 0, v196, v196 op_sel_hi:[0,0,0]
	s_setprio 0
	s_barrier
	s_add_i32 s73, 0, 0x18000
	s_add_i32 s74, 0, 0x1c000
	v_add_u32_e32 v14, s73, v191
	v_add_u32_e32 v30, s74, v191
	ds_read_b128 v[2:5], v14
	ds_read_b128 v[6:9], v14 offset:1024
	ds_read_b128 v[10:13], v14 offset:2048
	ds_read_b128 v[14:17], v14 offset:3072
	ds_read_b128 v[18:21], v30
	ds_read_b128 v[22:25], v30 offset:1024
	ds_read_b128 v[26:29], v30 offset:2048
	ds_read_b128 v[30:33], v30 offset:3072
	s_add_u32 s60, s60, 0x80000
	s_addc_u32 s61, s61, 0
	s_mov_b32 m0, s39
	v_lshl_add_u64 v[198:199], s[60:61], 0, v[172:173]
	ds_read_b128 v[204:207], v195 offset:32768
	ds_read_b128 v[208:211], v195 offset:33792
	ds_read_b128 v[212:215], v195 offset:34816
	ds_read_b128 v[216:219], v195 offset:35840
	ds_read_b128 v[220:223], v195 offset:36864
	ds_read_b128 v[224:227], v195 offset:37888
	ds_read_b128 v[228:231], v195 offset:38912
	ds_read_b128 v[232:235], v195 offset:39936
	global_load_lds_dwordx4 v[198:199], off
	v_lshl_add_u64 v[198:199], s[60:61], 0, v[168:169]
	s_mov_b32 m0, s55
	s_nop 0
	global_load_lds_dwordx4 v[198:199], off
	s_waitcnt vmcnt(8)
	s_waitcnt lgkmcnt(0)
	s_barrier
	s_setprio 1
	s_waitcnt lgkmcnt(0)
	v_mfma_scale_f32_16x16x128_f8f6f4 v[158:161], v[2:9], v[204:211], v[158:161], v196, v196 op_sel_hi:[0,0,0]
	v_mfma_scale_f32_16x16x128_f8f6f4 v[154:157], v[10:17], v[204:211], v[154:157], v196, v196 op_sel_hi:[0,0,0]
	v_mfma_scale_f32_16x16x128_f8f6f4 v[142:145], v[2:9], v[212:219], v[142:145], v196, v196 op_sel_hi:[0,0,0]
	v_mfma_scale_f32_16x16x128_f8f6f4 v[138:141], v[10:17], v[212:219], v[138:141], v196, v196 op_sel_hi:[0,0,0]
	v_mfma_scale_f32_16x16x128_f8f6f4 v[126:129], v[2:9], v[220:227], v[126:129], v196, v196 op_sel_hi:[0,0,0]
	v_mfma_scale_f32_16x16x128_f8f6f4 v[122:125], v[10:17], v[220:227], v[122:125], v196, v196 op_sel_hi:[0,0,0]
	v_mfma_scale_f32_16x16x128_f8f6f4 v[110:113], v[2:9], v[228:235], v[110:113], v196, v196 op_sel_hi:[0,0,0]
	v_mfma_scale_f32_16x16x128_f8f6f4 v[106:109], v[10:17], v[228:235], v[106:109], v196, v196 op_sel_hi:[0,0,0]
	s_setprio 0
	s_setprio 1
	v_mfma_scale_f32_16x16x128_f8f6f4 v[150:153], v[18:25], v[204:211], v[150:153], v196, v196 op_sel_hi:[0,0,0]
	v_mfma_scale_f32_16x16x128_f8f6f4 v[146:149], v[26:33], v[204:211], v[146:149], v196, v196 op_sel_hi:[0,0,0]
	v_mfma_scale_f32_16x16x128_f8f6f4 v[134:137], v[18:25], v[212:219], v[134:137], v196, v196 op_sel_hi:[0,0,0]
	v_mfma_scale_f32_16x16x128_f8f6f4 v[130:133], v[26:33], v[212:219], v[130:133], v196, v196 op_sel_hi:[0,0,0]
	v_mfma_scale_f32_16x16x128_f8f6f4 v[118:121], v[18:25], v[220:227], v[118:121], v196, v196 op_sel_hi:[0,0,0]
	v_mfma_scale_f32_16x16x128_f8f6f4 v[114:117], v[26:33], v[220:227], v[114:117], v196, v196 op_sel_hi:[0,0,0]
	v_mfma_scale_f32_16x16x128_f8f6f4 v[102:105], v[18:25], v[228:235], v[102:105], v196, v196 op_sel_hi:[0,0,0]
	v_mfma_scale_f32_16x16x128_f8f6f4 v[98:101], v[26:33], v[228:235], v[98:101], v196, v196 op_sel_hi:[0,0,0]
	s_setprio 0
	s_barrier
	s_add_i32 s60, s73, s20
	v_lshl_add_u64 v[182:183], v[182:183], 0, s[22:23]
	s_mov_b32 m0, s60
	ds_read_b128 v[204:207], v195 offset:49152
	ds_read_b128 v[208:211], v195 offset:50176
	ds_read_b128 v[212:215], v195 offset:51200
	ds_read_b128 v[216:219], v195 offset:52224
	ds_read_b128 v[220:223], v195 offset:53248
	ds_read_b128 v[224:227], v195 offset:54272
	ds_read_b128 v[228:231], v195 offset:55296
	ds_read_b128 v[232:235], v195 offset:56320
	global_load_lds_dwordx4 v[182:183], off
	s_add_i32 m0, s60, 0x2000
	s_add_u32 s58, s58, 0x80080
	v_lshl_add_u64 v[182:183], v[184:185], 0, s[22:23]
	s_addc_u32 s59, s59, 0
	s_add_i32 s60, s74, s20
	global_load_lds_dwordx4 v[182:183], off
	v_lshl_add_u64 v[182:183], s[58:59], 0, v[170:171]
	s_mov_b32 m0, s60
	s_nop 0
	global_load_lds_dwordx4 v[182:183], off
	v_lshl_add_u64 v[182:183], s[58:59], 0, v[166:167]
	s_add_i32 m0, s60, 0x2000
	s_nop 0
	global_load_lds_dwordx4 v[182:183], off
	v_lshl_add_u64 v[182:183], v[186:187], 0, s[22:23]
	s_mov_b32 m0, s63
	s_nop 0
	global_load_lds_dwordx4 v[182:183], off
	v_lshl_add_u64 v[182:183], v[188:189], 0, s[22:23]
	s_mov_b32 m0, s64
	s_nop 0
	global_load_lds_dwordx4 v[182:183], off
	s_waitcnt vmcnt(8)
	s_waitcnt lgkmcnt(0)
	s_barrier
	s_setprio 1
	s_waitcnt lgkmcnt(0)
	v_mfma_scale_f32_16x16x128_f8f6f4 v[94:97], v[2:9], v[204:211], v[94:97], v196, v196 op_sel_hi:[0,0,0]
	v_mfma_scale_f32_16x16x128_f8f6f4 v[90:93], v[10:17], v[204:211], v[90:93], v196, v196 op_sel_hi:[0,0,0]
	v_mfma_scale_f32_16x16x128_f8f6f4 v[78:81], v[2:9], v[212:219], v[78:81], v196, v196 op_sel_hi:[0,0,0]
	v_mfma_scale_f32_16x16x128_f8f6f4 v[74:77], v[10:17], v[212:219], v[74:77], v196, v196 op_sel_hi:[0,0,0]
	v_mfma_scale_f32_16x16x128_f8f6f4 v[62:65], v[2:9], v[220:227], v[62:65], v196, v196 op_sel_hi:[0,0,0]
	v_mfma_scale_f32_16x16x128_f8f6f4 v[58:61], v[10:17], v[220:227], v[58:61], v196, v196 op_sel_hi:[0,0,0]
	v_mfma_scale_f32_16x16x128_f8f6f4 v[46:49], v[2:9], v[228:235], v[46:49], v196, v196 op_sel_hi:[0,0,0]
	v_mfma_scale_f32_16x16x128_f8f6f4 v[42:45], v[10:17], v[228:235], v[42:45], v196, v196 op_sel_hi:[0,0,0]
	s_setprio 0
	s_setprio 1
	v_mfma_scale_f32_16x16x128_f8f6f4 v[86:89], v[18:25], v[204:211], v[86:89], v196, v196 op_sel_hi:[0,0,0]
	v_mfma_scale_f32_16x16x128_f8f6f4 v[82:85], v[26:33], v[204:211], v[82:85], v196, v196 op_sel_hi:[0,0,0]
	v_mfma_scale_f32_16x16x128_f8f6f4 v[70:73], v[18:25], v[212:219], v[70:73], v196, v196 op_sel_hi:[0,0,0]
	v_mfma_scale_f32_16x16x128_f8f6f4 v[66:69], v[26:33], v[212:219], v[66:69], v196, v196 op_sel_hi:[0,0,0]
	v_mfma_scale_f32_16x16x128_f8f6f4 v[54:57], v[18:25], v[220:227], v[54:57], v196, v196 op_sel_hi:[0,0,0]
	v_mfma_scale_f32_16x16x128_f8f6f4 v[50:53], v[26:33], v[220:227], v[50:53], v196, v196 op_sel_hi:[0,0,0]
	v_mfma_scale_f32_16x16x128_f8f6f4 v[38:41], v[18:25], v[228:235], v[38:41], v196, v196 op_sel_hi:[0,0,0]
	v_mfma_scale_f32_16x16x128_f8f6f4 v[34:37], v[26:33], v[228:235], v[34:37], v196, v196 op_sel_hi:[0,0,0]
	s_setprio 0
	s_barrier
	s_add_i32 s72, s72, 2
	s_add_u32 s56, s56, 0x100
	s_addc_u32 s57, s57, 0
	s_add_u32 s70, s70, 0x100
	s_addc_u32 s71, s71, 0
	.p2align	6

.LBB0_2399:
	s_add_u32 s20, s20, 0x158080
	s_addc_u32 s21, s21, 0
	s_add_u32 s41, s22, 0x100
	s_addc_u32 s42, s23, 0
	s_mov_b32 s43, -2
	ds_read_b128 v[16:19], v187
	ds_read_b128 v[20:23], v187 offset:1024
	ds_read_b128 v[24:27], v187 offset:2048
	ds_read_b128 v[28:31], v187 offset:3072
	ds_read_b128 v[0:3], v188
	ds_read_b128 v[4:7], v188 offset:1024
	ds_read_b128 v[8:11], v188 offset:2048
	ds_read_b128 v[12:15], v188 offset:3072
	s_add_u32 s22, s20, 0xffea8080
	s_addc_u32 s23, s21, -1
	s_cmpk_eq_i32 s43, 0x52
	s_cselect_b32 s25, s5, s23
	s_cselect_b32 s24, s4, s22
	s_cselect_b32 s23, s19, s42
	s_cselect_b32 s22, s18, s41
	v_lshl_add_u64 v[216:217], s[20:21], 0, v[162:163]
	s_add_i32 m0, s26, 0xc000
	ds_read_b128 v[176:179], v189
	ds_read_b128 v[180:183], v189 offset:1024
	ds_read_b128 v[192:195], v189 offset:2048
	ds_read_b128 v[196:199], v189 offset:3072
	ds_read_b128 v[200:203], v189 offset:4096
	ds_read_b128 v[204:207], v189 offset:5120
	ds_read_b128 v[208:211], v189 offset:6144
	ds_read_b128 v[212:215], v189 offset:7168
	global_load_lds_dwordx4 v[216:217], off
	v_lshl_add_u64 v[216:217], s[20:21], 0, v[170:171]
	s_add_i32 m0, s26, 0xe000
	s_nop 0
	global_load_lds_dwordx4 v[216:217], off
	s_waitcnt vmcnt(8)
	s_waitcnt lgkmcnt(0)
	s_barrier
	s_setprio 1
	s_waitcnt lgkmcnt(0)
	v_mfma_scale_f32_16x16x128_f8f6f4 v[156:159], v[16:23], v[176:183], 0, v190, v190 op_sel_hi:[0,0,0]
	v_mfma_scale_f32_16x16x128_f8f6f4 v[152:155], v[24:31], v[176:183], 0, v190, v190 op_sel_hi:[0,0,0]
	v_mfma_scale_f32_16x16x128_f8f6f4 v[148:151], v[16:23], v[192:199], 0, v190, v190 op_sel_hi:[0,0,0]
	v_mfma_scale_f32_16x16x128_f8f6f4 v[144:147], v[24:31], v[192:199], 0, v190, v190 op_sel_hi:[0,0,0]
	v_mfma_scale_f32_16x16x128_f8f6f4 v[132:135], v[16:23], v[200:207], 0, v190, v190 op_sel_hi:[0,0,0]
	v_mfma_scale_f32_16x16x128_f8f6f4 v[120:123], v[24:31], v[200:207], 0, v190, v190 op_sel_hi:[0,0,0]
	v_mfma_scale_f32_16x16x128_f8f6f4 v[112:115], v[16:23], v[208:215], 0, v190, v190 op_sel_hi:[0,0,0]
	v_mfma_scale_f32_16x16x128_f8f6f4 v[104:107], v[24:31], v[208:215], 0, v190, v190 op_sel_hi:[0,0,0]
	s_setprio 0
	s_setprio 1
	v_mfma_scale_f32_16x16x128_f8f6f4 v[140:143], v[0:7], v[176:183], 0, v190, v190 op_sel_hi:[0,0,0]
	v_mfma_scale_f32_16x16x128_f8f6f4 v[136:139], v[8:15], v[176:183], 0, v190, v190 op_sel_hi:[0,0,0]
	v_mfma_scale_f32_16x16x128_f8f6f4 v[128:131], v[0:7], v[192:199], 0, v190, v190 op_sel_hi:[0,0,0]
	v_mfma_scale_f32_16x16x128_f8f6f4 v[124:127], v[8:15], v[192:199], 0, v190, v190 op_sel_hi:[0,0,0]
	v_mfma_scale_f32_16x16x128_f8f6f4 v[116:119], v[0:7], v[200:207], 0, v190, v190 op_sel_hi:[0,0,0]
	v_mfma_scale_f32_16x16x128_f8f6f4 v[108:111], v[8:15], v[200:207], 0, v190, v190 op_sel_hi:[0,0,0]
	v_mfma_scale_f32_16x16x128_f8f6f4 v[100:103], v[0:7], v[208:215], 0, v190, v190 op_sel_hi:[0,0,0]
	v_mfma_scale_f32_16x16x128_f8f6f4 v[96:99], v[8:15], v[208:215], 0, v190, v190 op_sel_hi:[0,0,0]
	s_setprio 0
	s_barrier
	s_add_i32 s48, s35, s15
	v_lshl_add_u64 v[176:177], s[22:23], 0, v[164:165]
	s_mov_b32 m0, s48
	ds_read_b128 v[192:195], v189 offset:16384
	ds_read_b128 v[196:199], v189 offset:17408
	ds_read_b128 v[200:203], v189 offset:18432
	ds_read_b128 v[204:207], v189 offset:19456
	ds_read_b128 v[208:211], v189 offset:20480
	ds_read_b128 v[212:215], v189 offset:21504
	ds_read_b128 v[216:219], v189 offset:22528
	ds_read_b128 v[220:223], v189 offset:23552
	global_load_lds_dwordx4 v[176:177], off
	s_add_i32 m0, s48, 0x2000
	s_add_u32 s48, s22, 0x158000
	v_lshl_add_u64 v[178:179], s[22:23], 0, v[168:169]
	s_addc_u32 s49, s23, 0
	s_add_i32 s50, s36, s15
	global_load_lds_dwordx4 v[178:179], off
	v_lshl_add_u64 v[180:181], s[48:49], 0, v[164:165]
	s_mov_b32 m0, s50
	v_lshl_add_u64 v[182:183], s[24:25], 0, v[166:167]
	global_load_lds_dwordx4 v[180:181], off
	v_lshl_add_u64 v[180:181], s[48:49], 0, v[168:169]
	s_add_i32 m0, s50, 0x2000
	s_nop 0
	global_load_lds_dwordx4 v[180:181], off
	v_lshl_add_u64 v[180:181], s[24:25], 0, v[160:161]
	s_mov_b32 m0, s26
	s_nop 0
	global_load_lds_dwordx4 v[180:181], off
	s_mov_b32 m0, s27
	s_nop 0
	global_load_lds_dwordx4 v[182:183], off
	s_waitcnt vmcnt(8)
	s_waitcnt lgkmcnt(0)
	s_barrier
	s_setprio 1
	s_waitcnt lgkmcnt(0)
	v_mfma_scale_f32_16x16x128_f8f6f4 v[92:95], v[16:23], v[192:199], 0, v190, v190 op_sel_hi:[0,0,0]
	v_mfma_scale_f32_16x16x128_f8f6f4 v[88:91], v[24:31], v[192:199], 0, v190, v190 op_sel_hi:[0,0,0]
	v_mfma_scale_f32_16x16x128_f8f6f4 v[80:83], v[16:23], v[200:207], 0, v190, v190 op_sel_hi:[0,0,0]
	v_mfma_scale_f32_16x16x128_f8f6f4 v[72:75], v[24:31], v[200:207], 0, v190, v190 op_sel_hi:[0,0,0]
	v_mfma_scale_f32_16x16x128_f8f6f4 v[64:67], v[16:23], v[208:215], 0, v190, v190 op_sel_hi:[0,0,0]
	v_mfma_scale_f32_16x16x128_f8f6f4 v[56:59], v[24:31], v[208:215], 0, v190, v190 op_sel_hi:[0,0,0]
	v_mfma_scale_f32_16x16x128_f8f6f4 v[48:51], v[16:23], v[216:223], 0, v190, v190 op_sel_hi:[0,0,0]
	v_mfma_scale_f32_16x16x128_f8f6f4 v[40:43], v[24:31], v[216:223], 0, v190, v190 op_sel_hi:[0,0,0]
	s_setprio 0
	s_setprio 1
	v_mfma_scale_f32_16x16x128_f8f6f4 v[84:87], v[0:7], v[192:199], 0, v190, v190 op_sel_hi:[0,0,0]
	v_mfma_scale_f32_16x16x128_f8f6f4 v[76:79], v[8:15], v[192:199], 0, v190, v190 op_sel_hi:[0,0,0]
	v_mfma_scale_f32_16x16x128_f8f6f4 v[68:71], v[0:7], v[200:207], 0, v190, v190 op_sel_hi:[0,0,0]
	v_mfma_scale_f32_16x16x128_f8f6f4 v[60:63], v[8:15], v[200:207], 0, v190, v190 op_sel_hi:[0,0,0]
	v_mfma_scale_f32_16x16x128_f8f6f4 v[52:55], v[0:7], v[208:215], 0, v190, v190 op_sel_hi:[0,0,0]
	v_mfma_scale_f32_16x16x128_f8f6f4 v[44:47], v[8:15], v[208:215], 0, v190, v190 op_sel_hi:[0,0,0]
	v_mfma_scale_f32_16x16x128_f8f6f4 v[36:39], v[0:7], v[216:223], 0, v190, v190 op_sel_hi:[0,0,0]
	v_mfma_scale_f32_16x16x128_f8f6f4 v[32:35], v[8:15], v[216:223], 0, v190, v190 op_sel_hi:[0,0,0]
	s_setprio 0
	s_barrier
	s_add_i32 s48, 0, 0x18000
	s_add_i32 s49, 0, 0x1c000
	v_add_u32_e32 v12, s48, v184
	v_add_u32_e32 v28, s49, v184
	ds_read_b128 v[0:3], v12
	ds_read_b128 v[4:7], v12 offset:1024
	ds_read_b128 v[8:11], v12 offset:2048
	ds_read_b128 v[12:15], v12 offset:3072
	ds_read_b128 v[16:19], v28
	ds_read_b128 v[20:23], v28 offset:1024
	ds_read_b128 v[24:27], v28 offset:2048
	ds_read_b128 v[28:31], v28 offset:3072
	s_add_u32 s24, s24, 0x158000
	s_addc_u32 s25, s25, 0
	s_mov_b32 m0, s28
	v_lshl_add_u64 v[224:225], s[24:25], 0, v[160:161]
	ds_read_b128 v[192:195], v189 offset:32768
	ds_read_b128 v[196:199], v189 offset:33792
	ds_read_b128 v[200:203], v189 offset:34816
	ds_read_b128 v[204:207], v189 offset:35840
	ds_read_b128 v[208:211], v189 offset:36864
	ds_read_b128 v[212:215], v189 offset:37888
	ds_read_b128 v[216:219], v189 offset:38912
	ds_read_b128 v[220:223], v189 offset:39936
	global_load_lds_dwordx4 v[224:225], off
	v_lshl_add_u64 v[224:225], s[24:25], 0, v[166:167]
	s_mov_b32 m0, s29
	s_nop 0
	global_load_lds_dwordx4 v[224:225], off
	s_waitcnt vmcnt(8)
	s_waitcnt lgkmcnt(0)
	s_barrier
	s_setprio 1
	s_waitcnt lgkmcnt(0)
	v_mfma_scale_f32_16x16x128_f8f6f4 v[156:159], v[0:7], v[192:199], v[156:159], v190, v190 op_sel_hi:[0,0,0]
	v_mfma_scale_f32_16x16x128_f8f6f4 v[152:155], v[8:15], v[192:199], v[152:155], v190, v190 op_sel_hi:[0,0,0]
	v_mfma_scale_f32_16x16x128_f8f6f4 v[148:151], v[0:7], v[200:207], v[148:151], v190, v190 op_sel_hi:[0,0,0]
	v_mfma_scale_f32_16x16x128_f8f6f4 v[144:147], v[8:15], v[200:207], v[144:147], v190, v190 op_sel_hi:[0,0,0]
	v_mfma_scale_f32_16x16x128_f8f6f4 v[132:135], v[0:7], v[208:215], v[132:135], v190, v190 op_sel_hi:[0,0,0]
	v_mfma_scale_f32_16x16x128_f8f6f4 v[120:123], v[8:15], v[208:215], v[120:123], v190, v190 op_sel_hi:[0,0,0]
	v_mfma_scale_f32_16x16x128_f8f6f4 v[112:115], v[0:7], v[216:223], v[112:115], v190, v190 op_sel_hi:[0,0,0]
	v_mfma_scale_f32_16x16x128_f8f6f4 v[104:107], v[8:15], v[216:223], v[104:107], v190, v190 op_sel_hi:[0,0,0]
	s_setprio 0
	s_setprio 1
	v_mfma_scale_f32_16x16x128_f8f6f4 v[140:143], v[16:23], v[192:199], v[140:143], v190, v190 op_sel_hi:[0,0,0]
	v_mfma_scale_f32_16x16x128_f8f6f4 v[136:139], v[24:31], v[192:199], v[136:139], v190, v190 op_sel_hi:[0,0,0]
	v_mfma_scale_f32_16x16x128_f8f6f4 v[128:131], v[16:23], v[200:207], v[128:131], v190, v190 op_sel_hi:[0,0,0]
	v_mfma_scale_f32_16x16x128_f8f6f4 v[124:127], v[24:31], v[200:207], v[124:127], v190, v190 op_sel_hi:[0,0,0]
	v_mfma_scale_f32_16x16x128_f8f6f4 v[116:119], v[16:23], v[208:215], v[116:119], v190, v190 op_sel_hi:[0,0,0]
	v_mfma_scale_f32_16x16x128_f8f6f4 v[108:111], v[24:31], v[208:215], v[108:111], v190, v190 op_sel_hi:[0,0,0]
	v_mfma_scale_f32_16x16x128_f8f6f4 v[100:103], v[16:23], v[216:223], v[100:103], v190, v190 op_sel_hi:[0,0,0]
	v_mfma_scale_f32_16x16x128_f8f6f4 v[96:99], v[24:31], v[216:223], v[96:99], v190, v190 op_sel_hi:[0,0,0]
	s_setprio 0
	s_barrier
	s_add_i32 s24, s48, s15
	v_lshl_add_u64 v[176:177], v[176:177], 0, s[8:9]
	s_mov_b32 m0, s24
	ds_read_b128 v[192:195], v189 offset:49152
	ds_read_b128 v[196:199], v189 offset:50176
	ds_read_b128 v[200:203], v189 offset:51200
	ds_read_b128 v[204:207], v189 offset:52224
	ds_read_b128 v[208:211], v189 offset:53248
	ds_read_b128 v[212:215], v189 offset:54272
	ds_read_b128 v[216:219], v189 offset:55296
	ds_read_b128 v[220:223], v189 offset:56320
	global_load_lds_dwordx4 v[176:177], off
	s_add_i32 m0, s24, 0x2000
	s_add_u32 s22, s22, 0x158080
	v_lshl_add_u64 v[176:177], v[178:179], 0, s[8:9]
	s_addc_u32 s23, s23, 0
	s_add_i32 s24, s49, s15
	global_load_lds_dwordx4 v[176:177], off
	v_lshl_add_u64 v[176:177], s[22:23], 0, v[164:165]
	s_mov_b32 m0, s24
	s_nop 0
	global_load_lds_dwordx4 v[176:177], off
	v_lshl_add_u64 v[176:177], s[22:23], 0, v[168:169]
	s_add_i32 m0, s24, 0x2000
	s_nop 0
	global_load_lds_dwordx4 v[176:177], off
	v_lshl_add_u64 v[176:177], v[180:181], 0, s[8:9]
	s_mov_b32 m0, s31
	s_nop 0
	global_load_lds_dwordx4 v[176:177], off
	v_lshl_add_u64 v[176:177], v[182:183], 0, s[8:9]
	s_mov_b32 m0, s33
	s_nop 0
	global_load_lds_dwordx4 v[176:177], off
	s_waitcnt vmcnt(8)
	s_waitcnt lgkmcnt(0)
	s_barrier
	s_setprio 1
	s_waitcnt lgkmcnt(0)
	v_mfma_scale_f32_16x16x128_f8f6f4 v[92:95], v[0:7], v[192:199], v[92:95], v190, v190 op_sel_hi:[0,0,0]
	v_mfma_scale_f32_16x16x128_f8f6f4 v[88:91], v[8:15], v[192:199], v[88:91], v190, v190 op_sel_hi:[0,0,0]
	v_mfma_scale_f32_16x16x128_f8f6f4 v[80:83], v[0:7], v[200:207], v[80:83], v190, v190 op_sel_hi:[0,0,0]
	v_mfma_scale_f32_16x16x128_f8f6f4 v[72:75], v[8:15], v[200:207], v[72:75], v190, v190 op_sel_hi:[0,0,0]
	v_mfma_scale_f32_16x16x128_f8f6f4 v[64:67], v[0:7], v[208:215], v[64:67], v190, v190 op_sel_hi:[0,0,0]
	v_mfma_scale_f32_16x16x128_f8f6f4 v[56:59], v[8:15], v[208:215], v[56:59], v190, v190 op_sel_hi:[0,0,0]
	v_mfma_scale_f32_16x16x128_f8f6f4 v[48:51], v[0:7], v[216:223], v[48:51], v190, v190 op_sel_hi:[0,0,0]
	v_mfma_scale_f32_16x16x128_f8f6f4 v[40:43], v[8:15], v[216:223], v[40:43], v190, v190 op_sel_hi:[0,0,0]
	s_setprio 0
	s_setprio 1
	v_mfma_scale_f32_16x16x128_f8f6f4 v[84:87], v[16:23], v[192:199], v[84:87], v190, v190 op_sel_hi:[0,0,0]
	v_mfma_scale_f32_16x16x128_f8f6f4 v[76:79], v[24:31], v[192:199], v[76:79], v190, v190 op_sel_hi:[0,0,0]
	v_mfma_scale_f32_16x16x128_f8f6f4 v[68:71], v[16:23], v[200:207], v[68:71], v190, v190 op_sel_hi:[0,0,0]
	v_mfma_scale_f32_16x16x128_f8f6f4 v[60:63], v[24:31], v[200:207], v[60:63], v190, v190 op_sel_hi:[0,0,0]
	v_mfma_scale_f32_16x16x128_f8f6f4 v[52:55], v[16:23], v[208:215], v[52:55], v190, v190 op_sel_hi:[0,0,0]
	v_mfma_scale_f32_16x16x128_f8f6f4 v[44:47], v[24:31], v[208:215], v[44:47], v190, v190 op_sel_hi:[0,0,0]
	v_mfma_scale_f32_16x16x128_f8f6f4 v[36:39], v[16:23], v[216:223], v[36:39], v190, v190 op_sel_hi:[0,0,0]
	v_mfma_scale_f32_16x16x128_f8f6f4 v[32:35], v[24:31], v[216:223], v[32:35], v190, v190 op_sel_hi:[0,0,0]
	s_setprio 0
	s_barrier
	s_add_i32 s43, s43, 2
	s_add_u32 s20, s20, 0x100
	s_addc_u32 s21, s21, 0
	s_add_u32 s41, s41, 0x100
	s_addc_u32 s42, s42, 0
	.p2align	6
